# all s_setprio removed from the GEMM K loops (both wave halves run at the default priority)
# speedup vs baseline: 1.0051x; 1.0051x over previous
.LBB0_289:
	ds_read_b128 v[170:173], v167
	ds_read_b128 v[174:177], v167 offset:1024
	ds_read_b128 v[178:181], v167 offset:2048
	ds_read_b128 v[182:185], v167 offset:3072
	ds_read_b128 v[186:189], v168
	ds_read_b128 v[190:193], v168 offset:1024
	ds_read_b128 v[194:197], v168 offset:2048
	ds_read_b128 v[198:201], v168 offset:3072
	s_add_u32 s26, s24, 0xfffc0080
	s_addc_u32 s27, s25, -1
	s_cmp_eq_u32 s54, 12
	s_cselect_b32 s29, s13, s27
	s_cselect_b32 s28, s50, s26
	s_cselect_b32 s27, s15, s53
	s_cselect_b32 s26, s51, s52
	v_lshl_add_u64 v[164:165], s[24:25], 0, v[158:159]
	s_add_i32 m0, s21, 0xc000
	ds_read_b128 v[210:213], v169
	ds_read_b128 v[214:217], v169 offset:1024
	ds_read_b128 v[218:221], v169 offset:2048
	ds_read_b128 v[222:225], v169 offset:3072
	ds_read_b128 v[226:229], v169 offset:4096
	ds_read_b128 v[230:233], v169 offset:5120
	ds_read_b128 v[234:237], v169 offset:6144
	ds_read_b128 v[238:241], v169 offset:7168
	global_load_lds_dwordx4 v[164:165], off
	v_lshl_add_u64 v[164:165], s[24:25], 0, v[156:157]
	s_add_i32 m0, s21, 0xe000
	s_nop 0
	global_load_lds_dwordx4 v[164:165], off
	s_waitcnt vmcnt(8)
	s_waitcnt lgkmcnt(0)
	s_barrier
	s_waitcnt lgkmcnt(0)
	v_mfma_f32_16x16x32_bf16 v[124:127], v[170:173], v[210:213], v[124:127]
	v_mfma_f32_16x16x32_bf16 v[116:119], v[178:181], v[210:213], v[116:119]
	v_mfma_f32_16x16x32_bf16 v[108:111], v[170:173], v[218:221], v[108:111]
	v_mfma_f32_16x16x32_bf16 v[100:103], v[178:181], v[218:221], v[100:103]
	v_mfma_f32_16x16x32_bf16 v[92:95], v[170:173], v[226:229], v[92:95]
	v_mfma_f32_16x16x32_bf16 v[84:87], v[178:181], v[226:229], v[84:87]
	v_mfma_f32_16x16x32_bf16 v[76:79], v[170:173], v[234:237], v[76:79]
	v_mfma_f32_16x16x32_bf16 v[68:71], v[178:181], v[234:237], v[68:71]
	v_mfma_f32_16x16x32_bf16 v[124:127], v[174:177], v[214:217], v[124:127]
	v_mfma_f32_16x16x32_bf16 v[116:119], v[182:185], v[214:217], v[116:119]
	v_mfma_f32_16x16x32_bf16 v[108:111], v[174:177], v[222:225], v[108:111]
	v_mfma_f32_16x16x32_bf16 v[100:103], v[182:185], v[222:225], v[100:103]
	v_mfma_f32_16x16x32_bf16 v[92:95], v[174:177], v[230:233], v[92:95]
	v_mfma_f32_16x16x32_bf16 v[84:87], v[182:185], v[230:233], v[84:87]
	v_mfma_f32_16x16x32_bf16 v[76:79], v[174:177], v[238:241], v[76:79]
	v_mfma_f32_16x16x32_bf16 v[68:71], v[182:185], v[238:241], v[68:71]
	v_mfma_f32_16x16x32_bf16 v[120:123], v[186:189], v[210:213], v[120:123]
	v_mfma_f32_16x16x32_bf16 v[112:115], v[194:197], v[210:213], v[112:115]
	v_mfma_f32_16x16x32_bf16 v[104:107], v[186:189], v[218:221], v[104:107]
	v_mfma_f32_16x16x32_bf16 v[96:99], v[194:197], v[218:221], v[96:99]
	v_mfma_f32_16x16x32_bf16 v[88:91], v[186:189], v[226:229], v[88:91]
	v_mfma_f32_16x16x32_bf16 v[80:83], v[194:197], v[226:229], v[80:83]
	v_mfma_f32_16x16x32_bf16 v[72:75], v[186:189], v[234:237], v[72:75]
	v_mfma_f32_16x16x32_bf16 v[64:67], v[194:197], v[234:237], v[64:67]
	v_mfma_f32_16x16x32_bf16 v[120:123], v[190:193], v[214:217], v[120:123]
	v_mfma_f32_16x16x32_bf16 v[112:115], v[198:201], v[214:217], v[112:115]
	v_mfma_f32_16x16x32_bf16 v[104:107], v[190:193], v[222:225], v[104:107]
	v_mfma_f32_16x16x32_bf16 v[96:99], v[198:201], v[222:225], v[96:99]
	v_mfma_f32_16x16x32_bf16 v[88:91], v[190:193], v[230:233], v[88:91]
	v_mfma_f32_16x16x32_bf16 v[80:83], v[198:201], v[230:233], v[80:83]
	v_mfma_f32_16x16x32_bf16 v[72:75], v[190:193], v[238:241], v[72:75]
	v_mfma_f32_16x16x32_bf16 v[64:67], v[198:201], v[238:241], v[64:67]
	s_barrier
	s_add_i32 s55, s48, s38
	v_lshl_add_u64 v[164:165], s[26:27], 0, v[134:135]
	s_mov_b32 m0, s55
	ds_read_b128 v[210:213], v169 offset:16384
	ds_read_b128 v[214:217], v169 offset:17408
	ds_read_b128 v[218:221], v169 offset:18432
	ds_read_b128 v[222:225], v169 offset:19456
	ds_read_b128 v[226:229], v169 offset:20480
	ds_read_b128 v[230:233], v169 offset:21504
	ds_read_b128 v[234:237], v169 offset:22528
	ds_read_b128 v[238:241], v169 offset:23552
	global_load_lds_dwordx4 v[164:165], off
	s_add_i32 m0, s55, 0x2000
	s_add_u32 s56, s26, 0x4000
	v_lshl_add_u64 v[164:165], s[26:27], 0, v[130:131]
	s_addc_u32 s57, s27, 0
	s_add_i32 s55, s49, s38
	global_load_lds_dwordx4 v[164:165], off
	v_lshl_add_u64 v[164:165], s[56:57], 0, v[134:135]
	s_mov_b32 m0, s55
	v_lshl_add_u64 v[242:243], s[28:29], 0, v[132:133]
	global_load_lds_dwordx4 v[164:165], off
	v_lshl_add_u64 v[164:165], s[56:57], 0, v[130:131]
	s_add_i32 m0, s55, 0x2000
	s_nop 0
	global_load_lds_dwordx4 v[164:165], off
	v_lshl_add_u64 v[164:165], s[28:29], 0, v[136:137]
	s_mov_b32 m0, s21
	s_nop 0
	global_load_lds_dwordx4 v[164:165], off
	s_mov_b32 m0, s23
	s_nop 0
	global_load_lds_dwordx4 v[242:243], off
	s_waitcnt vmcnt(8)
	s_waitcnt lgkmcnt(0)
	s_barrier
	s_waitcnt lgkmcnt(0)
	v_mfma_f32_16x16x32_bf16 v[60:63], v[170:173], v[210:213], v[60:63]
	v_mfma_f32_16x16x32_bf16 v[52:55], v[178:181], v[210:213], v[52:55]
	v_mfma_f32_16x16x32_bf16 v[44:47], v[170:173], v[218:221], v[44:47]
	v_mfma_f32_16x16x32_bf16 v[36:39], v[178:181], v[218:221], v[36:39]
	v_mfma_f32_16x16x32_bf16 v[28:31], v[170:173], v[226:229], v[28:31]
	v_mfma_f32_16x16x32_bf16 v[20:23], v[178:181], v[226:229], v[20:23]
	v_mfma_f32_16x16x32_bf16 v[12:15], v[170:173], v[234:237], v[12:15]
	v_mfma_f32_16x16x32_bf16 v[4:7], v[178:181], v[234:237], v[4:7]
	v_mfma_f32_16x16x32_bf16 v[60:63], v[174:177], v[214:217], v[60:63]
	v_mfma_f32_16x16x32_bf16 v[52:55], v[182:185], v[214:217], v[52:55]
	v_mfma_f32_16x16x32_bf16 v[44:47], v[174:177], v[222:225], v[44:47]
	v_mfma_f32_16x16x32_bf16 v[36:39], v[182:185], v[222:225], v[36:39]
	v_mfma_f32_16x16x32_bf16 v[28:31], v[174:177], v[230:233], v[28:31]
	v_mfma_f32_16x16x32_bf16 v[20:23], v[182:185], v[230:233], v[20:23]
	v_mfma_f32_16x16x32_bf16 v[12:15], v[174:177], v[238:241], v[12:15]
	v_mfma_f32_16x16x32_bf16 v[4:7], v[182:185], v[238:241], v[4:7]
	v_mfma_f32_16x16x32_bf16 v[56:59], v[186:189], v[210:213], v[56:59]
	v_mfma_f32_16x16x32_bf16 v[48:51], v[194:197], v[210:213], v[48:51]
	v_mfma_f32_16x16x32_bf16 v[40:43], v[186:189], v[218:221], v[40:43]
	v_mfma_f32_16x16x32_bf16 v[32:35], v[194:197], v[218:221], v[32:35]
	v_mfma_f32_16x16x32_bf16 v[24:27], v[186:189], v[226:229], v[24:27]
	v_mfma_f32_16x16x32_bf16 v[16:19], v[194:197], v[226:229], v[16:19]
	v_mfma_f32_16x16x32_bf16 v[8:11], v[186:189], v[234:237], v[8:11]
	v_mfma_f32_16x16x32_bf16 v[0:3], v[194:197], v[234:237], v[0:3]
	v_mfma_f32_16x16x32_bf16 v[56:59], v[190:193], v[214:217], v[56:59]
	v_mfma_f32_16x16x32_bf16 v[48:51], v[198:201], v[214:217], v[48:51]
	v_mfma_f32_16x16x32_bf16 v[40:43], v[190:193], v[222:225], v[40:43]
	v_mfma_f32_16x16x32_bf16 v[32:35], v[198:201], v[222:225], v[32:35]
	v_mfma_f32_16x16x32_bf16 v[24:27], v[190:193], v[230:233], v[24:27]
	v_mfma_f32_16x16x32_bf16 v[16:19], v[198:201], v[230:233], v[16:19]
	v_mfma_f32_16x16x32_bf16 v[8:11], v[190:193], v[238:241], v[8:11]
	v_mfma_f32_16x16x32_bf16 v[0:3], v[198:201], v[238:241], v[0:3]
	s_barrier
	s_add_i32 s55, 0, 0x18000
	s_add_i32 s56, 0, 0x1c000
	v_add_u32_e32 v182, s55, v129
	v_add_u32_e32 v198, s56, v129
	ds_read_b128 v[170:173], v182
	ds_read_b128 v[174:177], v182 offset:1024
	ds_read_b128 v[178:181], v182 offset:2048
	ds_read_b128 v[182:185], v182 offset:3072
	ds_read_b128 v[186:189], v198
	ds_read_b128 v[190:193], v198 offset:1024
	ds_read_b128 v[194:197], v198 offset:2048
	ds_read_b128 v[198:201], v198 offset:3072
	s_add_u32 s28, s28, 0x40000
	s_addc_u32 s29, s29, 0
	s_mov_b32 m0, s41
	v_lshl_add_u64 v[244:245], s[28:29], 0, v[136:137]
	ds_read_b128 v[210:213], v169 offset:32768
	ds_read_b128 v[214:217], v169 offset:33792
	ds_read_b128 v[218:221], v169 offset:34816
	ds_read_b128 v[222:225], v169 offset:35840
	ds_read_b128 v[226:229], v169 offset:36864
	ds_read_b128 v[230:233], v169 offset:37888
	ds_read_b128 v[234:237], v169 offset:38912
	ds_read_b128 v[238:241], v169 offset:39936
	global_load_lds_dwordx4 v[244:245], off
	v_lshl_add_u64 v[244:245], s[28:29], 0, v[132:133]
	s_mov_b32 m0, s42
	s_nop 0
	global_load_lds_dwordx4 v[244:245], off
	s_waitcnt vmcnt(8)
	s_waitcnt lgkmcnt(0)
	s_barrier
	s_waitcnt lgkmcnt(0)
	v_mfma_f32_16x16x32_bf16 v[124:127], v[170:173], v[210:213], v[124:127]
	v_mfma_f32_16x16x32_bf16 v[116:119], v[178:181], v[210:213], v[116:119]
	v_mfma_f32_16x16x32_bf16 v[108:111], v[170:173], v[218:221], v[108:111]
	v_mfma_f32_16x16x32_bf16 v[100:103], v[178:181], v[218:221], v[100:103]
	v_mfma_f32_16x16x32_bf16 v[92:95], v[170:173], v[226:229], v[92:95]
	v_mfma_f32_16x16x32_bf16 v[84:87], v[178:181], v[226:229], v[84:87]
	v_mfma_f32_16x16x32_bf16 v[76:79], v[170:173], v[234:237], v[76:79]
	v_mfma_f32_16x16x32_bf16 v[68:71], v[178:181], v[234:237], v[68:71]
	v_mfma_f32_16x16x32_bf16 v[124:127], v[174:177], v[214:217], v[124:127]
	v_mfma_f32_16x16x32_bf16 v[116:119], v[182:185], v[214:217], v[116:119]
	v_mfma_f32_16x16x32_bf16 v[108:111], v[174:177], v[222:225], v[108:111]
	v_mfma_f32_16x16x32_bf16 v[100:103], v[182:185], v[222:225], v[100:103]
	v_mfma_f32_16x16x32_bf16 v[92:95], v[174:177], v[230:233], v[92:95]
	v_mfma_f32_16x16x32_bf16 v[84:87], v[182:185], v[230:233], v[84:87]
	v_mfma_f32_16x16x32_bf16 v[76:79], v[174:177], v[238:241], v[76:79]
	v_mfma_f32_16x16x32_bf16 v[68:71], v[182:185], v[238:241], v[68:71]
	v_mfma_f32_16x16x32_bf16 v[120:123], v[186:189], v[210:213], v[120:123]
	v_mfma_f32_16x16x32_bf16 v[112:115], v[194:197], v[210:213], v[112:115]
	v_mfma_f32_16x16x32_bf16 v[104:107], v[186:189], v[218:221], v[104:107]
	v_mfma_f32_16x16x32_bf16 v[96:99], v[194:197], v[218:221], v[96:99]
	v_mfma_f32_16x16x32_bf16 v[88:91], v[186:189], v[226:229], v[88:91]
	v_mfma_f32_16x16x32_bf16 v[80:83], v[194:197], v[226:229], v[80:83]
	v_mfma_f32_16x16x32_bf16 v[72:75], v[186:189], v[234:237], v[72:75]
	v_mfma_f32_16x16x32_bf16 v[64:67], v[194:197], v[234:237], v[64:67]
	v_mfma_f32_16x16x32_bf16 v[120:123], v[190:193], v[214:217], v[120:123]
	v_mfma_f32_16x16x32_bf16 v[112:115], v[198:201], v[214:217], v[112:115]
	v_mfma_f32_16x16x32_bf16 v[104:107], v[190:193], v[222:225], v[104:107]
	v_mfma_f32_16x16x32_bf16 v[96:99], v[198:201], v[222:225], v[96:99]
	v_mfma_f32_16x16x32_bf16 v[88:91], v[190:193], v[230:233], v[88:91]
	v_mfma_f32_16x16x32_bf16 v[80:83], v[198:201], v[230:233], v[80:83]
	v_mfma_f32_16x16x32_bf16 v[72:75], v[190:193], v[238:241], v[72:75]
	v_mfma_f32_16x16x32_bf16 v[64:67], v[198:201], v[238:241], v[64:67]
	s_barrier
	s_add_u32 s28, s26, 0x8000
	s_addc_u32 s29, s27, 0
	s_add_i32 s55, s55, s38
	v_lshl_add_u64 v[244:245], s[28:29], 0, v[134:135]
	s_mov_b32 m0, s55
	ds_read_b128 v[210:213], v169 offset:49152
	ds_read_b128 v[214:217], v169 offset:50176
	ds_read_b128 v[218:221], v169 offset:51200
	ds_read_b128 v[222:225], v169 offset:52224
	ds_read_b128 v[226:229], v169 offset:53248
	ds_read_b128 v[230:233], v169 offset:54272
	ds_read_b128 v[234:237], v169 offset:55296
	ds_read_b128 v[238:241], v169 offset:56320
	global_load_lds_dwordx4 v[244:245], off
	s_add_i32 m0, s55, 0x2000
	s_add_u32 s26, s26, 0xc000
	v_lshl_add_u64 v[244:245], s[28:29], 0, v[130:131]
	s_addc_u32 s27, s27, 0
	s_add_i32 s28, s56, s38
	global_load_lds_dwordx4 v[244:245], off
	v_lshl_add_u64 v[244:245], s[26:27], 0, v[134:135]
	s_mov_b32 m0, s28
	v_lshl_add_u64 v[164:165], v[164:165], 0, s[8:9]
	global_load_lds_dwordx4 v[244:245], off
	v_lshl_add_u64 v[244:245], s[26:27], 0, v[130:131]
	s_add_i32 m0, s28, 0x2000
	s_nop 0
	global_load_lds_dwordx4 v[244:245], off
	s_mov_b32 m0, s45
	s_nop 0
	global_load_lds_dwordx4 v[164:165], off
	v_lshl_add_u64 v[164:165], v[242:243], 0, s[8:9]
	s_mov_b32 m0, s46
	s_nop 0
	global_load_lds_dwordx4 v[164:165], off
	s_waitcnt vmcnt(8)
	s_waitcnt lgkmcnt(0)
	s_barrier
	s_waitcnt lgkmcnt(0)
	v_mfma_f32_16x16x32_bf16 v[60:63], v[170:173], v[210:213], v[60:63]
	v_mfma_f32_16x16x32_bf16 v[52:55], v[178:181], v[210:213], v[52:55]
	v_mfma_f32_16x16x32_bf16 v[44:47], v[170:173], v[218:221], v[44:47]
	v_mfma_f32_16x16x32_bf16 v[36:39], v[178:181], v[218:221], v[36:39]
	v_mfma_f32_16x16x32_bf16 v[28:31], v[170:173], v[226:229], v[28:31]
	v_mfma_f32_16x16x32_bf16 v[20:23], v[178:181], v[226:229], v[20:23]
	v_mfma_f32_16x16x32_bf16 v[12:15], v[170:173], v[234:237], v[12:15]
	v_mfma_f32_16x16x32_bf16 v[4:7], v[178:181], v[234:237], v[4:7]
	v_mfma_f32_16x16x32_bf16 v[60:63], v[174:177], v[214:217], v[60:63]
	v_mfma_f32_16x16x32_bf16 v[52:55], v[182:185], v[214:217], v[52:55]
	v_mfma_f32_16x16x32_bf16 v[44:47], v[174:177], v[222:225], v[44:47]
	v_mfma_f32_16x16x32_bf16 v[36:39], v[182:185], v[222:225], v[36:39]
	v_mfma_f32_16x16x32_bf16 v[28:31], v[174:177], v[230:233], v[28:31]
	v_mfma_f32_16x16x32_bf16 v[20:23], v[182:185], v[230:233], v[20:23]
	v_mfma_f32_16x16x32_bf16 v[12:15], v[174:177], v[238:241], v[12:15]
	v_mfma_f32_16x16x32_bf16 v[4:7], v[182:185], v[238:241], v[4:7]
	v_mfma_f32_16x16x32_bf16 v[56:59], v[186:189], v[210:213], v[56:59]
	v_mfma_f32_16x16x32_bf16 v[48:51], v[194:197], v[210:213], v[48:51]
	v_mfma_f32_16x16x32_bf16 v[40:43], v[186:189], v[218:221], v[40:43]
	v_mfma_f32_16x16x32_bf16 v[32:35], v[194:197], v[218:221], v[32:35]
	v_mfma_f32_16x16x32_bf16 v[24:27], v[186:189], v[226:229], v[24:27]
	v_mfma_f32_16x16x32_bf16 v[16:19], v[194:197], v[226:229], v[16:19]
	v_mfma_f32_16x16x32_bf16 v[8:11], v[186:189], v[234:237], v[8:11]
	v_mfma_f32_16x16x32_bf16 v[0:3], v[194:197], v[234:237], v[0:3]
	v_mfma_f32_16x16x32_bf16 v[56:59], v[190:193], v[214:217], v[56:59]
	v_mfma_f32_16x16x32_bf16 v[48:51], v[198:201], v[214:217], v[48:51]
	v_mfma_f32_16x16x32_bf16 v[40:43], v[190:193], v[222:225], v[40:43]
	v_mfma_f32_16x16x32_bf16 v[32:35], v[198:201], v[222:225], v[32:35]
	v_mfma_f32_16x16x32_bf16 v[24:27], v[190:193], v[230:233], v[24:27]
	v_mfma_f32_16x16x32_bf16 v[16:19], v[198:201], v[230:233], v[16:19]
	v_mfma_f32_16x16x32_bf16 v[8:11], v[190:193], v[238:241], v[8:11]
	v_mfma_f32_16x16x32_bf16 v[0:3], v[198:201], v[238:241], v[0:3]
	s_barrier
	s_add_i32 s54, s54, 2
	s_add_u32 s52, s52, 0x10000
	s_addc_u32 s53, s53, 0
	s_add_u32 s24, s24, 0x100
	s_addc_u32 s25, s25, 0
	s_cmp_gt_u32 s54, 13
	s_cbranch_scc0 .LBB0_289
	s_and_b64 vcc, exec, s[10:11]
	s_cbranch_vccz .LBB0_292
	s_barrier

.LBB0_408:
	v_add_u32_e32 v168, s71, v182
	v_add_u32_e32 v204, s72, v182
	ds_read_b128 v[156:159], v168
	ds_read_b128 v[160:163], v168 offset:1024
	ds_read_b128 v[164:167], v168 offset:2048
	ds_read_b128 v[168:171], v168 offset:3072
	ds_read_b128 v[172:175], v204
	ds_read_b128 v[176:179], v204 offset:1024
	ds_read_b128 v[212:215], v204 offset:2048
	ds_read_b128 v[216:219], v204 offset:3072
	s_add_u32 s40, s38, 0x4000
	s_addc_u32 s41, s39, 0
	s_cmp_eq_u32 s49, 40
	s_cselect_b32 s44, s0, s40
	s_cselect_b32 s45, s1, s41
	s_cselect_b32 s42, s36, s47
	s_cselect_b32 s43, s37, s48
	s_add_u32 s40, s44, 0x8000
	s_addc_u32 s41, s45, 0
	v_lshl_add_u64 v[252:253], s[38:39], 0, v[150:151]
	s_add_i32 m0, s58, 0xc000
	ds_read_b128 v[220:223], v199
	ds_read_b128 v[224:227], v199 offset:1024
	ds_read_b128 v[228:231], v199 offset:2048
	ds_read_b128 v[232:235], v199 offset:3072
	ds_read_b128 v[236:239], v199 offset:4096
	ds_read_b128 v[240:243], v199 offset:5120
	ds_read_b128 v[244:247], v199 offset:6144
	ds_read_b128 v[248:251], v199 offset:7168
	global_load_lds_dwordx4 v[252:253], off
	v_lshl_add_u64 v[252:253], s[38:39], 0, v[148:149]
	s_add_i32 m0, s58, 0xe000
	s_nop 0
	global_load_lds_dwordx4 v[252:253], off
	s_waitcnt vmcnt(8)
	s_waitcnt lgkmcnt(0)
	s_barrier
	s_waitcnt lgkmcnt(0)
	v_mfma_f32_16x16x32_bf16 v[124:127], v[156:159], v[220:223], v[124:127]
	v_mfma_f32_16x16x32_bf16 v[120:123], v[164:167], v[220:223], v[120:123]
	v_mfma_f32_16x16x32_bf16 v[116:119], v[156:159], v[228:231], v[116:119]
	v_mfma_f32_16x16x32_bf16 v[108:111], v[164:167], v[228:231], v[108:111]
	v_mfma_f32_16x16x32_bf16 v[92:95], v[156:159], v[236:239], v[92:95]
	v_mfma_f32_16x16x32_bf16 v[88:91], v[164:167], v[236:239], v[88:91]
	v_mfma_f32_16x16x32_bf16 v[84:87], v[156:159], v[244:247], v[84:87]
	v_mfma_f32_16x16x32_bf16 v[76:79], v[164:167], v[244:247], v[76:79]
	v_mfma_f32_16x16x32_bf16 v[124:127], v[160:163], v[224:227], v[124:127]
	v_mfma_f32_16x16x32_bf16 v[120:123], v[168:171], v[224:227], v[120:123]
	v_mfma_f32_16x16x32_bf16 v[116:119], v[160:163], v[232:235], v[116:119]
	v_mfma_f32_16x16x32_bf16 v[108:111], v[168:171], v[232:235], v[108:111]
	v_mfma_f32_16x16x32_bf16 v[92:95], v[160:163], v[240:243], v[92:95]
	v_mfma_f32_16x16x32_bf16 v[88:91], v[168:171], v[240:243], v[88:91]
	v_mfma_f32_16x16x32_bf16 v[84:87], v[160:163], v[248:251], v[84:87]
	v_mfma_f32_16x16x32_bf16 v[76:79], v[168:171], v[248:251], v[76:79]
	v_mfma_f32_16x16x32_bf16 v[112:115], v[172:175], v[220:223], v[112:115]
	v_mfma_f32_16x16x32_bf16 v[104:107], v[212:215], v[220:223], v[104:107]
	v_mfma_f32_16x16x32_bf16 v[100:103], v[172:175], v[228:231], v[100:103]
	v_mfma_f32_16x16x32_bf16 v[96:99], v[212:215], v[228:231], v[96:99]
	v_mfma_f32_16x16x32_bf16 v[80:83], v[172:175], v[236:239], v[80:83]
	v_mfma_f32_16x16x32_bf16 v[72:75], v[212:215], v[236:239], v[72:75]
	v_mfma_f32_16x16x32_bf16 v[68:71], v[172:175], v[244:247], v[68:71]
	v_mfma_f32_16x16x32_bf16 v[64:67], v[212:215], v[244:247], v[64:67]
	v_mfma_f32_16x16x32_bf16 v[112:115], v[176:179], v[224:227], v[112:115]
	v_mfma_f32_16x16x32_bf16 v[104:107], v[216:219], v[224:227], v[104:107]
	v_mfma_f32_16x16x32_bf16 v[100:103], v[176:179], v[232:235], v[100:103]
	v_mfma_f32_16x16x32_bf16 v[96:99], v[216:219], v[232:235], v[96:99]
	v_mfma_f32_16x16x32_bf16 v[80:83], v[176:179], v[240:243], v[80:83]
	v_mfma_f32_16x16x32_bf16 v[72:75], v[216:219], v[240:243], v[72:75]
	v_mfma_f32_16x16x32_bf16 v[68:71], v[176:179], v[248:251], v[68:71]
	v_mfma_f32_16x16x32_bf16 v[64:67], v[216:219], v[248:251], v[64:67]
	s_barrier
	s_add_i32 s50, s71, s57
	v_lshl_add_u64 v[252:253], s[42:43], 0, v[128:129]
	s_mov_b32 m0, s50
	ds_read_b128 v[220:223], v199 offset:16384
	ds_read_b128 v[224:227], v199 offset:17408
	ds_read_b128 v[228:231], v199 offset:18432
	ds_read_b128 v[232:235], v199 offset:19456
	ds_read_b128 v[236:239], v199 offset:20480
	ds_read_b128 v[240:243], v199 offset:21504
	ds_read_b128 v[244:247], v199 offset:22528
	ds_read_b128 v[248:251], v199 offset:23552
	global_load_lds_dwordx4 v[252:253], off
	s_add_i32 m0, s50, 0x2000
	s_add_u32 s50, s42, 0x4000
	v_lshl_add_u64 v[252:253], s[42:43], 0, v[130:131]
	s_addc_u32 s51, s43, 0
	s_add_i32 s52, s72, s57
	global_load_lds_dwordx4 v[252:253], off
	v_lshl_add_u64 v[252:253], s[50:51], 0, v[128:129]
	s_mov_b32 m0, s52
	s_nop 0
	global_load_lds_dwordx4 v[252:253], off
	v_lshl_add_u64 v[252:253], s[50:51], 0, v[130:131]
	s_add_i32 m0, s52, 0x2000
	s_nop 0
	global_load_lds_dwordx4 v[252:253], off
	v_lshl_add_u64 v[252:253], s[44:45], 0, v[128:129]
	s_mov_b32 m0, s58
	s_nop 0
	global_load_lds_dwordx4 v[252:253], off
	v_lshl_add_u64 v[252:253], s[44:45], 0, v[130:131]
	s_mov_b32 m0, s59
	s_nop 0
	global_load_lds_dwordx4 v[252:253], off
	s_waitcnt vmcnt(8)
	s_waitcnt lgkmcnt(0)
	s_barrier
	s_waitcnt lgkmcnt(0)
	v_mfma_f32_16x16x32_bf16 v[60:63], v[156:159], v[220:223], v[60:63]
	v_mfma_f32_16x16x32_bf16 v[56:59], v[164:167], v[220:223], v[56:59]
	v_mfma_f32_16x16x32_bf16 v[52:55], v[156:159], v[228:231], v[52:55]
	v_mfma_f32_16x16x32_bf16 v[44:47], v[164:167], v[228:231], v[44:47]
	v_mfma_f32_16x16x32_bf16 v[32:35], v[156:159], v[236:239], v[32:35]
	v_mfma_f32_16x16x32_bf16 v[24:27], v[164:167], v[236:239], v[24:27]
	v_mfma_f32_16x16x32_bf16 v[20:23], v[156:159], v[244:247], v[20:23]
	v_mfma_f32_16x16x32_bf16 v[12:15], v[164:167], v[244:247], v[12:15]
	v_mfma_f32_16x16x32_bf16 v[60:63], v[160:163], v[224:227], v[60:63]
	v_mfma_f32_16x16x32_bf16 v[56:59], v[168:171], v[224:227], v[56:59]
	v_mfma_f32_16x16x32_bf16 v[52:55], v[160:163], v[232:235], v[52:55]
	v_mfma_f32_16x16x32_bf16 v[44:47], v[168:171], v[232:235], v[44:47]
	v_mfma_f32_16x16x32_bf16 v[32:35], v[160:163], v[240:243], v[32:35]
	v_mfma_f32_16x16x32_bf16 v[24:27], v[168:171], v[240:243], v[24:27]
	v_mfma_f32_16x16x32_bf16 v[20:23], v[160:163], v[248:251], v[20:23]
	v_mfma_f32_16x16x32_bf16 v[12:15], v[168:171], v[248:251], v[12:15]
	v_mfma_f32_16x16x32_bf16 v[48:51], v[172:175], v[220:223], v[48:51]
	v_mfma_f32_16x16x32_bf16 v[40:43], v[212:215], v[220:223], v[40:43]
	v_mfma_f32_16x16x32_bf16 v[36:39], v[172:175], v[228:231], v[36:39]
	v_mfma_f32_16x16x32_bf16 v[28:31], v[212:215], v[228:231], v[28:31]
	v_mfma_f32_16x16x32_bf16 v[16:19], v[172:175], v[236:239], v[16:19]
	v_mfma_f32_16x16x32_bf16 v[8:11], v[212:215], v[236:239], v[8:11]
	v_mfma_f32_16x16x32_bf16 v[4:7], v[172:175], v[244:247], v[4:7]
	v_mfma_f32_16x16x32_bf16 v[0:3], v[212:215], v[244:247], v[0:3]
	v_mfma_f32_16x16x32_bf16 v[48:51], v[176:179], v[224:227], v[48:51]
	v_mfma_f32_16x16x32_bf16 v[40:43], v[216:219], v[224:227], v[40:43]
	v_mfma_f32_16x16x32_bf16 v[36:39], v[176:179], v[232:235], v[36:39]
	v_mfma_f32_16x16x32_bf16 v[28:31], v[216:219], v[232:235], v[28:31]
	v_mfma_f32_16x16x32_bf16 v[16:19], v[176:179], v[240:243], v[16:19]
	v_mfma_f32_16x16x32_bf16 v[8:11], v[216:219], v[240:243], v[8:11]
	v_mfma_f32_16x16x32_bf16 v[4:7], v[176:179], v[248:251], v[4:7]
	v_mfma_f32_16x16x32_bf16 v[0:3], v[216:219], v[248:251], v[0:3]
	s_barrier
	s_add_i32 s50, 0, 0x18000
	s_add_i32 s51, 0, 0x1c000
	v_add_u32_e32 v168, s50, v182
	v_add_u32_e32 v204, s51, v182
	ds_read_b128 v[156:159], v168
	ds_read_b128 v[160:163], v168 offset:1024
	ds_read_b128 v[164:167], v168 offset:2048
	ds_read_b128 v[168:171], v168 offset:3072
	ds_read_b128 v[172:175], v204
	ds_read_b128 v[176:179], v204 offset:1024
	ds_read_b128 v[212:215], v204 offset:2048
	ds_read_b128 v[216:219], v204 offset:3072
	s_add_u32 s44, s44, 0x4000
	s_addc_u32 s45, s45, 0
	s_mov_b32 m0, s60
	v_lshl_add_u64 v[252:253], s[44:45], 0, v[128:129]
	ds_read_b128 v[220:223], v199 offset:32768
	ds_read_b128 v[224:227], v199 offset:33792
	ds_read_b128 v[228:231], v199 offset:34816
	ds_read_b128 v[232:235], v199 offset:35840
	ds_read_b128 v[236:239], v199 offset:36864
	ds_read_b128 v[240:243], v199 offset:37888
	ds_read_b128 v[244:247], v199 offset:38912
	ds_read_b128 v[248:251], v199 offset:39936
	global_load_lds_dwordx4 v[252:253], off
	v_lshl_add_u64 v[252:253], s[44:45], 0, v[130:131]
	s_mov_b32 m0, s61
	s_nop 0
	global_load_lds_dwordx4 v[252:253], off
	s_waitcnt vmcnt(8)
	s_waitcnt lgkmcnt(0)
	s_barrier
	s_waitcnt lgkmcnt(0)
	v_mfma_f32_16x16x32_bf16 v[124:127], v[156:159], v[220:223], v[124:127]
	v_mfma_f32_16x16x32_bf16 v[120:123], v[164:167], v[220:223], v[120:123]
	v_mfma_f32_16x16x32_bf16 v[116:119], v[156:159], v[228:231], v[116:119]
	v_mfma_f32_16x16x32_bf16 v[108:111], v[164:167], v[228:231], v[108:111]
	v_mfma_f32_16x16x32_bf16 v[92:95], v[156:159], v[236:239], v[92:95]
	v_mfma_f32_16x16x32_bf16 v[88:91], v[164:167], v[236:239], v[88:91]
	v_mfma_f32_16x16x32_bf16 v[84:87], v[156:159], v[244:247], v[84:87]
	v_mfma_f32_16x16x32_bf16 v[76:79], v[164:167], v[244:247], v[76:79]
	v_mfma_f32_16x16x32_bf16 v[124:127], v[160:163], v[224:227], v[124:127]
	v_mfma_f32_16x16x32_bf16 v[120:123], v[168:171], v[224:227], v[120:123]
	v_mfma_f32_16x16x32_bf16 v[116:119], v[160:163], v[232:235], v[116:119]
	v_mfma_f32_16x16x32_bf16 v[108:111], v[168:171], v[232:235], v[108:111]
	v_mfma_f32_16x16x32_bf16 v[92:95], v[160:163], v[240:243], v[92:95]
	v_mfma_f32_16x16x32_bf16 v[88:91], v[168:171], v[240:243], v[88:91]
	v_mfma_f32_16x16x32_bf16 v[84:87], v[160:163], v[248:251], v[84:87]
	v_mfma_f32_16x16x32_bf16 v[76:79], v[168:171], v[248:251], v[76:79]
	v_mfma_f32_16x16x32_bf16 v[112:115], v[172:175], v[220:223], v[112:115]
	v_mfma_f32_16x16x32_bf16 v[104:107], v[212:215], v[220:223], v[104:107]
	v_mfma_f32_16x16x32_bf16 v[100:103], v[172:175], v[228:231], v[100:103]
	v_mfma_f32_16x16x32_bf16 v[96:99], v[212:215], v[228:231], v[96:99]
	v_mfma_f32_16x16x32_bf16 v[80:83], v[172:175], v[236:239], v[80:83]
	v_mfma_f32_16x16x32_bf16 v[72:75], v[212:215], v[236:239], v[72:75]
	v_mfma_f32_16x16x32_bf16 v[68:71], v[172:175], v[244:247], v[68:71]
	v_mfma_f32_16x16x32_bf16 v[64:67], v[212:215], v[244:247], v[64:67]
	v_mfma_f32_16x16x32_bf16 v[112:115], v[176:179], v[224:227], v[112:115]
	v_mfma_f32_16x16x32_bf16 v[104:107], v[216:219], v[224:227], v[104:107]
	v_mfma_f32_16x16x32_bf16 v[100:103], v[176:179], v[232:235], v[100:103]
	v_mfma_f32_16x16x32_bf16 v[96:99], v[216:219], v[232:235], v[96:99]
	v_mfma_f32_16x16x32_bf16 v[80:83], v[176:179], v[240:243], v[80:83]
	v_mfma_f32_16x16x32_bf16 v[72:75], v[216:219], v[240:243], v[72:75]
	v_mfma_f32_16x16x32_bf16 v[68:71], v[176:179], v[248:251], v[68:71]
	v_mfma_f32_16x16x32_bf16 v[64:67], v[216:219], v[248:251], v[64:67]
	s_barrier
	s_add_u32 s44, s42, 0x8000
	s_addc_u32 s45, s43, 0
	s_add_i32 s50, s50, s57
	v_lshl_add_u64 v[252:253], s[44:45], 0, v[128:129]
	s_mov_b32 m0, s50
	ds_read_b128 v[220:223], v199 offset:49152
	ds_read_b128 v[224:227], v199 offset:50176
	ds_read_b128 v[228:231], v199 offset:51200
	ds_read_b128 v[232:235], v199 offset:52224
	ds_read_b128 v[236:239], v199 offset:53248
	ds_read_b128 v[240:243], v199 offset:54272
	ds_read_b128 v[244:247], v199 offset:55296
	ds_read_b128 v[248:251], v199 offset:56320
	global_load_lds_dwordx4 v[252:253], off
	s_add_i32 m0, s50, 0x2000
	s_add_u32 s42, s42, 0xc000
	v_lshl_add_u64 v[252:253], s[44:45], 0, v[130:131]
	s_addc_u32 s43, s43, 0
	s_add_i32 s44, s51, s57
	global_load_lds_dwordx4 v[252:253], off
	v_lshl_add_u64 v[252:253], s[42:43], 0, v[128:129]
	s_mov_b32 m0, s44
	s_nop 0
	global_load_lds_dwordx4 v[252:253], off
	v_lshl_add_u64 v[252:253], s[42:43], 0, v[130:131]
	s_add_i32 m0, s44, 0x2000
	s_nop 0
	global_load_lds_dwordx4 v[252:253], off
	v_lshl_add_u64 v[252:253], s[40:41], 0, v[128:129]
	s_mov_b32 m0, s67
	s_nop 0
	global_load_lds_dwordx4 v[252:253], off
	v_lshl_add_u64 v[252:253], s[40:41], 0, v[130:131]
	s_mov_b32 m0, s68
	s_nop 0
	global_load_lds_dwordx4 v[252:253], off
	s_waitcnt vmcnt(8)
	s_waitcnt lgkmcnt(0)
	s_barrier
	s_waitcnt lgkmcnt(0)
	v_mfma_f32_16x16x32_bf16 v[60:63], v[156:159], v[220:223], v[60:63]
	v_mfma_f32_16x16x32_bf16 v[56:59], v[164:167], v[220:223], v[56:59]
	v_mfma_f32_16x16x32_bf16 v[52:55], v[156:159], v[228:231], v[52:55]
	v_mfma_f32_16x16x32_bf16 v[44:47], v[164:167], v[228:231], v[44:47]
	v_mfma_f32_16x16x32_bf16 v[32:35], v[156:159], v[236:239], v[32:35]
	v_mfma_f32_16x16x32_bf16 v[24:27], v[164:167], v[236:239], v[24:27]
	v_mfma_f32_16x16x32_bf16 v[20:23], v[156:159], v[244:247], v[20:23]
	v_mfma_f32_16x16x32_bf16 v[12:15], v[164:167], v[244:247], v[12:15]
	v_mfma_f32_16x16x32_bf16 v[60:63], v[160:163], v[224:227], v[60:63]
	v_mfma_f32_16x16x32_bf16 v[56:59], v[168:171], v[224:227], v[56:59]
	v_mfma_f32_16x16x32_bf16 v[52:55], v[160:163], v[232:235], v[52:55]
	v_mfma_f32_16x16x32_bf16 v[44:47], v[168:171], v[232:235], v[44:47]
	v_mfma_f32_16x16x32_bf16 v[32:35], v[160:163], v[240:243], v[32:35]
	v_mfma_f32_16x16x32_bf16 v[24:27], v[168:171], v[240:243], v[24:27]
	v_mfma_f32_16x16x32_bf16 v[20:23], v[160:163], v[248:251], v[20:23]
	v_mfma_f32_16x16x32_bf16 v[12:15], v[168:171], v[248:251], v[12:15]
	v_mfma_f32_16x16x32_bf16 v[48:51], v[172:175], v[220:223], v[48:51]
	v_mfma_f32_16x16x32_bf16 v[40:43], v[212:215], v[220:223], v[40:43]
	v_mfma_f32_16x16x32_bf16 v[36:39], v[172:175], v[228:231], v[36:39]
	v_mfma_f32_16x16x32_bf16 v[28:31], v[212:215], v[228:231], v[28:31]
	v_mfma_f32_16x16x32_bf16 v[16:19], v[172:175], v[236:239], v[16:19]
	v_mfma_f32_16x16x32_bf16 v[8:11], v[212:215], v[236:239], v[8:11]
	v_mfma_f32_16x16x32_bf16 v[4:7], v[172:175], v[244:247], v[4:7]
	v_mfma_f32_16x16x32_bf16 v[0:3], v[212:215], v[244:247], v[0:3]
	v_mfma_f32_16x16x32_bf16 v[48:51], v[176:179], v[224:227], v[48:51]
	v_mfma_f32_16x16x32_bf16 v[40:43], v[216:219], v[224:227], v[40:43]
	v_mfma_f32_16x16x32_bf16 v[36:39], v[176:179], v[232:235], v[36:39]
	v_mfma_f32_16x16x32_bf16 v[28:31], v[216:219], v[232:235], v[28:31]
	v_mfma_f32_16x16x32_bf16 v[16:19], v[176:179], v[240:243], v[16:19]
	v_mfma_f32_16x16x32_bf16 v[8:11], v[216:219], v[240:243], v[8:11]
	v_mfma_f32_16x16x32_bf16 v[4:7], v[176:179], v[248:251], v[4:7]
	v_mfma_f32_16x16x32_bf16 v[0:3], v[216:219], v[248:251], v[0:3]
	s_barrier
	s_add_i32 s49, s49, 2
	s_add_u32 s47, s47, 0x10000
	s_addc_u32 s48, s48, 0
	s_add_u32 s38, s38, 0x10000
	s_addc_u32 s39, s39, 0
	s_cmp_gt_u32 s49, 41
	s_cbranch_scc0 .LBB0_408
	s_and_b64 vcc, exec, s[14:15]
	s_cbranch_vccz .LBB0_411
	s_barrier

.LBB0_492:
	ds_read_b128 v[128:131], v212
	ds_read_b128 v[132:135], v212 offset:1024
	ds_read_b128 v[136:139], v212 offset:2048
	ds_read_b128 v[140:143], v212 offset:3072
	ds_read_b128 v[144:147], v213
	ds_read_b128 v[148:151], v213 offset:1024
	ds_read_b128 v[152:155], v213 offset:2048
	ds_read_b128 v[156:159], v213 offset:3072
	s_add_u32 s34, s30, 0xfffc0080
	s_addc_u32 s35, s31, -1
	s_cmp_eq_u32 s39, 12
	s_cselect_b32 s37, s1, s35
	s_cselect_b32 s36, s7, s34
	s_cselect_b32 s35, s10, s38
	s_cselect_b32 s34, s23, s25
	v_lshl_add_u64 v[200:201], s[30:31], 0, v[190:191]
	s_add_i32 m0, s47, 0xc000
	ds_read_b128 v[160:163], v214
	ds_read_b128 v[164:167], v214 offset:1024
	ds_read_b128 v[196:199], v214 offset:2048
	ds_read_b128 v[216:219], v214 offset:3072
	ds_read_b128 v[220:223], v214 offset:4096
	ds_read_b128 v[224:227], v214 offset:5120
	ds_read_b128 v[228:231], v214 offset:6144
	ds_read_b128 v[232:235], v214 offset:7168
	global_load_lds_dwordx4 v[200:201], off
	v_lshl_add_u64 v[200:201], s[30:31], 0, v[188:189]
	s_add_i32 m0, s47, 0xe000
	s_nop 0
	global_load_lds_dwordx4 v[200:201], off
	s_waitcnt vmcnt(8)
	s_waitcnt lgkmcnt(0)
	s_barrier
	s_waitcnt lgkmcnt(0)
	v_mfma_f32_16x16x32_bf16 v[124:127], v[128:131], v[160:163], v[124:127]
	v_mfma_f32_16x16x32_bf16 v[120:123], v[136:139], v[160:163], v[120:123]
	v_mfma_f32_16x16x32_bf16 v[116:119], v[128:131], v[196:199], v[116:119]
	v_mfma_f32_16x16x32_bf16 v[112:115], v[136:139], v[196:199], v[112:115]
	v_mfma_f32_16x16x32_bf16 v[108:111], v[128:131], v[220:223], v[108:111]
	v_mfma_f32_16x16x32_bf16 v[104:107], v[136:139], v[220:223], v[104:107]
	v_mfma_f32_16x16x32_bf16 v[100:103], v[128:131], v[228:231], v[100:103]
	v_mfma_f32_16x16x32_bf16 v[96:99], v[136:139], v[228:231], v[96:99]
	v_mfma_f32_16x16x32_bf16 v[124:127], v[132:135], v[164:167], v[124:127]
	v_mfma_f32_16x16x32_bf16 v[120:123], v[140:143], v[164:167], v[120:123]
	v_mfma_f32_16x16x32_bf16 v[116:119], v[132:135], v[216:219], v[116:119]
	v_mfma_f32_16x16x32_bf16 v[112:115], v[140:143], v[216:219], v[112:115]
	v_mfma_f32_16x16x32_bf16 v[108:111], v[132:135], v[224:227], v[108:111]
	v_mfma_f32_16x16x32_bf16 v[104:107], v[140:143], v[224:227], v[104:107]
	v_mfma_f32_16x16x32_bf16 v[100:103], v[132:135], v[232:235], v[100:103]
	v_mfma_f32_16x16x32_bf16 v[96:99], v[140:143], v[232:235], v[96:99]
	v_mfma_f32_16x16x32_bf16 v[60:63], v[144:147], v[160:163], v[60:63]
	v_mfma_f32_16x16x32_bf16 v[56:59], v[152:155], v[160:163], v[56:59]
	v_mfma_f32_16x16x32_bf16 v[52:55], v[144:147], v[196:199], v[52:55]
	v_mfma_f32_16x16x32_bf16 v[48:51], v[152:155], v[196:199], v[48:51]
	v_mfma_f32_16x16x32_bf16 v[44:47], v[144:147], v[220:223], v[44:47]
	v_mfma_f32_16x16x32_bf16 v[40:43], v[152:155], v[220:223], v[40:43]
	v_mfma_f32_16x16x32_bf16 v[36:39], v[144:147], v[228:231], v[36:39]
	v_mfma_f32_16x16x32_bf16 v[32:35], v[152:155], v[228:231], v[32:35]
	v_mfma_f32_16x16x32_bf16 v[60:63], v[148:151], v[164:167], v[60:63]
	v_mfma_f32_16x16x32_bf16 v[56:59], v[156:159], v[164:167], v[56:59]
	v_mfma_f32_16x16x32_bf16 v[52:55], v[148:151], v[216:219], v[52:55]
	v_mfma_f32_16x16x32_bf16 v[48:51], v[156:159], v[216:219], v[48:51]
	v_mfma_f32_16x16x32_bf16 v[44:47], v[148:151], v[224:227], v[44:47]
	v_mfma_f32_16x16x32_bf16 v[40:43], v[156:159], v[224:227], v[40:43]
	v_mfma_f32_16x16x32_bf16 v[36:39], v[148:151], v[232:235], v[36:39]
	v_mfma_f32_16x16x32_bf16 v[32:35], v[156:159], v[232:235], v[32:35]
	s_barrier
	s_add_i32 s66, s61, s46
	v_lshl_add_u64 v[200:201], s[34:35], 0, v[172:173]
	s_mov_b32 m0, s66
	ds_read_b128 v[160:163], v214 offset:16384
	ds_read_b128 v[164:167], v214 offset:17408
	ds_read_b128 v[196:199], v214 offset:18432
	ds_read_b128 v[216:219], v214 offset:19456
	ds_read_b128 v[220:223], v214 offset:20480
	ds_read_b128 v[224:227], v214 offset:21504
	ds_read_b128 v[228:231], v214 offset:22528
	ds_read_b128 v[232:235], v214 offset:23552
	global_load_lds_dwordx4 v[200:201], off
	s_add_i32 m0, s66, 0x2000
	s_add_u32 s66, s34, 0x4000
	v_lshl_add_u64 v[200:201], s[34:35], 0, v[176:177]
	s_addc_u32 s67, s35, 0
	s_add_i32 s68, s62, s46
	global_load_lds_dwordx4 v[200:201], off
	v_lshl_add_u64 v[200:201], s[66:67], 0, v[172:173]
	s_mov_b32 m0, s68
	v_lshl_add_u64 v[236:237], s[36:37], 0, v[174:175]
	global_load_lds_dwordx4 v[200:201], off
	v_lshl_add_u64 v[200:201], s[66:67], 0, v[176:177]
	s_add_i32 m0, s68, 0x2000
	s_nop 0
	global_load_lds_dwordx4 v[200:201], off
	v_lshl_add_u64 v[200:201], s[36:37], 0, v[170:171]
	s_mov_b32 m0, s47
	s_nop 0
	global_load_lds_dwordx4 v[200:201], off
	s_mov_b32 m0, s48
	s_nop 0
	global_load_lds_dwordx4 v[236:237], off
	s_waitcnt vmcnt(8)
	s_waitcnt lgkmcnt(0)
	s_barrier
	s_waitcnt lgkmcnt(0)
	v_mfma_f32_16x16x32_bf16 v[92:95], v[128:131], v[160:163], v[92:95]
	v_mfma_f32_16x16x32_bf16 v[88:91], v[136:139], v[160:163], v[88:91]
	v_mfma_f32_16x16x32_bf16 v[84:87], v[128:131], v[196:199], v[84:87]
	v_mfma_f32_16x16x32_bf16 v[80:83], v[136:139], v[196:199], v[80:83]
	v_mfma_f32_16x16x32_bf16 v[76:79], v[128:131], v[220:223], v[76:79]
	v_mfma_f32_16x16x32_bf16 v[72:75], v[136:139], v[220:223], v[72:75]
	v_mfma_f32_16x16x32_bf16 v[68:71], v[128:131], v[228:231], v[68:71]
	v_mfma_f32_16x16x32_bf16 v[64:67], v[136:139], v[228:231], v[64:67]
	v_mfma_f32_16x16x32_bf16 v[92:95], v[132:135], v[164:167], v[92:95]
	v_mfma_f32_16x16x32_bf16 v[88:91], v[140:143], v[164:167], v[88:91]
	v_mfma_f32_16x16x32_bf16 v[84:87], v[132:135], v[216:219], v[84:87]
	v_mfma_f32_16x16x32_bf16 v[80:83], v[140:143], v[216:219], v[80:83]
	v_mfma_f32_16x16x32_bf16 v[76:79], v[132:135], v[224:227], v[76:79]
	v_mfma_f32_16x16x32_bf16 v[72:75], v[140:143], v[224:227], v[72:75]
	v_mfma_f32_16x16x32_bf16 v[68:71], v[132:135], v[232:235], v[68:71]
	v_mfma_f32_16x16x32_bf16 v[64:67], v[140:143], v[232:235], v[64:67]
	v_mfma_f32_16x16x32_bf16 v[28:31], v[144:147], v[160:163], v[28:31]
	v_mfma_f32_16x16x32_bf16 v[24:27], v[152:155], v[160:163], v[24:27]
	v_mfma_f32_16x16x32_bf16 v[20:23], v[144:147], v[196:199], v[20:23]
	v_mfma_f32_16x16x32_bf16 v[16:19], v[152:155], v[196:199], v[16:19]
	v_mfma_f32_16x16x32_bf16 v[12:15], v[144:147], v[220:223], v[12:15]
	v_mfma_f32_16x16x32_bf16 v[8:11], v[152:155], v[220:223], v[8:11]
	v_mfma_f32_16x16x32_bf16 v[4:7], v[144:147], v[228:231], v[4:7]
	v_mfma_f32_16x16x32_bf16 v[0:3], v[152:155], v[228:231], v[0:3]
	v_mfma_f32_16x16x32_bf16 v[28:31], v[148:151], v[164:167], v[28:31]
	v_mfma_f32_16x16x32_bf16 v[24:27], v[156:159], v[164:167], v[24:27]
	v_mfma_f32_16x16x32_bf16 v[20:23], v[148:151], v[216:219], v[20:23]
	v_mfma_f32_16x16x32_bf16 v[16:19], v[156:159], v[216:219], v[16:19]
	v_mfma_f32_16x16x32_bf16 v[12:15], v[148:151], v[224:227], v[12:15]
	v_mfma_f32_16x16x32_bf16 v[8:11], v[156:159], v[224:227], v[8:11]
	v_mfma_f32_16x16x32_bf16 v[4:7], v[148:151], v[232:235], v[4:7]
	v_mfma_f32_16x16x32_bf16 v[0:3], v[156:159], v[232:235], v[0:3]
	s_barrier
	s_add_i32 s66, 0, 0x18000
	s_add_i32 s67, 0, 0x1c000
	v_add_u32_e32 v140, s66, v210
	v_add_u32_e32 v156, s67, v210
	ds_read_b128 v[128:131], v140
	ds_read_b128 v[132:135], v140 offset:1024
	ds_read_b128 v[136:139], v140 offset:2048
	ds_read_b128 v[140:143], v140 offset:3072
	ds_read_b128 v[144:147], v156
	ds_read_b128 v[148:151], v156 offset:1024
	ds_read_b128 v[152:155], v156 offset:2048
	ds_read_b128 v[156:159], v156 offset:3072
	s_add_u32 s36, s36, 0x40000
	s_addc_u32 s37, s37, 0
	s_mov_b32 m0, s49
	v_lshl_add_u64 v[238:239], s[36:37], 0, v[170:171]
	ds_read_b128 v[160:163], v214 offset:32768
	ds_read_b128 v[164:167], v214 offset:33792
	ds_read_b128 v[196:199], v214 offset:34816
	ds_read_b128 v[216:219], v214 offset:35840
	ds_read_b128 v[220:223], v214 offset:36864
	ds_read_b128 v[224:227], v214 offset:37888
	ds_read_b128 v[228:231], v214 offset:38912
	ds_read_b128 v[232:235], v214 offset:39936
	global_load_lds_dwordx4 v[238:239], off
	v_lshl_add_u64 v[238:239], s[36:37], 0, v[174:175]
	s_mov_b32 m0, s50
	s_nop 0
	global_load_lds_dwordx4 v[238:239], off
	s_waitcnt vmcnt(8)
	s_waitcnt lgkmcnt(0)
	s_barrier
	s_waitcnt lgkmcnt(0)
	v_mfma_f32_16x16x32_bf16 v[124:127], v[128:131], v[160:163], v[124:127]
	v_mfma_f32_16x16x32_bf16 v[120:123], v[136:139], v[160:163], v[120:123]
	v_mfma_f32_16x16x32_bf16 v[116:119], v[128:131], v[196:199], v[116:119]
	v_mfma_f32_16x16x32_bf16 v[112:115], v[136:139], v[196:199], v[112:115]
	v_mfma_f32_16x16x32_bf16 v[108:111], v[128:131], v[220:223], v[108:111]
	v_mfma_f32_16x16x32_bf16 v[104:107], v[136:139], v[220:223], v[104:107]
	v_mfma_f32_16x16x32_bf16 v[100:103], v[128:131], v[228:231], v[100:103]
	v_mfma_f32_16x16x32_bf16 v[96:99], v[136:139], v[228:231], v[96:99]
	v_mfma_f32_16x16x32_bf16 v[124:127], v[132:135], v[164:167], v[124:127]
	v_mfma_f32_16x16x32_bf16 v[120:123], v[140:143], v[164:167], v[120:123]
	v_mfma_f32_16x16x32_bf16 v[116:119], v[132:135], v[216:219], v[116:119]
	v_mfma_f32_16x16x32_bf16 v[112:115], v[140:143], v[216:219], v[112:115]
	v_mfma_f32_16x16x32_bf16 v[108:111], v[132:135], v[224:227], v[108:111]
	v_mfma_f32_16x16x32_bf16 v[104:107], v[140:143], v[224:227], v[104:107]
	v_mfma_f32_16x16x32_bf16 v[100:103], v[132:135], v[232:235], v[100:103]
	v_mfma_f32_16x16x32_bf16 v[96:99], v[140:143], v[232:235], v[96:99]
	v_mfma_f32_16x16x32_bf16 v[60:63], v[144:147], v[160:163], v[60:63]
	v_mfma_f32_16x16x32_bf16 v[56:59], v[152:155], v[160:163], v[56:59]
	v_mfma_f32_16x16x32_bf16 v[52:55], v[144:147], v[196:199], v[52:55]
	v_mfma_f32_16x16x32_bf16 v[48:51], v[152:155], v[196:199], v[48:51]
	v_mfma_f32_16x16x32_bf16 v[44:47], v[144:147], v[220:223], v[44:47]
	v_mfma_f32_16x16x32_bf16 v[40:43], v[152:155], v[220:223], v[40:43]
	v_mfma_f32_16x16x32_bf16 v[36:39], v[144:147], v[228:231], v[36:39]
	v_mfma_f32_16x16x32_bf16 v[32:35], v[152:155], v[228:231], v[32:35]
	v_mfma_f32_16x16x32_bf16 v[60:63], v[148:151], v[164:167], v[60:63]
	v_mfma_f32_16x16x32_bf16 v[56:59], v[156:159], v[164:167], v[56:59]
	v_mfma_f32_16x16x32_bf16 v[52:55], v[148:151], v[216:219], v[52:55]
	v_mfma_f32_16x16x32_bf16 v[48:51], v[156:159], v[216:219], v[48:51]
	v_mfma_f32_16x16x32_bf16 v[44:47], v[148:151], v[224:227], v[44:47]
	v_mfma_f32_16x16x32_bf16 v[40:43], v[156:159], v[224:227], v[40:43]
	v_mfma_f32_16x16x32_bf16 v[36:39], v[148:151], v[232:235], v[36:39]
	v_mfma_f32_16x16x32_bf16 v[32:35], v[156:159], v[232:235], v[32:35]
	s_barrier
	s_add_u32 s36, s34, 0x8000
	s_addc_u32 s37, s35, 0
	s_add_i32 s66, s66, s46
	v_lshl_add_u64 v[238:239], s[36:37], 0, v[172:173]
	s_mov_b32 m0, s66
	ds_read_b128 v[160:163], v214 offset:49152
	ds_read_b128 v[164:167], v214 offset:50176
	ds_read_b128 v[196:199], v214 offset:51200
	ds_read_b128 v[216:219], v214 offset:52224
	ds_read_b128 v[220:223], v214 offset:53248
	ds_read_b128 v[224:227], v214 offset:54272
	ds_read_b128 v[228:231], v214 offset:55296
	ds_read_b128 v[232:235], v214 offset:56320
	global_load_lds_dwordx4 v[238:239], off
	s_add_i32 m0, s66, 0x2000
	s_add_u32 s34, s34, 0xc000
	v_lshl_add_u64 v[238:239], s[36:37], 0, v[176:177]
	s_addc_u32 s35, s35, 0
	s_add_i32 s36, s67, s46
	global_load_lds_dwordx4 v[238:239], off
	v_lshl_add_u64 v[238:239], s[34:35], 0, v[172:173]
	s_mov_b32 m0, s36
	v_lshl_add_u64 v[200:201], v[200:201], 0, s[16:17]
	global_load_lds_dwordx4 v[238:239], off
	v_lshl_add_u64 v[238:239], s[34:35], 0, v[176:177]
	s_add_i32 m0, s36, 0x2000
	s_nop 0
	global_load_lds_dwordx4 v[238:239], off
	s_mov_b32 m0, s55
	s_nop 0
	global_load_lds_dwordx4 v[200:201], off
	v_lshl_add_u64 v[200:201], v[236:237], 0, s[16:17]
	s_mov_b32 m0, s56
	s_nop 0
	global_load_lds_dwordx4 v[200:201], off
	s_waitcnt vmcnt(8)
	s_waitcnt lgkmcnt(0)
	s_barrier
	s_waitcnt lgkmcnt(0)
	v_mfma_f32_16x16x32_bf16 v[92:95], v[128:131], v[160:163], v[92:95]
	v_mfma_f32_16x16x32_bf16 v[88:91], v[136:139], v[160:163], v[88:91]
	v_mfma_f32_16x16x32_bf16 v[84:87], v[128:131], v[196:199], v[84:87]
	v_mfma_f32_16x16x32_bf16 v[80:83], v[136:139], v[196:199], v[80:83]
	v_mfma_f32_16x16x32_bf16 v[76:79], v[128:131], v[220:223], v[76:79]
	v_mfma_f32_16x16x32_bf16 v[72:75], v[136:139], v[220:223], v[72:75]
	v_mfma_f32_16x16x32_bf16 v[68:71], v[128:131], v[228:231], v[68:71]
	v_mfma_f32_16x16x32_bf16 v[64:67], v[136:139], v[228:231], v[64:67]
	v_mfma_f32_16x16x32_bf16 v[92:95], v[132:135], v[164:167], v[92:95]
	v_mfma_f32_16x16x32_bf16 v[88:91], v[140:143], v[164:167], v[88:91]
	v_mfma_f32_16x16x32_bf16 v[84:87], v[132:135], v[216:219], v[84:87]
	v_mfma_f32_16x16x32_bf16 v[80:83], v[140:143], v[216:219], v[80:83]
	v_mfma_f32_16x16x32_bf16 v[76:79], v[132:135], v[224:227], v[76:79]
	v_mfma_f32_16x16x32_bf16 v[72:75], v[140:143], v[224:227], v[72:75]
	v_mfma_f32_16x16x32_bf16 v[68:71], v[132:135], v[232:235], v[68:71]
	v_mfma_f32_16x16x32_bf16 v[64:67], v[140:143], v[232:235], v[64:67]
	v_mfma_f32_16x16x32_bf16 v[28:31], v[144:147], v[160:163], v[28:31]
	v_mfma_f32_16x16x32_bf16 v[24:27], v[152:155], v[160:163], v[24:27]
	v_mfma_f32_16x16x32_bf16 v[20:23], v[144:147], v[196:199], v[20:23]
	v_mfma_f32_16x16x32_bf16 v[16:19], v[152:155], v[196:199], v[16:19]
	v_mfma_f32_16x16x32_bf16 v[12:15], v[144:147], v[220:223], v[12:15]
	v_mfma_f32_16x16x32_bf16 v[8:11], v[152:155], v[220:223], v[8:11]
	v_mfma_f32_16x16x32_bf16 v[4:7], v[144:147], v[228:231], v[4:7]
	v_mfma_f32_16x16x32_bf16 v[0:3], v[152:155], v[228:231], v[0:3]
	v_mfma_f32_16x16x32_bf16 v[28:31], v[148:151], v[164:167], v[28:31]
	v_mfma_f32_16x16x32_bf16 v[24:27], v[156:159], v[164:167], v[24:27]
	v_mfma_f32_16x16x32_bf16 v[20:23], v[148:151], v[216:219], v[20:23]
	v_mfma_f32_16x16x32_bf16 v[16:19], v[156:159], v[216:219], v[16:19]
	v_mfma_f32_16x16x32_bf16 v[12:15], v[148:151], v[224:227], v[12:15]
	v_mfma_f32_16x16x32_bf16 v[8:11], v[156:159], v[224:227], v[8:11]
	v_mfma_f32_16x16x32_bf16 v[4:7], v[148:151], v[232:235], v[4:7]
	v_mfma_f32_16x16x32_bf16 v[0:3], v[156:159], v[232:235], v[0:3]
	s_barrier
	s_add_i32 s39, s39, 2
	s_add_u32 s25, s25, 0x10000
	s_addc_u32 s38, s38, 0
	s_add_u32 s30, s30, 0x100
	s_addc_u32 s31, s31, 0
	s_cmp_gt_u32 s39, 13
	s_cbranch_scc0 .LBB0_492
	s_and_b64 vcc, exec, s[18:19]
	s_cbranch_vccz .LBB0_503
	s_barrier
	v_lshl_add_u32 v216, s0, 8, v169
	s_cmp_gt_i32 s6, 4
	s_mov_b64 s[0:1], -1
	s_cbranch_scc1 .LBB0_504

.LBB0_1071:
	ds_read_b128 v[128:131], v170
	ds_read_b128 v[148:151], v170 offset:1024
	ds_read_b128 v[152:155], v170 offset:2048
	ds_read_b128 v[174:177], v170 offset:3072
	ds_read_b128 v[178:181], v171
	ds_read_b128 v[182:185], v171 offset:1024
	ds_read_b128 v[186:189], v171 offset:2048
	ds_read_b128 v[190:193], v171 offset:3072
	s_add_u32 s30, s28, 0xfffe0080
	s_addc_u32 s31, s29, -1
	s_cmp_eq_u32 s56, 4
	s_cselect_b32 s35, s17, s31
	s_cselect_b32 s34, s52, s30
	s_cselect_b32 s31, s19, s55
	s_cselect_b32 s30, s53, s54
	v_lshl_add_u64 v[234:235], s[28:29], 0, v[142:143]
	s_add_i32 m0, s25, 0xc000
	ds_read_b128 v[194:197], v172
	ds_read_b128 v[198:201], v172 offset:1024
	ds_read_b128 v[210:213], v172 offset:2048
	ds_read_b128 v[214:217], v172 offset:3072
	ds_read_b128 v[218:221], v172 offset:4096
	ds_read_b128 v[222:225], v172 offset:5120
	ds_read_b128 v[226:229], v172 offset:6144
	ds_read_b128 v[230:233], v172 offset:7168
	global_load_lds_dwordx4 v[234:235], off
	v_lshl_add_u64 v[234:235], s[28:29], 0, v[140:141]
	s_add_i32 m0, s25, 0xe000
	s_nop 0
	global_load_lds_dwordx4 v[234:235], off
	s_waitcnt vmcnt(8)
	s_waitcnt lgkmcnt(0)
	s_barrier
	s_waitcnt lgkmcnt(0)
	v_mfma_f32_16x16x32_bf16 v[124:127], v[128:131], v[194:197], v[124:127]
	v_mfma_f32_16x16x32_bf16 v[120:123], v[152:155], v[194:197], v[120:123]
	v_mfma_f32_16x16x32_bf16 v[116:119], v[128:131], v[210:213], v[116:119]
	v_mfma_f32_16x16x32_bf16 v[112:115], v[152:155], v[210:213], v[112:115]
	v_mfma_f32_16x16x32_bf16 v[92:95], v[128:131], v[218:221], v[92:95]
	v_mfma_f32_16x16x32_bf16 v[88:91], v[152:155], v[218:221], v[88:91]
	v_mfma_f32_16x16x32_bf16 v[84:87], v[128:131], v[226:229], v[84:87]
	v_mfma_f32_16x16x32_bf16 v[72:75], v[152:155], v[226:229], v[72:75]
	v_mfma_f32_16x16x32_bf16 v[124:127], v[148:151], v[198:201], v[124:127]
	v_mfma_f32_16x16x32_bf16 v[120:123], v[174:177], v[198:201], v[120:123]
	v_mfma_f32_16x16x32_bf16 v[116:119], v[148:151], v[214:217], v[116:119]
	v_mfma_f32_16x16x32_bf16 v[112:115], v[174:177], v[214:217], v[112:115]
	v_mfma_f32_16x16x32_bf16 v[92:95], v[148:151], v[222:225], v[92:95]
	v_mfma_f32_16x16x32_bf16 v[88:91], v[174:177], v[222:225], v[88:91]
	v_mfma_f32_16x16x32_bf16 v[84:87], v[148:151], v[230:233], v[84:87]
	v_mfma_f32_16x16x32_bf16 v[72:75], v[174:177], v[230:233], v[72:75]
	v_mfma_f32_16x16x32_bf16 v[108:111], v[178:181], v[194:197], v[108:111]
	v_mfma_f32_16x16x32_bf16 v[104:107], v[186:189], v[194:197], v[104:107]
	v_mfma_f32_16x16x32_bf16 v[100:103], v[178:181], v[210:213], v[100:103]
	v_mfma_f32_16x16x32_bf16 v[96:99], v[186:189], v[210:213], v[96:99]
	v_mfma_f32_16x16x32_bf16 v[80:83], v[178:181], v[218:221], v[80:83]
	v_mfma_f32_16x16x32_bf16 v[76:79], v[186:189], v[218:221], v[76:79]
	v_mfma_f32_16x16x32_bf16 v[68:71], v[178:181], v[226:229], v[68:71]
	v_mfma_f32_16x16x32_bf16 v[64:67], v[186:189], v[226:229], v[64:67]
	v_mfma_f32_16x16x32_bf16 v[108:111], v[182:185], v[198:201], v[108:111]
	v_mfma_f32_16x16x32_bf16 v[104:107], v[190:193], v[198:201], v[104:107]
	v_mfma_f32_16x16x32_bf16 v[100:103], v[182:185], v[214:217], v[100:103]
	v_mfma_f32_16x16x32_bf16 v[96:99], v[190:193], v[214:217], v[96:99]
	v_mfma_f32_16x16x32_bf16 v[80:83], v[182:185], v[222:225], v[80:83]
	v_mfma_f32_16x16x32_bf16 v[76:79], v[190:193], v[222:225], v[76:79]
	v_mfma_f32_16x16x32_bf16 v[68:71], v[182:185], v[230:233], v[68:71]
	v_mfma_f32_16x16x32_bf16 v[64:67], v[190:193], v[230:233], v[64:67]
	s_barrier
	s_add_i32 s57, s49, s42
	v_lshl_add_u64 v[234:235], s[30:31], 0, v[134:135]
	s_mov_b32 m0, s57
	ds_read_b128 v[194:197], v172 offset:16384
	ds_read_b128 v[198:201], v172 offset:17408
	ds_read_b128 v[210:213], v172 offset:18432
	ds_read_b128 v[214:217], v172 offset:19456
	ds_read_b128 v[218:221], v172 offset:20480
	ds_read_b128 v[222:225], v172 offset:21504
	ds_read_b128 v[226:229], v172 offset:22528
	ds_read_b128 v[230:233], v172 offset:23552
	global_load_lds_dwordx4 v[234:235], off
	s_add_i32 m0, s57, 0x2000
	s_add_u32 s58, s30, 0x4000
	v_lshl_add_u64 v[234:235], s[30:31], 0, v[138:139]
	s_addc_u32 s59, s31, 0
	s_add_i32 s57, s50, s42
	global_load_lds_dwordx4 v[234:235], off
	v_lshl_add_u64 v[234:235], s[58:59], 0, v[134:135]
	s_mov_b32 m0, s57
	v_lshl_add_u64 v[236:237], s[34:35], 0, v[136:137]
	global_load_lds_dwordx4 v[234:235], off
	v_lshl_add_u64 v[234:235], s[58:59], 0, v[138:139]
	s_add_i32 m0, s57, 0x2000
	s_nop 0
	global_load_lds_dwordx4 v[234:235], off
	v_lshl_add_u64 v[234:235], s[34:35], 0, v[132:133]
	s_mov_b32 m0, s25
	s_nop 0
	global_load_lds_dwordx4 v[234:235], off
	s_mov_b32 m0, s27
	s_nop 0
	global_load_lds_dwordx4 v[236:237], off
	s_waitcnt vmcnt(8)
	s_waitcnt lgkmcnt(0)
	s_barrier
	s_waitcnt lgkmcnt(0)
	v_mfma_f32_16x16x32_bf16 v[60:63], v[128:131], v[194:197], v[60:63]
	v_mfma_f32_16x16x32_bf16 v[56:59], v[152:155], v[194:197], v[56:59]
	v_mfma_f32_16x16x32_bf16 v[48:51], v[128:131], v[210:213], v[48:51]
	v_mfma_f32_16x16x32_bf16 v[40:43], v[152:155], v[210:213], v[40:43]
	v_mfma_f32_16x16x32_bf16 v[32:35], v[128:131], v[218:221], v[32:35]
	v_mfma_f32_16x16x32_bf16 v[24:27], v[152:155], v[218:221], v[24:27]
	v_mfma_f32_16x16x32_bf16 v[16:19], v[128:131], v[226:229], v[16:19]
	v_mfma_f32_16x16x32_bf16 v[8:11], v[152:155], v[226:229], v[8:11]
	v_mfma_f32_16x16x32_bf16 v[60:63], v[148:151], v[198:201], v[60:63]
	v_mfma_f32_16x16x32_bf16 v[56:59], v[174:177], v[198:201], v[56:59]
	v_mfma_f32_16x16x32_bf16 v[48:51], v[148:151], v[214:217], v[48:51]
	v_mfma_f32_16x16x32_bf16 v[40:43], v[174:177], v[214:217], v[40:43]
	v_mfma_f32_16x16x32_bf16 v[32:35], v[148:151], v[222:225], v[32:35]
	v_mfma_f32_16x16x32_bf16 v[24:27], v[174:177], v[222:225], v[24:27]
	v_mfma_f32_16x16x32_bf16 v[16:19], v[148:151], v[230:233], v[16:19]
	v_mfma_f32_16x16x32_bf16 v[8:11], v[174:177], v[230:233], v[8:11]
	v_mfma_f32_16x16x32_bf16 v[52:55], v[178:181], v[194:197], v[52:55]
	v_mfma_f32_16x16x32_bf16 v[44:47], v[186:189], v[194:197], v[44:47]
	v_mfma_f32_16x16x32_bf16 v[36:39], v[178:181], v[210:213], v[36:39]
	v_mfma_f32_16x16x32_bf16 v[28:31], v[186:189], v[210:213], v[28:31]
	v_mfma_f32_16x16x32_bf16 v[20:23], v[178:181], v[218:221], v[20:23]
	v_mfma_f32_16x16x32_bf16 v[12:15], v[186:189], v[218:221], v[12:15]
	v_mfma_f32_16x16x32_bf16 v[4:7], v[178:181], v[226:229], v[4:7]
	v_mfma_f32_16x16x32_bf16 v[0:3], v[186:189], v[226:229], v[0:3]
	v_mfma_f32_16x16x32_bf16 v[52:55], v[182:185], v[198:201], v[52:55]
	v_mfma_f32_16x16x32_bf16 v[44:47], v[190:193], v[198:201], v[44:47]
	v_mfma_f32_16x16x32_bf16 v[36:39], v[182:185], v[214:217], v[36:39]
	v_mfma_f32_16x16x32_bf16 v[28:31], v[190:193], v[214:217], v[28:31]
	v_mfma_f32_16x16x32_bf16 v[20:23], v[182:185], v[222:225], v[20:23]
	v_mfma_f32_16x16x32_bf16 v[12:15], v[190:193], v[222:225], v[12:15]
	v_mfma_f32_16x16x32_bf16 v[4:7], v[182:185], v[230:233], v[4:7]
	v_mfma_f32_16x16x32_bf16 v[0:3], v[190:193], v[230:233], v[0:3]
	s_barrier
	s_add_i32 s57, 0, 0x18000
	v_add_u32_e32 v173, s57, v168
	s_add_i32 s58, 0, 0x1c000
	ds_read_b128 v[128:131], v173
	ds_read_b128 v[148:151], v173 offset:1024
	ds_read_b128 v[152:155], v173 offset:2048
	ds_read_b128 v[174:177], v173 offset:3072
	v_add_u32_e32 v173, s58, v168
	ds_read_b128 v[178:181], v173
	ds_read_b128 v[182:185], v173 offset:1024
	ds_read_b128 v[186:189], v173 offset:2048
	ds_read_b128 v[190:193], v173 offset:3072
	s_add_u32 s34, s34, 0x20000
	s_addc_u32 s35, s35, 0
	s_mov_b32 m0, s43
	v_lshl_add_u64 v[238:239], s[34:35], 0, v[132:133]
	ds_read_b128 v[194:197], v172 offset:32768
	ds_read_b128 v[198:201], v172 offset:33792
	ds_read_b128 v[210:213], v172 offset:34816
	ds_read_b128 v[214:217], v172 offset:35840
	ds_read_b128 v[218:221], v172 offset:36864
	ds_read_b128 v[222:225], v172 offset:37888
	ds_read_b128 v[226:229], v172 offset:38912
	ds_read_b128 v[230:233], v172 offset:39936
	global_load_lds_dwordx4 v[238:239], off
	v_lshl_add_u64 v[238:239], s[34:35], 0, v[136:137]
	s_mov_b32 m0, s44
	s_nop 0
	global_load_lds_dwordx4 v[238:239], off
	s_waitcnt vmcnt(8)
	s_waitcnt lgkmcnt(0)
	s_barrier
	s_waitcnt lgkmcnt(0)
	v_mfma_f32_16x16x32_bf16 v[124:127], v[128:131], v[194:197], v[124:127]
	v_mfma_f32_16x16x32_bf16 v[120:123], v[152:155], v[194:197], v[120:123]
	v_mfma_f32_16x16x32_bf16 v[116:119], v[128:131], v[210:213], v[116:119]
	v_mfma_f32_16x16x32_bf16 v[112:115], v[152:155], v[210:213], v[112:115]
	v_mfma_f32_16x16x32_bf16 v[92:95], v[128:131], v[218:221], v[92:95]
	v_mfma_f32_16x16x32_bf16 v[88:91], v[152:155], v[218:221], v[88:91]
	v_mfma_f32_16x16x32_bf16 v[84:87], v[128:131], v[226:229], v[84:87]
	v_mfma_f32_16x16x32_bf16 v[72:75], v[152:155], v[226:229], v[72:75]
	v_mfma_f32_16x16x32_bf16 v[124:127], v[148:151], v[198:201], v[124:127]
	v_mfma_f32_16x16x32_bf16 v[120:123], v[174:177], v[198:201], v[120:123]
	v_mfma_f32_16x16x32_bf16 v[116:119], v[148:151], v[214:217], v[116:119]
	v_mfma_f32_16x16x32_bf16 v[112:115], v[174:177], v[214:217], v[112:115]
	v_mfma_f32_16x16x32_bf16 v[92:95], v[148:151], v[222:225], v[92:95]
	v_mfma_f32_16x16x32_bf16 v[88:91], v[174:177], v[222:225], v[88:91]
	v_mfma_f32_16x16x32_bf16 v[84:87], v[148:151], v[230:233], v[84:87]
	v_mfma_f32_16x16x32_bf16 v[72:75], v[174:177], v[230:233], v[72:75]
	v_mfma_f32_16x16x32_bf16 v[108:111], v[178:181], v[194:197], v[108:111]
	v_mfma_f32_16x16x32_bf16 v[104:107], v[186:189], v[194:197], v[104:107]
	v_mfma_f32_16x16x32_bf16 v[100:103], v[178:181], v[210:213], v[100:103]
	v_mfma_f32_16x16x32_bf16 v[96:99], v[186:189], v[210:213], v[96:99]
	v_mfma_f32_16x16x32_bf16 v[80:83], v[178:181], v[218:221], v[80:83]
	v_mfma_f32_16x16x32_bf16 v[76:79], v[186:189], v[218:221], v[76:79]
	v_mfma_f32_16x16x32_bf16 v[68:71], v[178:181], v[226:229], v[68:71]
	v_mfma_f32_16x16x32_bf16 v[64:67], v[186:189], v[226:229], v[64:67]
	v_mfma_f32_16x16x32_bf16 v[108:111], v[182:185], v[198:201], v[108:111]
	v_mfma_f32_16x16x32_bf16 v[104:107], v[190:193], v[198:201], v[104:107]
	v_mfma_f32_16x16x32_bf16 v[100:103], v[182:185], v[214:217], v[100:103]
	v_mfma_f32_16x16x32_bf16 v[96:99], v[190:193], v[214:217], v[96:99]
	v_mfma_f32_16x16x32_bf16 v[80:83], v[182:185], v[222:225], v[80:83]
	v_mfma_f32_16x16x32_bf16 v[76:79], v[190:193], v[222:225], v[76:79]
	v_mfma_f32_16x16x32_bf16 v[68:71], v[182:185], v[230:233], v[68:71]
	v_mfma_f32_16x16x32_bf16 v[64:67], v[190:193], v[230:233], v[64:67]
	s_barrier
	s_add_u32 s34, s30, 0x8000
	s_addc_u32 s35, s31, 0
	s_add_i32 s57, s57, s42
	v_lshl_add_u64 v[238:239], s[34:35], 0, v[134:135]
	s_mov_b32 m0, s57
	ds_read_b128 v[194:197], v172 offset:49152
	ds_read_b128 v[198:201], v172 offset:50176
	ds_read_b128 v[210:213], v172 offset:51200
	ds_read_b128 v[214:217], v172 offset:52224
	ds_read_b128 v[218:221], v172 offset:53248
	ds_read_b128 v[222:225], v172 offset:54272
	ds_read_b128 v[226:229], v172 offset:55296
	ds_read_b128 v[230:233], v172 offset:56320
	global_load_lds_dwordx4 v[238:239], off
	s_add_i32 m0, s57, 0x2000
	s_add_u32 s30, s30, 0xc000
	v_lshl_add_u64 v[238:239], s[34:35], 0, v[138:139]
	s_addc_u32 s31, s31, 0
	s_add_i32 s34, s58, s42
	global_load_lds_dwordx4 v[238:239], off
	v_lshl_add_u64 v[238:239], s[30:31], 0, v[134:135]
	s_mov_b32 m0, s34
	v_lshl_add_u64 v[234:235], v[234:235], 0, s[12:13]
	global_load_lds_dwordx4 v[238:239], off
	v_lshl_add_u64 v[238:239], s[30:31], 0, v[138:139]
	s_add_i32 m0, s34, 0x2000
	s_nop 0
	global_load_lds_dwordx4 v[238:239], off
	s_mov_b32 m0, s46
	s_nop 0
	global_load_lds_dwordx4 v[234:235], off
	v_lshl_add_u64 v[234:235], v[236:237], 0, s[12:13]
	s_mov_b32 m0, s47
	s_nop 0
	global_load_lds_dwordx4 v[234:235], off
	s_waitcnt vmcnt(8)
	s_waitcnt lgkmcnt(0)
	s_barrier
	s_waitcnt lgkmcnt(0)
	v_mfma_f32_16x16x32_bf16 v[60:63], v[128:131], v[194:197], v[60:63]
	v_mfma_f32_16x16x32_bf16 v[56:59], v[152:155], v[194:197], v[56:59]
	v_mfma_f32_16x16x32_bf16 v[48:51], v[128:131], v[210:213], v[48:51]
	v_mfma_f32_16x16x32_bf16 v[40:43], v[152:155], v[210:213], v[40:43]
	v_mfma_f32_16x16x32_bf16 v[32:35], v[128:131], v[218:221], v[32:35]
	v_mfma_f32_16x16x32_bf16 v[24:27], v[152:155], v[218:221], v[24:27]
	v_mfma_f32_16x16x32_bf16 v[16:19], v[128:131], v[226:229], v[16:19]
	v_mfma_f32_16x16x32_bf16 v[8:11], v[152:155], v[226:229], v[8:11]
	v_mfma_f32_16x16x32_bf16 v[60:63], v[148:151], v[198:201], v[60:63]
	v_mfma_f32_16x16x32_bf16 v[56:59], v[174:177], v[198:201], v[56:59]
	v_mfma_f32_16x16x32_bf16 v[48:51], v[148:151], v[214:217], v[48:51]
	v_mfma_f32_16x16x32_bf16 v[40:43], v[174:177], v[214:217], v[40:43]
	v_mfma_f32_16x16x32_bf16 v[32:35], v[148:151], v[222:225], v[32:35]
	v_mfma_f32_16x16x32_bf16 v[24:27], v[174:177], v[222:225], v[24:27]
	v_mfma_f32_16x16x32_bf16 v[16:19], v[148:151], v[230:233], v[16:19]
	v_mfma_f32_16x16x32_bf16 v[8:11], v[174:177], v[230:233], v[8:11]
	v_mfma_f32_16x16x32_bf16 v[52:55], v[178:181], v[194:197], v[52:55]
	v_mfma_f32_16x16x32_bf16 v[44:47], v[186:189], v[194:197], v[44:47]
	v_mfma_f32_16x16x32_bf16 v[36:39], v[178:181], v[210:213], v[36:39]
	v_mfma_f32_16x16x32_bf16 v[28:31], v[186:189], v[210:213], v[28:31]
	v_mfma_f32_16x16x32_bf16 v[20:23], v[178:181], v[218:221], v[20:23]
	v_mfma_f32_16x16x32_bf16 v[12:15], v[186:189], v[218:221], v[12:15]
	v_mfma_f32_16x16x32_bf16 v[4:7], v[178:181], v[226:229], v[4:7]
	v_mfma_f32_16x16x32_bf16 v[0:3], v[186:189], v[226:229], v[0:3]
	v_mfma_f32_16x16x32_bf16 v[52:55], v[182:185], v[198:201], v[52:55]
	v_mfma_f32_16x16x32_bf16 v[44:47], v[190:193], v[198:201], v[44:47]
	v_mfma_f32_16x16x32_bf16 v[36:39], v[182:185], v[214:217], v[36:39]
	v_mfma_f32_16x16x32_bf16 v[28:31], v[190:193], v[214:217], v[28:31]
	v_mfma_f32_16x16x32_bf16 v[20:23], v[182:185], v[222:225], v[20:23]
	v_mfma_f32_16x16x32_bf16 v[12:15], v[190:193], v[222:225], v[12:15]
	v_mfma_f32_16x16x32_bf16 v[4:7], v[182:185], v[230:233], v[4:7]
	v_mfma_f32_16x16x32_bf16 v[0:3], v[190:193], v[230:233], v[0:3]
	s_barrier
	s_add_i32 s56, s56, 2
	s_add_u32 s54, s54, 0x10000
	s_addc_u32 s55, s55, 0
	s_add_u32 s28, s28, 0x100
	s_addc_u32 s29, s29, 0
	s_cmp_gt_u32 s56, 5
	s_cbranch_scc0 .LBB0_1071
	s_and_b64 vcc, exec, s[14:15]
	s_cbranch_vccz .LBB0_1074
	s_barrier

.LBB0_1095:
	ds_read_b128 v[144:147], v155
	ds_read_b128 v[148:151], v155 offset:1024
	ds_read_b128 v[158:161], v155 offset:2048
	ds_read_b128 v[162:165], v155 offset:3072
	ds_read_b128 v[166:169], v156
	ds_read_b128 v[170:173], v156 offset:1024
	ds_read_b128 v[174:177], v156 offset:2048
	ds_read_b128 v[178:181], v156 offset:3072
	s_add_u32 s28, s26, 0xfffe0080
	s_addc_u32 s29, s27, -1
	s_cmp_eq_u32 s54, 4
	s_cselect_b32 s31, s15, s29
	s_cselect_b32 s30, s50, s28
	s_cselect_b32 s29, s17, s53
	s_cselect_b32 s28, s51, s52
	v_lshl_add_u64 v[222:223], s[26:27], 0, v[130:131]
	s_add_i32 m0, s23, 0xc000
	ds_read_b128 v[182:185], v157
	ds_read_b128 v[186:189], v157 offset:1024
	ds_read_b128 v[190:193], v157 offset:2048
	ds_read_b128 v[194:197], v157 offset:3072
	ds_read_b128 v[198:201], v157 offset:4096
	ds_read_b128 v[210:213], v157 offset:5120
	ds_read_b128 v[214:217], v157 offset:6144
	ds_read_b128 v[218:221], v157 offset:7168
	global_load_lds_dwordx4 v[222:223], off
	v_lshl_add_u64 v[222:223], s[26:27], 0, v[128:129]
	s_add_i32 m0, s23, 0xe000
	s_nop 0
	global_load_lds_dwordx4 v[222:223], off
	s_waitcnt vmcnt(8)
	s_waitcnt lgkmcnt(0)
	s_barrier
	s_waitcnt lgkmcnt(0)
	v_mfma_f32_16x16x32_bf16 v[124:127], v[144:147], v[182:185], v[124:127]
	v_mfma_f32_16x16x32_bf16 v[120:123], v[158:161], v[182:185], v[120:123]
	v_mfma_f32_16x16x32_bf16 v[112:115], v[144:147], v[190:193], v[112:115]
	v_mfma_f32_16x16x32_bf16 v[104:107], v[158:161], v[190:193], v[104:107]
	v_mfma_f32_16x16x32_bf16 v[92:95], v[144:147], v[198:201], v[92:95]
	v_mfma_f32_16x16x32_bf16 v[88:91], v[158:161], v[198:201], v[88:91]
	v_mfma_f32_16x16x32_bf16 v[80:83], v[144:147], v[214:217], v[80:83]
	v_mfma_f32_16x16x32_bf16 v[72:75], v[158:161], v[214:217], v[72:75]
	v_mfma_f32_16x16x32_bf16 v[124:127], v[148:151], v[186:189], v[124:127]
	v_mfma_f32_16x16x32_bf16 v[120:123], v[162:165], v[186:189], v[120:123]
	v_mfma_f32_16x16x32_bf16 v[112:115], v[148:151], v[194:197], v[112:115]
	v_mfma_f32_16x16x32_bf16 v[104:107], v[162:165], v[194:197], v[104:107]
	v_mfma_f32_16x16x32_bf16 v[92:95], v[148:151], v[210:213], v[92:95]
	v_mfma_f32_16x16x32_bf16 v[88:91], v[162:165], v[210:213], v[88:91]
	v_mfma_f32_16x16x32_bf16 v[80:83], v[148:151], v[218:221], v[80:83]
	v_mfma_f32_16x16x32_bf16 v[72:75], v[162:165], v[218:221], v[72:75]
	v_mfma_f32_16x16x32_bf16 v[116:119], v[166:169], v[182:185], v[116:119]
	v_mfma_f32_16x16x32_bf16 v[108:111], v[174:177], v[182:185], v[108:111]
	v_mfma_f32_16x16x32_bf16 v[100:103], v[166:169], v[190:193], v[100:103]
	v_mfma_f32_16x16x32_bf16 v[96:99], v[174:177], v[190:193], v[96:99]
	v_mfma_f32_16x16x32_bf16 v[84:87], v[166:169], v[198:201], v[84:87]
	v_mfma_f32_16x16x32_bf16 v[76:79], v[174:177], v[198:201], v[76:79]
	v_mfma_f32_16x16x32_bf16 v[68:71], v[166:169], v[214:217], v[68:71]
	v_mfma_f32_16x16x32_bf16 v[64:67], v[174:177], v[214:217], v[64:67]
	v_mfma_f32_16x16x32_bf16 v[116:119], v[170:173], v[186:189], v[116:119]
	v_mfma_f32_16x16x32_bf16 v[108:111], v[178:181], v[186:189], v[108:111]
	v_mfma_f32_16x16x32_bf16 v[100:103], v[170:173], v[194:197], v[100:103]
	v_mfma_f32_16x16x32_bf16 v[96:99], v[178:181], v[194:197], v[96:99]
	v_mfma_f32_16x16x32_bf16 v[84:87], v[170:173], v[210:213], v[84:87]
	v_mfma_f32_16x16x32_bf16 v[76:79], v[178:181], v[210:213], v[76:79]
	v_mfma_f32_16x16x32_bf16 v[68:71], v[170:173], v[218:221], v[68:71]
	v_mfma_f32_16x16x32_bf16 v[64:67], v[178:181], v[218:221], v[64:67]
	s_barrier
	s_add_i32 s55, s47, s40
	v_lshl_add_u64 v[222:223], s[28:29], 0, v[134:135]
	s_mov_b32 m0, s55
	ds_read_b128 v[182:185], v157 offset:16384
	ds_read_b128 v[186:189], v157 offset:17408
	ds_read_b128 v[190:193], v157 offset:18432
	ds_read_b128 v[194:197], v157 offset:19456
	ds_read_b128 v[198:201], v157 offset:20480
	ds_read_b128 v[210:213], v157 offset:21504
	ds_read_b128 v[214:217], v157 offset:22528
	ds_read_b128 v[218:221], v157 offset:23552
	global_load_lds_dwordx4 v[222:223], off
	s_add_i32 m0, s55, 0x2000
	s_add_u32 s56, s28, 0x4000
	v_lshl_add_u64 v[222:223], s[28:29], 0, v[138:139]
	s_addc_u32 s57, s29, 0
	s_add_i32 s55, s48, s40
	global_load_lds_dwordx4 v[222:223], off
	v_lshl_add_u64 v[222:223], s[56:57], 0, v[134:135]
	s_mov_b32 m0, s55
	v_lshl_add_u64 v[224:225], s[30:31], 0, v[136:137]
	global_load_lds_dwordx4 v[222:223], off
	v_lshl_add_u64 v[222:223], s[56:57], 0, v[138:139]
	s_add_i32 m0, s55, 0x2000
	s_nop 0
	global_load_lds_dwordx4 v[222:223], off
	v_lshl_add_u64 v[222:223], s[30:31], 0, v[132:133]
	s_mov_b32 m0, s23
	s_nop 0
	global_load_lds_dwordx4 v[222:223], off
	s_mov_b32 m0, s25
	s_nop 0
	global_load_lds_dwordx4 v[224:225], off
	s_waitcnt vmcnt(8)
	s_waitcnt lgkmcnt(0)
	s_barrier
	s_waitcnt lgkmcnt(0)
	v_mfma_f32_16x16x32_bf16 v[60:63], v[144:147], v[182:185], v[60:63]
	v_mfma_f32_16x16x32_bf16 v[56:59], v[158:161], v[182:185], v[56:59]
	v_mfma_f32_16x16x32_bf16 v[48:51], v[144:147], v[190:193], v[48:51]
	v_mfma_f32_16x16x32_bf16 v[40:43], v[158:161], v[190:193], v[40:43]
	v_mfma_f32_16x16x32_bf16 v[28:31], v[144:147], v[198:201], v[28:31]
	v_mfma_f32_16x16x32_bf16 v[24:27], v[158:161], v[198:201], v[24:27]
	v_mfma_f32_16x16x32_bf16 v[16:19], v[144:147], v[214:217], v[16:19]
	v_mfma_f32_16x16x32_bf16 v[8:11], v[158:161], v[214:217], v[8:11]
	v_mfma_f32_16x16x32_bf16 v[60:63], v[148:151], v[186:189], v[60:63]
	v_mfma_f32_16x16x32_bf16 v[56:59], v[162:165], v[186:189], v[56:59]
	v_mfma_f32_16x16x32_bf16 v[48:51], v[148:151], v[194:197], v[48:51]
	v_mfma_f32_16x16x32_bf16 v[40:43], v[162:165], v[194:197], v[40:43]
	v_mfma_f32_16x16x32_bf16 v[28:31], v[148:151], v[210:213], v[28:31]
	v_mfma_f32_16x16x32_bf16 v[24:27], v[162:165], v[210:213], v[24:27]
	v_mfma_f32_16x16x32_bf16 v[16:19], v[148:151], v[218:221], v[16:19]
	v_mfma_f32_16x16x32_bf16 v[8:11], v[162:165], v[218:221], v[8:11]
	v_mfma_f32_16x16x32_bf16 v[52:55], v[166:169], v[182:185], v[52:55]
	v_mfma_f32_16x16x32_bf16 v[44:47], v[174:177], v[182:185], v[44:47]
	v_mfma_f32_16x16x32_bf16 v[36:39], v[166:169], v[190:193], v[36:39]
	v_mfma_f32_16x16x32_bf16 v[32:35], v[174:177], v[190:193], v[32:35]
	v_mfma_f32_16x16x32_bf16 v[20:23], v[166:169], v[198:201], v[20:23]
	v_mfma_f32_16x16x32_bf16 v[12:15], v[174:177], v[198:201], v[12:15]
	v_mfma_f32_16x16x32_bf16 v[4:7], v[166:169], v[214:217], v[4:7]
	v_mfma_f32_16x16x32_bf16 v[0:3], v[174:177], v[214:217], v[0:3]
	v_mfma_f32_16x16x32_bf16 v[52:55], v[170:173], v[186:189], v[52:55]
	v_mfma_f32_16x16x32_bf16 v[44:47], v[178:181], v[186:189], v[44:47]
	v_mfma_f32_16x16x32_bf16 v[36:39], v[170:173], v[194:197], v[36:39]
	v_mfma_f32_16x16x32_bf16 v[32:35], v[178:181], v[194:197], v[32:35]
	v_mfma_f32_16x16x32_bf16 v[20:23], v[170:173], v[210:213], v[20:23]
	v_mfma_f32_16x16x32_bf16 v[12:15], v[178:181], v[210:213], v[12:15]
	v_mfma_f32_16x16x32_bf16 v[4:7], v[170:173], v[218:221], v[4:7]
	v_mfma_f32_16x16x32_bf16 v[0:3], v[178:181], v[218:221], v[0:3]
	s_barrier
	s_add_i32 s55, 0, 0x18000
	s_add_i32 s56, 0, 0x1c000
	v_add_u32_e32 v162, s55, v153
	v_add_u32_e32 v178, s56, v153
	ds_read_b128 v[144:147], v162
	ds_read_b128 v[148:151], v162 offset:1024
	ds_read_b128 v[158:161], v162 offset:2048
	ds_read_b128 v[162:165], v162 offset:3072
	ds_read_b128 v[166:169], v178
	ds_read_b128 v[170:173], v178 offset:1024
	ds_read_b128 v[174:177], v178 offset:2048
	ds_read_b128 v[178:181], v178 offset:3072
	s_add_u32 s30, s30, 0x20000
	s_addc_u32 s31, s31, 0
	s_mov_b32 m0, s41
	v_lshl_add_u64 v[226:227], s[30:31], 0, v[132:133]
	ds_read_b128 v[182:185], v157 offset:32768
	ds_read_b128 v[186:189], v157 offset:33792
	ds_read_b128 v[190:193], v157 offset:34816
	ds_read_b128 v[194:197], v157 offset:35840
	ds_read_b128 v[198:201], v157 offset:36864
	ds_read_b128 v[210:213], v157 offset:37888
	ds_read_b128 v[214:217], v157 offset:38912
	ds_read_b128 v[218:221], v157 offset:39936
	global_load_lds_dwordx4 v[226:227], off
	v_lshl_add_u64 v[226:227], s[30:31], 0, v[136:137]
	s_mov_b32 m0, s42
	s_nop 0
	global_load_lds_dwordx4 v[226:227], off
	s_waitcnt vmcnt(8)
	s_waitcnt lgkmcnt(0)
	s_barrier
	s_waitcnt lgkmcnt(0)
	v_mfma_f32_16x16x32_bf16 v[124:127], v[144:147], v[182:185], v[124:127]
	v_mfma_f32_16x16x32_bf16 v[120:123], v[158:161], v[182:185], v[120:123]
	v_mfma_f32_16x16x32_bf16 v[112:115], v[144:147], v[190:193], v[112:115]
	v_mfma_f32_16x16x32_bf16 v[104:107], v[158:161], v[190:193], v[104:107]
	v_mfma_f32_16x16x32_bf16 v[92:95], v[144:147], v[198:201], v[92:95]
	v_mfma_f32_16x16x32_bf16 v[88:91], v[158:161], v[198:201], v[88:91]
	v_mfma_f32_16x16x32_bf16 v[80:83], v[144:147], v[214:217], v[80:83]
	v_mfma_f32_16x16x32_bf16 v[72:75], v[158:161], v[214:217], v[72:75]
	v_mfma_f32_16x16x32_bf16 v[124:127], v[148:151], v[186:189], v[124:127]
	v_mfma_f32_16x16x32_bf16 v[120:123], v[162:165], v[186:189], v[120:123]
	v_mfma_f32_16x16x32_bf16 v[112:115], v[148:151], v[194:197], v[112:115]
	v_mfma_f32_16x16x32_bf16 v[104:107], v[162:165], v[194:197], v[104:107]
	v_mfma_f32_16x16x32_bf16 v[92:95], v[148:151], v[210:213], v[92:95]
	v_mfma_f32_16x16x32_bf16 v[88:91], v[162:165], v[210:213], v[88:91]
	v_mfma_f32_16x16x32_bf16 v[80:83], v[148:151], v[218:221], v[80:83]
	v_mfma_f32_16x16x32_bf16 v[72:75], v[162:165], v[218:221], v[72:75]
	v_mfma_f32_16x16x32_bf16 v[116:119], v[166:169], v[182:185], v[116:119]
	v_mfma_f32_16x16x32_bf16 v[108:111], v[174:177], v[182:185], v[108:111]
	v_mfma_f32_16x16x32_bf16 v[100:103], v[166:169], v[190:193], v[100:103]
	v_mfma_f32_16x16x32_bf16 v[96:99], v[174:177], v[190:193], v[96:99]
	v_mfma_f32_16x16x32_bf16 v[84:87], v[166:169], v[198:201], v[84:87]
	v_mfma_f32_16x16x32_bf16 v[76:79], v[174:177], v[198:201], v[76:79]
	v_mfma_f32_16x16x32_bf16 v[68:71], v[166:169], v[214:217], v[68:71]
	v_mfma_f32_16x16x32_bf16 v[64:67], v[174:177], v[214:217], v[64:67]
	v_mfma_f32_16x16x32_bf16 v[116:119], v[170:173], v[186:189], v[116:119]
	v_mfma_f32_16x16x32_bf16 v[108:111], v[178:181], v[186:189], v[108:111]
	v_mfma_f32_16x16x32_bf16 v[100:103], v[170:173], v[194:197], v[100:103]
	v_mfma_f32_16x16x32_bf16 v[96:99], v[178:181], v[194:197], v[96:99]
	v_mfma_f32_16x16x32_bf16 v[84:87], v[170:173], v[210:213], v[84:87]
	v_mfma_f32_16x16x32_bf16 v[76:79], v[178:181], v[210:213], v[76:79]
	v_mfma_f32_16x16x32_bf16 v[68:71], v[170:173], v[218:221], v[68:71]
	v_mfma_f32_16x16x32_bf16 v[64:67], v[178:181], v[218:221], v[64:67]
	s_barrier
	s_add_u32 s30, s28, 0x8000
	s_addc_u32 s31, s29, 0
	s_add_i32 s55, s55, s40
	v_lshl_add_u64 v[226:227], s[30:31], 0, v[134:135]
	s_mov_b32 m0, s55
	ds_read_b128 v[182:185], v157 offset:49152
	ds_read_b128 v[186:189], v157 offset:50176
	ds_read_b128 v[190:193], v157 offset:51200
	ds_read_b128 v[194:197], v157 offset:52224
	ds_read_b128 v[198:201], v157 offset:53248
	ds_read_b128 v[210:213], v157 offset:54272
	ds_read_b128 v[214:217], v157 offset:55296
	ds_read_b128 v[218:221], v157 offset:56320
	global_load_lds_dwordx4 v[226:227], off
	s_add_i32 m0, s55, 0x2000
	s_add_u32 s28, s28, 0xc000
	v_lshl_add_u64 v[226:227], s[30:31], 0, v[138:139]
	s_addc_u32 s29, s29, 0
	s_add_i32 s30, s56, s40
	global_load_lds_dwordx4 v[226:227], off
	v_lshl_add_u64 v[226:227], s[28:29], 0, v[134:135]
	s_mov_b32 m0, s30
	v_lshl_add_u64 v[222:223], v[222:223], 0, s[8:9]
	global_load_lds_dwordx4 v[226:227], off
	v_lshl_add_u64 v[226:227], s[28:29], 0, v[138:139]
	s_add_i32 m0, s30, 0x2000
	s_nop 0
	global_load_lds_dwordx4 v[226:227], off
	s_mov_b32 m0, s44
	s_nop 0
	global_load_lds_dwordx4 v[222:223], off
	v_lshl_add_u64 v[222:223], v[224:225], 0, s[8:9]
	s_mov_b32 m0, s45
	s_nop 0
	global_load_lds_dwordx4 v[222:223], off
	s_waitcnt vmcnt(8)
	s_waitcnt lgkmcnt(0)
	s_barrier
	s_waitcnt lgkmcnt(0)
	v_mfma_f32_16x16x32_bf16 v[60:63], v[144:147], v[182:185], v[60:63]
	v_mfma_f32_16x16x32_bf16 v[56:59], v[158:161], v[182:185], v[56:59]
	v_mfma_f32_16x16x32_bf16 v[48:51], v[144:147], v[190:193], v[48:51]
	v_mfma_f32_16x16x32_bf16 v[40:43], v[158:161], v[190:193], v[40:43]
	v_mfma_f32_16x16x32_bf16 v[28:31], v[144:147], v[198:201], v[28:31]
	v_mfma_f32_16x16x32_bf16 v[24:27], v[158:161], v[198:201], v[24:27]
	v_mfma_f32_16x16x32_bf16 v[16:19], v[144:147], v[214:217], v[16:19]
	v_mfma_f32_16x16x32_bf16 v[8:11], v[158:161], v[214:217], v[8:11]
	v_mfma_f32_16x16x32_bf16 v[60:63], v[148:151], v[186:189], v[60:63]
	v_mfma_f32_16x16x32_bf16 v[56:59], v[162:165], v[186:189], v[56:59]
	v_mfma_f32_16x16x32_bf16 v[48:51], v[148:151], v[194:197], v[48:51]
	v_mfma_f32_16x16x32_bf16 v[40:43], v[162:165], v[194:197], v[40:43]
	v_mfma_f32_16x16x32_bf16 v[28:31], v[148:151], v[210:213], v[28:31]
	v_mfma_f32_16x16x32_bf16 v[24:27], v[162:165], v[210:213], v[24:27]
	v_mfma_f32_16x16x32_bf16 v[16:19], v[148:151], v[218:221], v[16:19]
	v_mfma_f32_16x16x32_bf16 v[8:11], v[162:165], v[218:221], v[8:11]
	v_mfma_f32_16x16x32_bf16 v[52:55], v[166:169], v[182:185], v[52:55]
	v_mfma_f32_16x16x32_bf16 v[44:47], v[174:177], v[182:185], v[44:47]
	v_mfma_f32_16x16x32_bf16 v[36:39], v[166:169], v[190:193], v[36:39]
	v_mfma_f32_16x16x32_bf16 v[32:35], v[174:177], v[190:193], v[32:35]
	v_mfma_f32_16x16x32_bf16 v[20:23], v[166:169], v[198:201], v[20:23]
	v_mfma_f32_16x16x32_bf16 v[12:15], v[174:177], v[198:201], v[12:15]
	v_mfma_f32_16x16x32_bf16 v[4:7], v[166:169], v[214:217], v[4:7]
	v_mfma_f32_16x16x32_bf16 v[0:3], v[174:177], v[214:217], v[0:3]
	v_mfma_f32_16x16x32_bf16 v[52:55], v[170:173], v[186:189], v[52:55]
	v_mfma_f32_16x16x32_bf16 v[44:47], v[178:181], v[186:189], v[44:47]
	v_mfma_f32_16x16x32_bf16 v[36:39], v[170:173], v[194:197], v[36:39]
	v_mfma_f32_16x16x32_bf16 v[32:35], v[178:181], v[194:197], v[32:35]
	v_mfma_f32_16x16x32_bf16 v[20:23], v[170:173], v[210:213], v[20:23]
	v_mfma_f32_16x16x32_bf16 v[12:15], v[178:181], v[210:213], v[12:15]
	v_mfma_f32_16x16x32_bf16 v[4:7], v[170:173], v[218:221], v[4:7]
	v_mfma_f32_16x16x32_bf16 v[0:3], v[178:181], v[218:221], v[0:3]
	s_barrier
	s_add_i32 s54, s54, 2
	s_add_u32 s52, s52, 0x10000
	s_addc_u32 s53, s53, 0
	s_add_u32 s26, s26, 0x100
	s_addc_u32 s27, s27, 0
	s_cmp_gt_u32 s54, 5
	s_cbranch_scc0 .LBB0_1095
	s_and_b64 vcc, exec, s[10:11]
	s_cbranch_vccz .LBB0_1098
	s_barrier

.LBB0_1171:
	v_add_u32_e32 v168, s77, v182
	v_add_u32_e32 v204, s78, v182
	ds_read_b128 v[156:159], v168
	ds_read_b128 v[160:163], v168 offset:1024
	ds_read_b128 v[164:167], v168 offset:2048
	ds_read_b128 v[168:171], v168 offset:3072
	ds_read_b128 v[172:175], v204
	ds_read_b128 v[176:179], v204 offset:1024
	ds_read_b128 v[212:215], v204 offset:2048
	ds_read_b128 v[216:219], v204 offset:3072
	s_add_u32 s48, s46, 0xfffc0080
	s_addc_u32 s49, s47, -1
	s_cmp_eq_u32 s54, 12
	s_cselect_b32 s51, s35, s49
	s_cselect_b32 s50, s43, s48
	s_cselect_b32 s49, s37, s53
	s_cselect_b32 s48, s45, s52
	v_lshl_add_u64 v[252:253], s[46:47], 0, v[154:155]
	s_add_i32 m0, s65, 0xc000
	ds_read_b128 v[220:223], v199
	ds_read_b128 v[224:227], v199 offset:1024
	ds_read_b128 v[228:231], v199 offset:2048
	ds_read_b128 v[232:235], v199 offset:3072
	ds_read_b128 v[236:239], v199 offset:4096
	ds_read_b128 v[240:243], v199 offset:5120
	ds_read_b128 v[244:247], v199 offset:6144
	ds_read_b128 v[248:251], v199 offset:7168
	global_load_lds_dwordx4 v[252:253], off
	v_lshl_add_u64 v[252:253], s[46:47], 0, v[152:153]
	s_add_i32 m0, s65, 0xe000
	s_nop 0
	global_load_lds_dwordx4 v[252:253], off
	s_waitcnt vmcnt(8)
	s_waitcnt lgkmcnt(0)
	s_barrier
	s_waitcnt lgkmcnt(0)
	v_mfma_f32_16x16x32_bf16 v[124:127], v[156:159], v[220:223], v[124:127]
	v_mfma_f32_16x16x32_bf16 v[120:123], v[164:167], v[220:223], v[120:123]
	v_mfma_f32_16x16x32_bf16 v[116:119], v[156:159], v[228:231], v[116:119]
	v_mfma_f32_16x16x32_bf16 v[112:115], v[164:167], v[228:231], v[112:115]
	v_mfma_f32_16x16x32_bf16 v[92:95], v[156:159], v[236:239], v[92:95]
	v_mfma_f32_16x16x32_bf16 v[88:91], v[164:167], v[236:239], v[88:91]
	v_mfma_f32_16x16x32_bf16 v[84:87], v[156:159], v[244:247], v[84:87]
	v_mfma_f32_16x16x32_bf16 v[80:83], v[164:167], v[244:247], v[80:83]
	v_mfma_f32_16x16x32_bf16 v[124:127], v[160:163], v[224:227], v[124:127]
	v_mfma_f32_16x16x32_bf16 v[120:123], v[168:171], v[224:227], v[120:123]
	v_mfma_f32_16x16x32_bf16 v[116:119], v[160:163], v[232:235], v[116:119]
	v_mfma_f32_16x16x32_bf16 v[112:115], v[168:171], v[232:235], v[112:115]
	v_mfma_f32_16x16x32_bf16 v[92:95], v[160:163], v[240:243], v[92:95]
	v_mfma_f32_16x16x32_bf16 v[88:91], v[168:171], v[240:243], v[88:91]
	v_mfma_f32_16x16x32_bf16 v[84:87], v[160:163], v[248:251], v[84:87]
	v_mfma_f32_16x16x32_bf16 v[80:83], v[168:171], v[248:251], v[80:83]
	v_mfma_f32_16x16x32_bf16 v[108:111], v[172:175], v[220:223], v[108:111]
	v_mfma_f32_16x16x32_bf16 v[104:107], v[212:215], v[220:223], v[104:107]
	v_mfma_f32_16x16x32_bf16 v[100:103], v[172:175], v[228:231], v[100:103]
	v_mfma_f32_16x16x32_bf16 v[96:99], v[212:215], v[228:231], v[96:99]
	v_mfma_f32_16x16x32_bf16 v[76:79], v[172:175], v[236:239], v[76:79]
	v_mfma_f32_16x16x32_bf16 v[72:75], v[212:215], v[236:239], v[72:75]
	v_mfma_f32_16x16x32_bf16 v[68:71], v[172:175], v[244:247], v[68:71]
	v_mfma_f32_16x16x32_bf16 v[64:67], v[212:215], v[244:247], v[64:67]
	v_mfma_f32_16x16x32_bf16 v[108:111], v[176:179], v[224:227], v[108:111]
	v_mfma_f32_16x16x32_bf16 v[104:107], v[216:219], v[224:227], v[104:107]
	v_mfma_f32_16x16x32_bf16 v[100:103], v[176:179], v[232:235], v[100:103]
	v_mfma_f32_16x16x32_bf16 v[96:99], v[216:219], v[232:235], v[96:99]
	v_mfma_f32_16x16x32_bf16 v[76:79], v[176:179], v[240:243], v[76:79]
	v_mfma_f32_16x16x32_bf16 v[72:75], v[216:219], v[240:243], v[72:75]
	v_mfma_f32_16x16x32_bf16 v[68:71], v[176:179], v[248:251], v[68:71]
	v_mfma_f32_16x16x32_bf16 v[64:67], v[216:219], v[248:251], v[64:67]
	s_barrier
	s_add_i32 s55, s77, s64
	v_lshl_add_u64 v[252:253], s[48:49], 0, v[130:131]
	s_mov_b32 m0, s55
	ds_read_b128 v[220:223], v199 offset:16384
	ds_read_b128 v[224:227], v199 offset:17408
	ds_read_b128 v[228:231], v199 offset:18432
	ds_read_b128 v[232:235], v199 offset:19456
	ds_read_b128 v[236:239], v199 offset:20480
	ds_read_b128 v[240:243], v199 offset:21504
	ds_read_b128 v[244:247], v199 offset:22528
	ds_read_b128 v[248:251], v199 offset:23552
	global_load_lds_dwordx4 v[252:253], off
	s_add_i32 m0, s55, 0x2000
	s_add_u32 s56, s48, 0x4000
	v_lshl_add_u64 v[252:253], s[48:49], 0, v[134:135]
	s_addc_u32 s57, s49, 0
	s_add_i32 s55, s78, s64
	global_load_lds_dwordx4 v[252:253], off
	v_lshl_add_u64 v[252:253], s[56:57], 0, v[130:131]
	s_mov_b32 m0, s55
	v_lshl_add_u64 v[204:205], s[50:51], 0, v[132:133]
	global_load_lds_dwordx4 v[252:253], off
	v_lshl_add_u64 v[252:253], s[56:57], 0, v[134:135]
	s_add_i32 m0, s55, 0x2000
	s_nop 0
	global_load_lds_dwordx4 v[252:253], off
	v_lshl_add_u64 v[252:253], s[50:51], 0, v[128:129]
	s_mov_b32 m0, s65
	s_nop 0
	global_load_lds_dwordx4 v[252:253], off
	s_mov_b32 m0, s66
	s_nop 0
	global_load_lds_dwordx4 v[204:205], off
	s_waitcnt vmcnt(8)
	s_waitcnt lgkmcnt(0)
	s_barrier
	s_waitcnt lgkmcnt(0)
	v_mfma_f32_16x16x32_bf16 v[60:63], v[156:159], v[220:223], v[60:63]
	v_mfma_f32_16x16x32_bf16 v[56:59], v[164:167], v[220:223], v[56:59]
	v_mfma_f32_16x16x32_bf16 v[52:55], v[156:159], v[228:231], v[52:55]
	v_mfma_f32_16x16x32_bf16 v[48:51], v[164:167], v[228:231], v[48:51]
	v_mfma_f32_16x16x32_bf16 v[28:31], v[156:159], v[236:239], v[28:31]
	v_mfma_f32_16x16x32_bf16 v[24:27], v[164:167], v[236:239], v[24:27]
	v_mfma_f32_16x16x32_bf16 v[20:23], v[156:159], v[244:247], v[20:23]
	v_mfma_f32_16x16x32_bf16 v[12:15], v[164:167], v[244:247], v[12:15]
	v_mfma_f32_16x16x32_bf16 v[60:63], v[160:163], v[224:227], v[60:63]
	v_mfma_f32_16x16x32_bf16 v[56:59], v[168:171], v[224:227], v[56:59]
	v_mfma_f32_16x16x32_bf16 v[52:55], v[160:163], v[232:235], v[52:55]
	v_mfma_f32_16x16x32_bf16 v[48:51], v[168:171], v[232:235], v[48:51]
	v_mfma_f32_16x16x32_bf16 v[28:31], v[160:163], v[240:243], v[28:31]
	v_mfma_f32_16x16x32_bf16 v[24:27], v[168:171], v[240:243], v[24:27]
	v_mfma_f32_16x16x32_bf16 v[20:23], v[160:163], v[248:251], v[20:23]
	v_mfma_f32_16x16x32_bf16 v[12:15], v[168:171], v[248:251], v[12:15]
	v_mfma_f32_16x16x32_bf16 v[44:47], v[172:175], v[220:223], v[44:47]
	v_mfma_f32_16x16x32_bf16 v[40:43], v[212:215], v[220:223], v[40:43]
	v_mfma_f32_16x16x32_bf16 v[36:39], v[172:175], v[228:231], v[36:39]
	v_mfma_f32_16x16x32_bf16 v[32:35], v[212:215], v[228:231], v[32:35]
	v_mfma_f32_16x16x32_bf16 v[16:19], v[172:175], v[236:239], v[16:19]
	v_mfma_f32_16x16x32_bf16 v[8:11], v[212:215], v[236:239], v[8:11]
	v_mfma_f32_16x16x32_bf16 v[4:7], v[172:175], v[244:247], v[4:7]
	v_mfma_f32_16x16x32_bf16 v[0:3], v[212:215], v[244:247], v[0:3]
	v_mfma_f32_16x16x32_bf16 v[44:47], v[176:179], v[224:227], v[44:47]
	v_mfma_f32_16x16x32_bf16 v[40:43], v[216:219], v[224:227], v[40:43]
	v_mfma_f32_16x16x32_bf16 v[36:39], v[176:179], v[232:235], v[36:39]
	v_mfma_f32_16x16x32_bf16 v[32:35], v[216:219], v[232:235], v[32:35]
	v_mfma_f32_16x16x32_bf16 v[16:19], v[176:179], v[240:243], v[16:19]
	v_mfma_f32_16x16x32_bf16 v[8:11], v[216:219], v[240:243], v[8:11]
	v_mfma_f32_16x16x32_bf16 v[4:7], v[176:179], v[248:251], v[4:7]
	v_mfma_f32_16x16x32_bf16 v[0:3], v[216:219], v[248:251], v[0:3]
	s_barrier
	s_add_i32 s55, 0, 0x18000
	s_add_i32 s56, 0, 0x1c000
	v_add_u32_e32 v168, s55, v182
	v_add_u32_e32 v206, s56, v182
	ds_read_b128 v[156:159], v168
	ds_read_b128 v[160:163], v168 offset:1024
	ds_read_b128 v[164:167], v168 offset:2048
	ds_read_b128 v[168:171], v168 offset:3072
	ds_read_b128 v[172:175], v206
	ds_read_b128 v[176:179], v206 offset:1024
	ds_read_b128 v[212:215], v206 offset:2048
	ds_read_b128 v[216:219], v206 offset:3072
	s_add_u32 s50, s50, 0x40000
	s_addc_u32 s51, s51, 0
	s_mov_b32 m0, s67
	v_lshl_add_u64 v[206:207], s[50:51], 0, v[128:129]
	ds_read_b128 v[220:223], v199 offset:32768
	ds_read_b128 v[224:227], v199 offset:33792
	ds_read_b128 v[228:231], v199 offset:34816
	ds_read_b128 v[232:235], v199 offset:35840
	ds_read_b128 v[236:239], v199 offset:36864
	ds_read_b128 v[240:243], v199 offset:37888
	ds_read_b128 v[244:247], v199 offset:38912
	ds_read_b128 v[248:251], v199 offset:39936
	global_load_lds_dwordx4 v[206:207], off
	v_lshl_add_u64 v[206:207], s[50:51], 0, v[132:133]
	s_mov_b32 m0, s68
	s_nop 0
	global_load_lds_dwordx4 v[206:207], off
	s_waitcnt vmcnt(8)
	s_waitcnt lgkmcnt(0)
	s_barrier
	s_waitcnt lgkmcnt(0)
	v_mfma_f32_16x16x32_bf16 v[124:127], v[156:159], v[220:223], v[124:127]
	v_mfma_f32_16x16x32_bf16 v[120:123], v[164:167], v[220:223], v[120:123]
	v_mfma_f32_16x16x32_bf16 v[116:119], v[156:159], v[228:231], v[116:119]
	v_mfma_f32_16x16x32_bf16 v[112:115], v[164:167], v[228:231], v[112:115]
	v_mfma_f32_16x16x32_bf16 v[92:95], v[156:159], v[236:239], v[92:95]
	v_mfma_f32_16x16x32_bf16 v[88:91], v[164:167], v[236:239], v[88:91]
	v_mfma_f32_16x16x32_bf16 v[84:87], v[156:159], v[244:247], v[84:87]
	v_mfma_f32_16x16x32_bf16 v[80:83], v[164:167], v[244:247], v[80:83]
	v_mfma_f32_16x16x32_bf16 v[124:127], v[160:163], v[224:227], v[124:127]
	v_mfma_f32_16x16x32_bf16 v[120:123], v[168:171], v[224:227], v[120:123]
	v_mfma_f32_16x16x32_bf16 v[116:119], v[160:163], v[232:235], v[116:119]
	v_mfma_f32_16x16x32_bf16 v[112:115], v[168:171], v[232:235], v[112:115]
	v_mfma_f32_16x16x32_bf16 v[92:95], v[160:163], v[240:243], v[92:95]
	v_mfma_f32_16x16x32_bf16 v[88:91], v[168:171], v[240:243], v[88:91]
	v_mfma_f32_16x16x32_bf16 v[84:87], v[160:163], v[248:251], v[84:87]
	v_mfma_f32_16x16x32_bf16 v[80:83], v[168:171], v[248:251], v[80:83]
	v_mfma_f32_16x16x32_bf16 v[108:111], v[172:175], v[220:223], v[108:111]
	v_mfma_f32_16x16x32_bf16 v[104:107], v[212:215], v[220:223], v[104:107]
	v_mfma_f32_16x16x32_bf16 v[100:103], v[172:175], v[228:231], v[100:103]
	v_mfma_f32_16x16x32_bf16 v[96:99], v[212:215], v[228:231], v[96:99]
	v_mfma_f32_16x16x32_bf16 v[76:79], v[172:175], v[236:239], v[76:79]
	v_mfma_f32_16x16x32_bf16 v[72:75], v[212:215], v[236:239], v[72:75]
	v_mfma_f32_16x16x32_bf16 v[68:71], v[172:175], v[244:247], v[68:71]
	v_mfma_f32_16x16x32_bf16 v[64:67], v[212:215], v[244:247], v[64:67]
	v_mfma_f32_16x16x32_bf16 v[108:111], v[176:179], v[224:227], v[108:111]
	v_mfma_f32_16x16x32_bf16 v[104:107], v[216:219], v[224:227], v[104:107]
	v_mfma_f32_16x16x32_bf16 v[100:103], v[176:179], v[232:235], v[100:103]
	v_mfma_f32_16x16x32_bf16 v[96:99], v[216:219], v[232:235], v[96:99]
	v_mfma_f32_16x16x32_bf16 v[76:79], v[176:179], v[240:243], v[76:79]
	v_mfma_f32_16x16x32_bf16 v[72:75], v[216:219], v[240:243], v[72:75]
	v_mfma_f32_16x16x32_bf16 v[68:71], v[176:179], v[248:251], v[68:71]
	v_mfma_f32_16x16x32_bf16 v[64:67], v[216:219], v[248:251], v[64:67]
	s_barrier
	s_add_u32 s50, s48, 0x8000
	s_addc_u32 s51, s49, 0
	s_add_i32 s55, s55, s64
	v_lshl_add_u64 v[206:207], s[50:51], 0, v[130:131]
	s_mov_b32 m0, s55
	ds_read_b128 v[220:223], v199 offset:49152
	ds_read_b128 v[224:227], v199 offset:50176
	ds_read_b128 v[228:231], v199 offset:51200
	ds_read_b128 v[232:235], v199 offset:52224
	ds_read_b128 v[236:239], v199 offset:53248
	ds_read_b128 v[240:243], v199 offset:54272
	ds_read_b128 v[244:247], v199 offset:55296
	ds_read_b128 v[248:251], v199 offset:56320
	global_load_lds_dwordx4 v[206:207], off
	s_add_i32 m0, s55, 0x2000
	s_add_u32 s48, s48, 0xc000
	v_lshl_add_u64 v[206:207], s[50:51], 0, v[134:135]
	s_addc_u32 s49, s49, 0
	s_add_i32 s50, s56, s64
	global_load_lds_dwordx4 v[206:207], off
	v_lshl_add_u64 v[206:207], s[48:49], 0, v[130:131]
	s_mov_b32 m0, s50
	v_lshl_add_u64 v[204:205], v[204:205], 0, s[14:15]
	global_load_lds_dwordx4 v[206:207], off
	v_lshl_add_u64 v[206:207], s[48:49], 0, v[134:135]
	s_add_i32 m0, s50, 0x2000
	s_nop 0
	global_load_lds_dwordx4 v[206:207], off
	v_lshl_add_u64 v[206:207], v[252:253], 0, s[14:15]
	s_mov_b32 m0, s74
	s_nop 0
	global_load_lds_dwordx4 v[206:207], off
	s_mov_b32 m0, s75
	s_nop 0
	global_load_lds_dwordx4 v[204:205], off
	s_waitcnt vmcnt(8)
	s_waitcnt lgkmcnt(0)
	s_barrier
	s_waitcnt lgkmcnt(0)
	v_mfma_f32_16x16x32_bf16 v[60:63], v[156:159], v[220:223], v[60:63]
	v_mfma_f32_16x16x32_bf16 v[56:59], v[164:167], v[220:223], v[56:59]
	v_mfma_f32_16x16x32_bf16 v[52:55], v[156:159], v[228:231], v[52:55]
	v_mfma_f32_16x16x32_bf16 v[48:51], v[164:167], v[228:231], v[48:51]
	v_mfma_f32_16x16x32_bf16 v[28:31], v[156:159], v[236:239], v[28:31]
	v_mfma_f32_16x16x32_bf16 v[24:27], v[164:167], v[236:239], v[24:27]
	v_mfma_f32_16x16x32_bf16 v[20:23], v[156:159], v[244:247], v[20:23]
	v_mfma_f32_16x16x32_bf16 v[12:15], v[164:167], v[244:247], v[12:15]
	v_mfma_f32_16x16x32_bf16 v[60:63], v[160:163], v[224:227], v[60:63]
	v_mfma_f32_16x16x32_bf16 v[56:59], v[168:171], v[224:227], v[56:59]
	v_mfma_f32_16x16x32_bf16 v[52:55], v[160:163], v[232:235], v[52:55]
	v_mfma_f32_16x16x32_bf16 v[48:51], v[168:171], v[232:235], v[48:51]
	v_mfma_f32_16x16x32_bf16 v[28:31], v[160:163], v[240:243], v[28:31]
	v_mfma_f32_16x16x32_bf16 v[24:27], v[168:171], v[240:243], v[24:27]
	v_mfma_f32_16x16x32_bf16 v[20:23], v[160:163], v[248:251], v[20:23]
	v_mfma_f32_16x16x32_bf16 v[12:15], v[168:171], v[248:251], v[12:15]
	v_mfma_f32_16x16x32_bf16 v[44:47], v[172:175], v[220:223], v[44:47]
	v_mfma_f32_16x16x32_bf16 v[40:43], v[212:215], v[220:223], v[40:43]
	v_mfma_f32_16x16x32_bf16 v[36:39], v[172:175], v[228:231], v[36:39]
	v_mfma_f32_16x16x32_bf16 v[32:35], v[212:215], v[228:231], v[32:35]
	v_mfma_f32_16x16x32_bf16 v[16:19], v[172:175], v[236:239], v[16:19]
	v_mfma_f32_16x16x32_bf16 v[8:11], v[212:215], v[236:239], v[8:11]
	v_mfma_f32_16x16x32_bf16 v[4:7], v[172:175], v[244:247], v[4:7]
	v_mfma_f32_16x16x32_bf16 v[0:3], v[212:215], v[244:247], v[0:3]
	v_mfma_f32_16x16x32_bf16 v[44:47], v[176:179], v[224:227], v[44:47]
	v_mfma_f32_16x16x32_bf16 v[40:43], v[216:219], v[224:227], v[40:43]
	v_mfma_f32_16x16x32_bf16 v[36:39], v[176:179], v[232:235], v[36:39]
	v_mfma_f32_16x16x32_bf16 v[32:35], v[216:219], v[232:235], v[32:35]
	v_mfma_f32_16x16x32_bf16 v[16:19], v[176:179], v[240:243], v[16:19]
	v_mfma_f32_16x16x32_bf16 v[8:11], v[216:219], v[240:243], v[8:11]
	v_mfma_f32_16x16x32_bf16 v[4:7], v[176:179], v[248:251], v[4:7]
	v_mfma_f32_16x16x32_bf16 v[0:3], v[216:219], v[248:251], v[0:3]
	s_barrier
	s_add_i32 s54, s54, 2
	s_add_u32 s52, s52, 0x10000
	s_addc_u32 s53, s53, 0
	s_add_u32 s46, s46, 0x100
	s_addc_u32 s47, s47, 0
	s_cmp_gt_u32 s54, 13
	s_cbranch_scc0 .LBB0_1171
	s_and_b64 vcc, exec, s[18:19]
	s_cbranch_vccz .LBB0_1174
	s_barrier

.LBB0_1253:
	ds_read_b128 v[170:173], v167
	ds_read_b128 v[174:177], v167 offset:1024
	ds_read_b128 v[178:181], v167 offset:2048
	ds_read_b128 v[182:185], v167 offset:3072
	ds_read_b128 v[186:189], v168
	ds_read_b128 v[190:193], v168 offset:1024
	ds_read_b128 v[194:197], v168 offset:2048
	ds_read_b128 v[198:201], v168 offset:3072
	s_add_u32 s26, s24, 0xfffc0080
	s_addc_u32 s27, s25, -1
	s_cmp_eq_u32 s54, 12
	s_cselect_b32 s29, s11, s27
	s_cselect_b32 s28, s50, s26
	s_cselect_b32 s27, s13, s53
	s_cselect_b32 s26, s51, s52
	v_lshl_add_u64 v[164:165], s[24:25], 0, v[158:159]
	s_add_i32 m0, s21, 0xc000
	ds_read_b128 v[210:213], v169
	ds_read_b128 v[214:217], v169 offset:1024
	ds_read_b128 v[218:221], v169 offset:2048
	ds_read_b128 v[222:225], v169 offset:3072
	ds_read_b128 v[226:229], v169 offset:4096
	ds_read_b128 v[230:233], v169 offset:5120
	ds_read_b128 v[234:237], v169 offset:6144
	ds_read_b128 v[238:241], v169 offset:7168
	global_load_lds_dwordx4 v[164:165], off
	v_lshl_add_u64 v[164:165], s[24:25], 0, v[156:157]
	s_add_i32 m0, s21, 0xe000
	s_nop 0
	global_load_lds_dwordx4 v[164:165], off
	s_waitcnt vmcnt(8)
	s_waitcnt lgkmcnt(0)
	s_barrier
	s_waitcnt lgkmcnt(0)
	v_mfma_f32_16x16x32_bf16 v[124:127], v[170:173], v[210:213], v[124:127]
	v_mfma_f32_16x16x32_bf16 v[116:119], v[178:181], v[210:213], v[116:119]
	v_mfma_f32_16x16x32_bf16 v[108:111], v[170:173], v[218:221], v[108:111]
	v_mfma_f32_16x16x32_bf16 v[100:103], v[178:181], v[218:221], v[100:103]
	v_mfma_f32_16x16x32_bf16 v[92:95], v[170:173], v[226:229], v[92:95]
	v_mfma_f32_16x16x32_bf16 v[84:87], v[178:181], v[226:229], v[84:87]
	v_mfma_f32_16x16x32_bf16 v[76:79], v[170:173], v[234:237], v[76:79]
	v_mfma_f32_16x16x32_bf16 v[68:71], v[178:181], v[234:237], v[68:71]
	v_mfma_f32_16x16x32_bf16 v[124:127], v[174:177], v[214:217], v[124:127]
	v_mfma_f32_16x16x32_bf16 v[116:119], v[182:185], v[214:217], v[116:119]
	v_mfma_f32_16x16x32_bf16 v[108:111], v[174:177], v[222:225], v[108:111]
	v_mfma_f32_16x16x32_bf16 v[100:103], v[182:185], v[222:225], v[100:103]
	v_mfma_f32_16x16x32_bf16 v[92:95], v[174:177], v[230:233], v[92:95]
	v_mfma_f32_16x16x32_bf16 v[84:87], v[182:185], v[230:233], v[84:87]
	v_mfma_f32_16x16x32_bf16 v[76:79], v[174:177], v[238:241], v[76:79]
	v_mfma_f32_16x16x32_bf16 v[68:71], v[182:185], v[238:241], v[68:71]
	v_mfma_f32_16x16x32_bf16 v[120:123], v[186:189], v[210:213], v[120:123]
	v_mfma_f32_16x16x32_bf16 v[112:115], v[194:197], v[210:213], v[112:115]
	v_mfma_f32_16x16x32_bf16 v[104:107], v[186:189], v[218:221], v[104:107]
	v_mfma_f32_16x16x32_bf16 v[96:99], v[194:197], v[218:221], v[96:99]
	v_mfma_f32_16x16x32_bf16 v[88:91], v[186:189], v[226:229], v[88:91]
	v_mfma_f32_16x16x32_bf16 v[80:83], v[194:197], v[226:229], v[80:83]
	v_mfma_f32_16x16x32_bf16 v[72:75], v[186:189], v[234:237], v[72:75]
	v_mfma_f32_16x16x32_bf16 v[64:67], v[194:197], v[234:237], v[64:67]
	v_mfma_f32_16x16x32_bf16 v[120:123], v[190:193], v[214:217], v[120:123]
	v_mfma_f32_16x16x32_bf16 v[112:115], v[198:201], v[214:217], v[112:115]
	v_mfma_f32_16x16x32_bf16 v[104:107], v[190:193], v[222:225], v[104:107]
	v_mfma_f32_16x16x32_bf16 v[96:99], v[198:201], v[222:225], v[96:99]
	v_mfma_f32_16x16x32_bf16 v[88:91], v[190:193], v[230:233], v[88:91]
	v_mfma_f32_16x16x32_bf16 v[80:83], v[198:201], v[230:233], v[80:83]
	v_mfma_f32_16x16x32_bf16 v[72:75], v[190:193], v[238:241], v[72:75]
	v_mfma_f32_16x16x32_bf16 v[64:67], v[198:201], v[238:241], v[64:67]
	s_barrier
	s_add_i32 s55, s48, s35
	v_lshl_add_u64 v[164:165], s[26:27], 0, v[134:135]
	s_mov_b32 m0, s55
	ds_read_b128 v[210:213], v169 offset:16384
	ds_read_b128 v[214:217], v169 offset:17408
	ds_read_b128 v[218:221], v169 offset:18432
	ds_read_b128 v[222:225], v169 offset:19456
	ds_read_b128 v[226:229], v169 offset:20480
	ds_read_b128 v[230:233], v169 offset:21504
	ds_read_b128 v[234:237], v169 offset:22528
	ds_read_b128 v[238:241], v169 offset:23552
	global_load_lds_dwordx4 v[164:165], off
	s_add_i32 m0, s55, 0x2000
	s_add_u32 s56, s26, 0x4000
	v_lshl_add_u64 v[164:165], s[26:27], 0, v[130:131]
	s_addc_u32 s57, s27, 0
	s_add_i32 s55, s49, s35
	global_load_lds_dwordx4 v[164:165], off
	v_lshl_add_u64 v[164:165], s[56:57], 0, v[134:135]
	s_mov_b32 m0, s55
	v_lshl_add_u64 v[204:205], s[28:29], 0, v[132:133]
	global_load_lds_dwordx4 v[164:165], off
	v_lshl_add_u64 v[164:165], s[56:57], 0, v[130:131]
	s_add_i32 m0, s55, 0x2000
	s_nop 0
	global_load_lds_dwordx4 v[164:165], off
	v_lshl_add_u64 v[164:165], s[28:29], 0, v[136:137]
	s_mov_b32 m0, s21
	s_nop 0
	global_load_lds_dwordx4 v[164:165], off
	s_mov_b32 m0, s23
	s_nop 0
	global_load_lds_dwordx4 v[204:205], off
	s_waitcnt vmcnt(8)
	s_waitcnt lgkmcnt(0)
	s_barrier
	s_waitcnt lgkmcnt(0)
	v_mfma_f32_16x16x32_bf16 v[60:63], v[170:173], v[210:213], v[60:63]
	v_mfma_f32_16x16x32_bf16 v[52:55], v[178:181], v[210:213], v[52:55]
	v_mfma_f32_16x16x32_bf16 v[44:47], v[170:173], v[218:221], v[44:47]
	v_mfma_f32_16x16x32_bf16 v[36:39], v[178:181], v[218:221], v[36:39]
	v_mfma_f32_16x16x32_bf16 v[28:31], v[170:173], v[226:229], v[28:31]
	v_mfma_f32_16x16x32_bf16 v[20:23], v[178:181], v[226:229], v[20:23]
	v_mfma_f32_16x16x32_bf16 v[12:15], v[170:173], v[234:237], v[12:15]
	v_mfma_f32_16x16x32_bf16 v[4:7], v[178:181], v[234:237], v[4:7]
	v_mfma_f32_16x16x32_bf16 v[60:63], v[174:177], v[214:217], v[60:63]
	v_mfma_f32_16x16x32_bf16 v[52:55], v[182:185], v[214:217], v[52:55]
	v_mfma_f32_16x16x32_bf16 v[44:47], v[174:177], v[222:225], v[44:47]
	v_mfma_f32_16x16x32_bf16 v[36:39], v[182:185], v[222:225], v[36:39]
	v_mfma_f32_16x16x32_bf16 v[28:31], v[174:177], v[230:233], v[28:31]
	v_mfma_f32_16x16x32_bf16 v[20:23], v[182:185], v[230:233], v[20:23]
	v_mfma_f32_16x16x32_bf16 v[12:15], v[174:177], v[238:241], v[12:15]
	v_mfma_f32_16x16x32_bf16 v[4:7], v[182:185], v[238:241], v[4:7]
	v_mfma_f32_16x16x32_bf16 v[56:59], v[186:189], v[210:213], v[56:59]
	v_mfma_f32_16x16x32_bf16 v[48:51], v[194:197], v[210:213], v[48:51]
	v_mfma_f32_16x16x32_bf16 v[40:43], v[186:189], v[218:221], v[40:43]
	v_mfma_f32_16x16x32_bf16 v[32:35], v[194:197], v[218:221], v[32:35]
	v_mfma_f32_16x16x32_bf16 v[24:27], v[186:189], v[226:229], v[24:27]
	v_mfma_f32_16x16x32_bf16 v[16:19], v[194:197], v[226:229], v[16:19]
	v_mfma_f32_16x16x32_bf16 v[8:11], v[186:189], v[234:237], v[8:11]
	v_mfma_f32_16x16x32_bf16 v[0:3], v[194:197], v[234:237], v[0:3]
	v_mfma_f32_16x16x32_bf16 v[56:59], v[190:193], v[214:217], v[56:59]
	v_mfma_f32_16x16x32_bf16 v[48:51], v[198:201], v[214:217], v[48:51]
	v_mfma_f32_16x16x32_bf16 v[40:43], v[190:193], v[222:225], v[40:43]
	v_mfma_f32_16x16x32_bf16 v[32:35], v[198:201], v[222:225], v[32:35]
	v_mfma_f32_16x16x32_bf16 v[24:27], v[190:193], v[230:233], v[24:27]
	v_mfma_f32_16x16x32_bf16 v[16:19], v[198:201], v[230:233], v[16:19]
	v_mfma_f32_16x16x32_bf16 v[8:11], v[190:193], v[238:241], v[8:11]
	v_mfma_f32_16x16x32_bf16 v[0:3], v[198:201], v[238:241], v[0:3]
	s_barrier
	s_add_i32 s55, 0, 0x18000
	s_add_i32 s56, 0, 0x1c000
	v_add_u32_e32 v182, s55, v129
	v_add_u32_e32 v198, s56, v129
	ds_read_b128 v[170:173], v182
	ds_read_b128 v[174:177], v182 offset:1024
	ds_read_b128 v[178:181], v182 offset:2048
	ds_read_b128 v[182:185], v182 offset:3072
	ds_read_b128 v[186:189], v198
	ds_read_b128 v[190:193], v198 offset:1024
	ds_read_b128 v[194:197], v198 offset:2048
	ds_read_b128 v[198:201], v198 offset:3072
	s_add_u32 s28, s28, 0x40000
	s_addc_u32 s29, s29, 0
	s_mov_b32 m0, s39
	v_lshl_add_u64 v[206:207], s[28:29], 0, v[136:137]
	ds_read_b128 v[210:213], v169 offset:32768
	ds_read_b128 v[214:217], v169 offset:33792
	ds_read_b128 v[218:221], v169 offset:34816
	ds_read_b128 v[222:225], v169 offset:35840
	ds_read_b128 v[226:229], v169 offset:36864
	ds_read_b128 v[230:233], v169 offset:37888
	ds_read_b128 v[234:237], v169 offset:38912
	ds_read_b128 v[238:241], v169 offset:39936
	global_load_lds_dwordx4 v[206:207], off
	v_lshl_add_u64 v[206:207], s[28:29], 0, v[132:133]
	s_mov_b32 m0, s40
	s_nop 0
	global_load_lds_dwordx4 v[206:207], off
	s_waitcnt vmcnt(8)
	s_waitcnt lgkmcnt(0)
	s_barrier
	s_waitcnt lgkmcnt(0)
	v_mfma_f32_16x16x32_bf16 v[124:127], v[170:173], v[210:213], v[124:127]
	v_mfma_f32_16x16x32_bf16 v[116:119], v[178:181], v[210:213], v[116:119]
	v_mfma_f32_16x16x32_bf16 v[108:111], v[170:173], v[218:221], v[108:111]
	v_mfma_f32_16x16x32_bf16 v[100:103], v[178:181], v[218:221], v[100:103]
	v_mfma_f32_16x16x32_bf16 v[92:95], v[170:173], v[226:229], v[92:95]
	v_mfma_f32_16x16x32_bf16 v[84:87], v[178:181], v[226:229], v[84:87]
	v_mfma_f32_16x16x32_bf16 v[76:79], v[170:173], v[234:237], v[76:79]
	v_mfma_f32_16x16x32_bf16 v[68:71], v[178:181], v[234:237], v[68:71]
	v_mfma_f32_16x16x32_bf16 v[124:127], v[174:177], v[214:217], v[124:127]
	v_mfma_f32_16x16x32_bf16 v[116:119], v[182:185], v[214:217], v[116:119]
	v_mfma_f32_16x16x32_bf16 v[108:111], v[174:177], v[222:225], v[108:111]
	v_mfma_f32_16x16x32_bf16 v[100:103], v[182:185], v[222:225], v[100:103]
	v_mfma_f32_16x16x32_bf16 v[92:95], v[174:177], v[230:233], v[92:95]
	v_mfma_f32_16x16x32_bf16 v[84:87], v[182:185], v[230:233], v[84:87]
	v_mfma_f32_16x16x32_bf16 v[76:79], v[174:177], v[238:241], v[76:79]
	v_mfma_f32_16x16x32_bf16 v[68:71], v[182:185], v[238:241], v[68:71]
	v_mfma_f32_16x16x32_bf16 v[120:123], v[186:189], v[210:213], v[120:123]
	v_mfma_f32_16x16x32_bf16 v[112:115], v[194:197], v[210:213], v[112:115]
	v_mfma_f32_16x16x32_bf16 v[104:107], v[186:189], v[218:221], v[104:107]
	v_mfma_f32_16x16x32_bf16 v[96:99], v[194:197], v[218:221], v[96:99]
	v_mfma_f32_16x16x32_bf16 v[88:91], v[186:189], v[226:229], v[88:91]
	v_mfma_f32_16x16x32_bf16 v[80:83], v[194:197], v[226:229], v[80:83]
	v_mfma_f32_16x16x32_bf16 v[72:75], v[186:189], v[234:237], v[72:75]
	v_mfma_f32_16x16x32_bf16 v[64:67], v[194:197], v[234:237], v[64:67]
	v_mfma_f32_16x16x32_bf16 v[120:123], v[190:193], v[214:217], v[120:123]
	v_mfma_f32_16x16x32_bf16 v[112:115], v[198:201], v[214:217], v[112:115]
	v_mfma_f32_16x16x32_bf16 v[104:107], v[190:193], v[222:225], v[104:107]
	v_mfma_f32_16x16x32_bf16 v[96:99], v[198:201], v[222:225], v[96:99]
	v_mfma_f32_16x16x32_bf16 v[88:91], v[190:193], v[230:233], v[88:91]
	v_mfma_f32_16x16x32_bf16 v[80:83], v[198:201], v[230:233], v[80:83]
	v_mfma_f32_16x16x32_bf16 v[72:75], v[190:193], v[238:241], v[72:75]
	v_mfma_f32_16x16x32_bf16 v[64:67], v[198:201], v[238:241], v[64:67]
	s_barrier
	s_add_u32 s28, s26, 0x8000
	s_addc_u32 s29, s27, 0
	s_add_i32 s55, s55, s35
	v_lshl_add_u64 v[206:207], s[28:29], 0, v[134:135]
	s_mov_b32 m0, s55
	ds_read_b128 v[210:213], v169 offset:49152
	ds_read_b128 v[214:217], v169 offset:50176
	ds_read_b128 v[218:221], v169 offset:51200
	ds_read_b128 v[222:225], v169 offset:52224
	ds_read_b128 v[226:229], v169 offset:53248
	ds_read_b128 v[230:233], v169 offset:54272
	ds_read_b128 v[234:237], v169 offset:55296
	ds_read_b128 v[238:241], v169 offset:56320
	global_load_lds_dwordx4 v[206:207], off
	s_add_i32 m0, s55, 0x2000
	s_add_u32 s26, s26, 0xc000
	v_lshl_add_u64 v[206:207], s[28:29], 0, v[130:131]
	s_addc_u32 s27, s27, 0
	s_add_i32 s28, s56, s35
	global_load_lds_dwordx4 v[206:207], off
	v_lshl_add_u64 v[206:207], s[26:27], 0, v[134:135]
	s_mov_b32 m0, s28
	v_lshl_add_u64 v[164:165], v[164:165], 0, s[6:7]
	global_load_lds_dwordx4 v[206:207], off
	v_lshl_add_u64 v[206:207], s[26:27], 0, v[130:131]
	s_add_i32 m0, s28, 0x2000
	s_nop 0
	global_load_lds_dwordx4 v[206:207], off
	s_mov_b32 m0, s45
	s_nop 0
	global_load_lds_dwordx4 v[164:165], off
	v_lshl_add_u64 v[164:165], v[204:205], 0, s[6:7]
	s_mov_b32 m0, s46
	s_nop 0
	global_load_lds_dwordx4 v[164:165], off
	s_waitcnt vmcnt(8)
	s_waitcnt lgkmcnt(0)
	s_barrier
	s_waitcnt lgkmcnt(0)
	v_mfma_f32_16x16x32_bf16 v[60:63], v[170:173], v[210:213], v[60:63]
	v_mfma_f32_16x16x32_bf16 v[52:55], v[178:181], v[210:213], v[52:55]
	v_mfma_f32_16x16x32_bf16 v[44:47], v[170:173], v[218:221], v[44:47]
	v_mfma_f32_16x16x32_bf16 v[36:39], v[178:181], v[218:221], v[36:39]
	v_mfma_f32_16x16x32_bf16 v[28:31], v[170:173], v[226:229], v[28:31]
	v_mfma_f32_16x16x32_bf16 v[20:23], v[178:181], v[226:229], v[20:23]
	v_mfma_f32_16x16x32_bf16 v[12:15], v[170:173], v[234:237], v[12:15]
	v_mfma_f32_16x16x32_bf16 v[4:7], v[178:181], v[234:237], v[4:7]
	v_mfma_f32_16x16x32_bf16 v[60:63], v[174:177], v[214:217], v[60:63]
	v_mfma_f32_16x16x32_bf16 v[52:55], v[182:185], v[214:217], v[52:55]
	v_mfma_f32_16x16x32_bf16 v[44:47], v[174:177], v[222:225], v[44:47]
	v_mfma_f32_16x16x32_bf16 v[36:39], v[182:185], v[222:225], v[36:39]
	v_mfma_f32_16x16x32_bf16 v[28:31], v[174:177], v[230:233], v[28:31]
	v_mfma_f32_16x16x32_bf16 v[20:23], v[182:185], v[230:233], v[20:23]
	v_mfma_f32_16x16x32_bf16 v[12:15], v[174:177], v[238:241], v[12:15]
	v_mfma_f32_16x16x32_bf16 v[4:7], v[182:185], v[238:241], v[4:7]
	v_mfma_f32_16x16x32_bf16 v[56:59], v[186:189], v[210:213], v[56:59]
	v_mfma_f32_16x16x32_bf16 v[48:51], v[194:197], v[210:213], v[48:51]
	v_mfma_f32_16x16x32_bf16 v[40:43], v[186:189], v[218:221], v[40:43]
	v_mfma_f32_16x16x32_bf16 v[32:35], v[194:197], v[218:221], v[32:35]
	v_mfma_f32_16x16x32_bf16 v[24:27], v[186:189], v[226:229], v[24:27]
	v_mfma_f32_16x16x32_bf16 v[16:19], v[194:197], v[226:229], v[16:19]
	v_mfma_f32_16x16x32_bf16 v[8:11], v[186:189], v[234:237], v[8:11]
	v_mfma_f32_16x16x32_bf16 v[0:3], v[194:197], v[234:237], v[0:3]
	v_mfma_f32_16x16x32_bf16 v[56:59], v[190:193], v[214:217], v[56:59]
	v_mfma_f32_16x16x32_bf16 v[48:51], v[198:201], v[214:217], v[48:51]
	v_mfma_f32_16x16x32_bf16 v[40:43], v[190:193], v[222:225], v[40:43]
	v_mfma_f32_16x16x32_bf16 v[32:35], v[198:201], v[222:225], v[32:35]
	v_mfma_f32_16x16x32_bf16 v[24:27], v[190:193], v[230:233], v[24:27]
	v_mfma_f32_16x16x32_bf16 v[16:19], v[198:201], v[230:233], v[16:19]
	v_mfma_f32_16x16x32_bf16 v[8:11], v[190:193], v[238:241], v[8:11]
	v_mfma_f32_16x16x32_bf16 v[0:3], v[198:201], v[238:241], v[0:3]
	s_barrier
	s_add_i32 s54, s54, 2
	s_add_u32 s52, s52, 0x10000
	s_addc_u32 s53, s53, 0
	s_add_u32 s24, s24, 0x100
	s_addc_u32 s25, s25, 0
	s_cmp_gt_u32 s54, 13
	s_cbranch_scc0 .LBB0_1253
	s_and_b64 vcc, exec, s[8:9]
	s_cbranch_vccz .LBB0_1256
	s_barrier

.LBB0_1481:
	v_add_u32_e32 v168, s61, v182
	v_add_u32_e32 v204, s62, v182
	ds_read_b128 v[156:159], v168
	ds_read_b128 v[160:163], v168 offset:1024
	ds_read_b128 v[164:167], v168 offset:2048
	ds_read_b128 v[168:171], v168 offset:3072
	ds_read_b128 v[172:175], v204
	ds_read_b128 v[176:179], v204 offset:1024
	ds_read_b128 v[212:215], v204 offset:2048
	ds_read_b128 v[216:219], v204 offset:3072
	s_add_u32 s38, s36, 0x4000
	s_addc_u32 s39, s37, 0
	s_cmp_eq_u32 s70, 40
	s_cselect_b32 s42, s0, s38
	s_cselect_b32 s43, s1, s39
	s_cselect_b32 s40, s34, s68
	s_cselect_b32 s41, s35, s69
	s_add_u32 s38, s42, 0x8000
	s_addc_u32 s39, s43, 0
	v_lshl_add_u64 v[204:205], s[36:37], 0, v[150:151]
	s_add_i32 m0, s48, 0xc000
	ds_read_b128 v[220:223], v199
	ds_read_b128 v[224:227], v199 offset:1024
	ds_read_b128 v[228:231], v199 offset:2048
	ds_read_b128 v[232:235], v199 offset:3072
	ds_read_b128 v[236:239], v199 offset:4096
	ds_read_b128 v[240:243], v199 offset:5120
	ds_read_b128 v[244:247], v199 offset:6144
	ds_read_b128 v[248:251], v199 offset:7168
	global_load_lds_dwordx4 v[204:205], off
	v_lshl_add_u64 v[204:205], s[36:37], 0, v[148:149]
	s_add_i32 m0, s48, 0xe000
	s_nop 0
	global_load_lds_dwordx4 v[204:205], off
	s_waitcnt vmcnt(8)
	s_waitcnt lgkmcnt(0)
	s_barrier
	s_waitcnt lgkmcnt(0)
	v_mfma_f32_16x16x32_bf16 v[124:127], v[156:159], v[220:223], v[124:127]
	v_mfma_f32_16x16x32_bf16 v[120:123], v[164:167], v[220:223], v[120:123]
	v_mfma_f32_16x16x32_bf16 v[116:119], v[156:159], v[228:231], v[116:119]
	v_mfma_f32_16x16x32_bf16 v[112:115], v[164:167], v[228:231], v[112:115]
	v_mfma_f32_16x16x32_bf16 v[92:95], v[156:159], v[236:239], v[92:95]
	v_mfma_f32_16x16x32_bf16 v[88:91], v[164:167], v[236:239], v[88:91]
	v_mfma_f32_16x16x32_bf16 v[84:87], v[156:159], v[244:247], v[84:87]
	v_mfma_f32_16x16x32_bf16 v[80:83], v[164:167], v[244:247], v[80:83]
	v_mfma_f32_16x16x32_bf16 v[124:127], v[160:163], v[224:227], v[124:127]
	v_mfma_f32_16x16x32_bf16 v[120:123], v[168:171], v[224:227], v[120:123]
	v_mfma_f32_16x16x32_bf16 v[116:119], v[160:163], v[232:235], v[116:119]
	v_mfma_f32_16x16x32_bf16 v[112:115], v[168:171], v[232:235], v[112:115]
	v_mfma_f32_16x16x32_bf16 v[92:95], v[160:163], v[240:243], v[92:95]
	v_mfma_f32_16x16x32_bf16 v[88:91], v[168:171], v[240:243], v[88:91]
	v_mfma_f32_16x16x32_bf16 v[84:87], v[160:163], v[248:251], v[84:87]
	v_mfma_f32_16x16x32_bf16 v[80:83], v[168:171], v[248:251], v[80:83]
	v_mfma_f32_16x16x32_bf16 v[108:111], v[172:175], v[220:223], v[108:111]
	v_mfma_f32_16x16x32_bf16 v[104:107], v[212:215], v[220:223], v[104:107]
	v_mfma_f32_16x16x32_bf16 v[100:103], v[172:175], v[228:231], v[100:103]
	v_mfma_f32_16x16x32_bf16 v[96:99], v[212:215], v[228:231], v[96:99]
	v_mfma_f32_16x16x32_bf16 v[76:79], v[172:175], v[236:239], v[76:79]
	v_mfma_f32_16x16x32_bf16 v[72:75], v[212:215], v[236:239], v[72:75]
	v_mfma_f32_16x16x32_bf16 v[68:71], v[172:175], v[244:247], v[68:71]
	v_mfma_f32_16x16x32_bf16 v[64:67], v[212:215], v[244:247], v[64:67]
	v_mfma_f32_16x16x32_bf16 v[108:111], v[176:179], v[224:227], v[108:111]
	v_mfma_f32_16x16x32_bf16 v[104:107], v[216:219], v[224:227], v[104:107]
	v_mfma_f32_16x16x32_bf16 v[100:103], v[176:179], v[232:235], v[100:103]
	v_mfma_f32_16x16x32_bf16 v[96:99], v[216:219], v[232:235], v[96:99]
	v_mfma_f32_16x16x32_bf16 v[76:79], v[176:179], v[240:243], v[76:79]
	v_mfma_f32_16x16x32_bf16 v[72:75], v[216:219], v[240:243], v[72:75]
	v_mfma_f32_16x16x32_bf16 v[68:71], v[176:179], v[248:251], v[68:71]
	v_mfma_f32_16x16x32_bf16 v[64:67], v[216:219], v[248:251], v[64:67]
	s_barrier
	s_add_i32 s71, s61, s47
	v_lshl_add_u64 v[204:205], s[40:41], 0, v[128:129]
	s_mov_b32 m0, s71
	ds_read_b128 v[220:223], v199 offset:16384
	ds_read_b128 v[224:227], v199 offset:17408
	ds_read_b128 v[228:231], v199 offset:18432
	ds_read_b128 v[232:235], v199 offset:19456
	ds_read_b128 v[236:239], v199 offset:20480
	ds_read_b128 v[240:243], v199 offset:21504
	ds_read_b128 v[244:247], v199 offset:22528
	ds_read_b128 v[248:251], v199 offset:23552
	global_load_lds_dwordx4 v[204:205], off
	s_add_i32 m0, s71, 0x2000
	s_add_u32 s72, s40, 0x4000
	v_lshl_add_u64 v[204:205], s[40:41], 0, v[130:131]
	s_addc_u32 s73, s41, 0
	s_add_i32 s71, s62, s47
	global_load_lds_dwordx4 v[204:205], off
	v_lshl_add_u64 v[204:205], s[72:73], 0, v[128:129]
	s_mov_b32 m0, s71
	s_nop 0
	global_load_lds_dwordx4 v[204:205], off
	v_lshl_add_u64 v[204:205], s[72:73], 0, v[130:131]
	s_add_i32 m0, s71, 0x2000
	s_nop 0
	global_load_lds_dwordx4 v[204:205], off
	v_lshl_add_u64 v[204:205], s[42:43], 0, v[128:129]
	s_mov_b32 m0, s48
	s_nop 0
	global_load_lds_dwordx4 v[204:205], off
	v_lshl_add_u64 v[204:205], s[42:43], 0, v[130:131]
	s_mov_b32 m0, s49
	s_nop 0
	global_load_lds_dwordx4 v[204:205], off
	s_waitcnt vmcnt(8)
	s_waitcnt lgkmcnt(0)
	s_barrier
	s_waitcnt lgkmcnt(0)
	v_mfma_f32_16x16x32_bf16 v[60:63], v[156:159], v[220:223], v[60:63]
	v_mfma_f32_16x16x32_bf16 v[56:59], v[164:167], v[220:223], v[56:59]
	v_mfma_f32_16x16x32_bf16 v[52:55], v[156:159], v[228:231], v[52:55]
	v_mfma_f32_16x16x32_bf16 v[48:51], v[164:167], v[228:231], v[48:51]
	v_mfma_f32_16x16x32_bf16 v[28:31], v[156:159], v[236:239], v[28:31]
	v_mfma_f32_16x16x32_bf16 v[24:27], v[164:167], v[236:239], v[24:27]
	v_mfma_f32_16x16x32_bf16 v[20:23], v[156:159], v[244:247], v[20:23]
	v_mfma_f32_16x16x32_bf16 v[12:15], v[164:167], v[244:247], v[12:15]
	v_mfma_f32_16x16x32_bf16 v[60:63], v[160:163], v[224:227], v[60:63]
	v_mfma_f32_16x16x32_bf16 v[56:59], v[168:171], v[224:227], v[56:59]
	v_mfma_f32_16x16x32_bf16 v[52:55], v[160:163], v[232:235], v[52:55]
	v_mfma_f32_16x16x32_bf16 v[48:51], v[168:171], v[232:235], v[48:51]
	v_mfma_f32_16x16x32_bf16 v[28:31], v[160:163], v[240:243], v[28:31]
	v_mfma_f32_16x16x32_bf16 v[24:27], v[168:171], v[240:243], v[24:27]
	v_mfma_f32_16x16x32_bf16 v[20:23], v[160:163], v[248:251], v[20:23]
	v_mfma_f32_16x16x32_bf16 v[12:15], v[168:171], v[248:251], v[12:15]
	v_mfma_f32_16x16x32_bf16 v[44:47], v[172:175], v[220:223], v[44:47]
	v_mfma_f32_16x16x32_bf16 v[40:43], v[212:215], v[220:223], v[40:43]
	v_mfma_f32_16x16x32_bf16 v[36:39], v[172:175], v[228:231], v[36:39]
	v_mfma_f32_16x16x32_bf16 v[32:35], v[212:215], v[228:231], v[32:35]
	v_mfma_f32_16x16x32_bf16 v[16:19], v[172:175], v[236:239], v[16:19]
	v_mfma_f32_16x16x32_bf16 v[8:11], v[212:215], v[236:239], v[8:11]
	v_mfma_f32_16x16x32_bf16 v[4:7], v[172:175], v[244:247], v[4:7]
	v_mfma_f32_16x16x32_bf16 v[0:3], v[212:215], v[244:247], v[0:3]
	v_mfma_f32_16x16x32_bf16 v[44:47], v[176:179], v[224:227], v[44:47]
	v_mfma_f32_16x16x32_bf16 v[40:43], v[216:219], v[224:227], v[40:43]
	v_mfma_f32_16x16x32_bf16 v[36:39], v[176:179], v[232:235], v[36:39]
	v_mfma_f32_16x16x32_bf16 v[32:35], v[216:219], v[232:235], v[32:35]
	v_mfma_f32_16x16x32_bf16 v[16:19], v[176:179], v[240:243], v[16:19]
	v_mfma_f32_16x16x32_bf16 v[8:11], v[216:219], v[240:243], v[8:11]
	v_mfma_f32_16x16x32_bf16 v[4:7], v[176:179], v[248:251], v[4:7]
	v_mfma_f32_16x16x32_bf16 v[0:3], v[216:219], v[248:251], v[0:3]
	s_barrier
	s_add_i32 s71, 0, 0x18000
	s_add_i32 s72, 0, 0x1c000
	v_add_u32_e32 v168, s71, v182
	v_add_u32_e32 v204, s72, v182
	ds_read_b128 v[156:159], v168
	ds_read_b128 v[160:163], v168 offset:1024
	ds_read_b128 v[164:167], v168 offset:2048
	ds_read_b128 v[168:171], v168 offset:3072
	ds_read_b128 v[172:175], v204
	ds_read_b128 v[176:179], v204 offset:1024
	ds_read_b128 v[212:215], v204 offset:2048
	ds_read_b128 v[216:219], v204 offset:3072
	s_add_u32 s42, s42, 0x4000
	s_addc_u32 s43, s43, 0
	s_mov_b32 m0, s50
	v_lshl_add_u64 v[204:205], s[42:43], 0, v[128:129]
	ds_read_b128 v[220:223], v199 offset:32768
	ds_read_b128 v[224:227], v199 offset:33792
	ds_read_b128 v[228:231], v199 offset:34816
	ds_read_b128 v[232:235], v199 offset:35840
	ds_read_b128 v[236:239], v199 offset:36864
	ds_read_b128 v[240:243], v199 offset:37888
	ds_read_b128 v[244:247], v199 offset:38912
	ds_read_b128 v[248:251], v199 offset:39936
	global_load_lds_dwordx4 v[204:205], off
	v_lshl_add_u64 v[204:205], s[42:43], 0, v[130:131]
	s_mov_b32 m0, s51
	s_nop 0
	global_load_lds_dwordx4 v[204:205], off
	s_waitcnt vmcnt(8)
	s_waitcnt lgkmcnt(0)
	s_barrier
	s_waitcnt lgkmcnt(0)
	v_mfma_f32_16x16x32_bf16 v[124:127], v[156:159], v[220:223], v[124:127]
	v_mfma_f32_16x16x32_bf16 v[120:123], v[164:167], v[220:223], v[120:123]
	v_mfma_f32_16x16x32_bf16 v[116:119], v[156:159], v[228:231], v[116:119]
	v_mfma_f32_16x16x32_bf16 v[112:115], v[164:167], v[228:231], v[112:115]
	v_mfma_f32_16x16x32_bf16 v[92:95], v[156:159], v[236:239], v[92:95]
	v_mfma_f32_16x16x32_bf16 v[88:91], v[164:167], v[236:239], v[88:91]
	v_mfma_f32_16x16x32_bf16 v[84:87], v[156:159], v[244:247], v[84:87]
	v_mfma_f32_16x16x32_bf16 v[80:83], v[164:167], v[244:247], v[80:83]
	v_mfma_f32_16x16x32_bf16 v[124:127], v[160:163], v[224:227], v[124:127]
	v_mfma_f32_16x16x32_bf16 v[120:123], v[168:171], v[224:227], v[120:123]
	v_mfma_f32_16x16x32_bf16 v[116:119], v[160:163], v[232:235], v[116:119]
	v_mfma_f32_16x16x32_bf16 v[112:115], v[168:171], v[232:235], v[112:115]
	v_mfma_f32_16x16x32_bf16 v[92:95], v[160:163], v[240:243], v[92:95]
	v_mfma_f32_16x16x32_bf16 v[88:91], v[168:171], v[240:243], v[88:91]
	v_mfma_f32_16x16x32_bf16 v[84:87], v[160:163], v[248:251], v[84:87]
	v_mfma_f32_16x16x32_bf16 v[80:83], v[168:171], v[248:251], v[80:83]
	v_mfma_f32_16x16x32_bf16 v[108:111], v[172:175], v[220:223], v[108:111]
	v_mfma_f32_16x16x32_bf16 v[104:107], v[212:215], v[220:223], v[104:107]
	v_mfma_f32_16x16x32_bf16 v[100:103], v[172:175], v[228:231], v[100:103]
	v_mfma_f32_16x16x32_bf16 v[96:99], v[212:215], v[228:231], v[96:99]
	v_mfma_f32_16x16x32_bf16 v[76:79], v[172:175], v[236:239], v[76:79]
	v_mfma_f32_16x16x32_bf16 v[72:75], v[212:215], v[236:239], v[72:75]
	v_mfma_f32_16x16x32_bf16 v[68:71], v[172:175], v[244:247], v[68:71]
	v_mfma_f32_16x16x32_bf16 v[64:67], v[212:215], v[244:247], v[64:67]
	v_mfma_f32_16x16x32_bf16 v[108:111], v[176:179], v[224:227], v[108:111]
	v_mfma_f32_16x16x32_bf16 v[104:107], v[216:219], v[224:227], v[104:107]
	v_mfma_f32_16x16x32_bf16 v[100:103], v[176:179], v[232:235], v[100:103]
	v_mfma_f32_16x16x32_bf16 v[96:99], v[216:219], v[232:235], v[96:99]
	v_mfma_f32_16x16x32_bf16 v[76:79], v[176:179], v[240:243], v[76:79]
	v_mfma_f32_16x16x32_bf16 v[72:75], v[216:219], v[240:243], v[72:75]
	v_mfma_f32_16x16x32_bf16 v[68:71], v[176:179], v[248:251], v[68:71]
	v_mfma_f32_16x16x32_bf16 v[64:67], v[216:219], v[248:251], v[64:67]
	s_barrier
	s_add_u32 s42, s40, 0x8000
	s_addc_u32 s43, s41, 0
	s_add_i32 s71, s71, s47
	v_lshl_add_u64 v[204:205], s[42:43], 0, v[128:129]
	s_mov_b32 m0, s71
	ds_read_b128 v[220:223], v199 offset:49152
	ds_read_b128 v[224:227], v199 offset:50176
	ds_read_b128 v[228:231], v199 offset:51200
	ds_read_b128 v[232:235], v199 offset:52224
	ds_read_b128 v[236:239], v199 offset:53248
	ds_read_b128 v[240:243], v199 offset:54272
	ds_read_b128 v[244:247], v199 offset:55296
	ds_read_b128 v[248:251], v199 offset:56320
	global_load_lds_dwordx4 v[204:205], off
	s_add_i32 m0, s71, 0x2000
	s_add_u32 s40, s40, 0xc000
	v_lshl_add_u64 v[204:205], s[42:43], 0, v[130:131]
	s_addc_u32 s41, s41, 0
	s_add_i32 s42, s72, s47
	global_load_lds_dwordx4 v[204:205], off
	v_lshl_add_u64 v[204:205], s[40:41], 0, v[128:129]
	s_mov_b32 m0, s42
	s_nop 0
	global_load_lds_dwordx4 v[204:205], off
	v_lshl_add_u64 v[204:205], s[40:41], 0, v[130:131]
	s_add_i32 m0, s42, 0x2000
	s_nop 0
	global_load_lds_dwordx4 v[204:205], off
	v_lshl_add_u64 v[204:205], s[38:39], 0, v[128:129]
	s_mov_b32 m0, s57
	s_nop 0
	global_load_lds_dwordx4 v[204:205], off
	v_lshl_add_u64 v[204:205], s[38:39], 0, v[130:131]
	s_mov_b32 m0, s58
	s_nop 0
	global_load_lds_dwordx4 v[204:205], off
	s_waitcnt vmcnt(8)
	s_waitcnt lgkmcnt(0)
	s_barrier
	s_waitcnt lgkmcnt(0)
	v_mfma_f32_16x16x32_bf16 v[60:63], v[156:159], v[220:223], v[60:63]
	v_mfma_f32_16x16x32_bf16 v[56:59], v[164:167], v[220:223], v[56:59]
	v_mfma_f32_16x16x32_bf16 v[52:55], v[156:159], v[228:231], v[52:55]
	v_mfma_f32_16x16x32_bf16 v[48:51], v[164:167], v[228:231], v[48:51]
	v_mfma_f32_16x16x32_bf16 v[28:31], v[156:159], v[236:239], v[28:31]
	v_mfma_f32_16x16x32_bf16 v[24:27], v[164:167], v[236:239], v[24:27]
	v_mfma_f32_16x16x32_bf16 v[20:23], v[156:159], v[244:247], v[20:23]
	v_mfma_f32_16x16x32_bf16 v[12:15], v[164:167], v[244:247], v[12:15]
	v_mfma_f32_16x16x32_bf16 v[60:63], v[160:163], v[224:227], v[60:63]
	v_mfma_f32_16x16x32_bf16 v[56:59], v[168:171], v[224:227], v[56:59]
	v_mfma_f32_16x16x32_bf16 v[52:55], v[160:163], v[232:235], v[52:55]
	v_mfma_f32_16x16x32_bf16 v[48:51], v[168:171], v[232:235], v[48:51]
	v_mfma_f32_16x16x32_bf16 v[28:31], v[160:163], v[240:243], v[28:31]
	v_mfma_f32_16x16x32_bf16 v[24:27], v[168:171], v[240:243], v[24:27]
	v_mfma_f32_16x16x32_bf16 v[20:23], v[160:163], v[248:251], v[20:23]
	v_mfma_f32_16x16x32_bf16 v[12:15], v[168:171], v[248:251], v[12:15]
	v_mfma_f32_16x16x32_bf16 v[44:47], v[172:175], v[220:223], v[44:47]
	v_mfma_f32_16x16x32_bf16 v[40:43], v[212:215], v[220:223], v[40:43]
	v_mfma_f32_16x16x32_bf16 v[36:39], v[172:175], v[228:231], v[36:39]
	v_mfma_f32_16x16x32_bf16 v[32:35], v[212:215], v[228:231], v[32:35]
	v_mfma_f32_16x16x32_bf16 v[16:19], v[172:175], v[236:239], v[16:19]
	v_mfma_f32_16x16x32_bf16 v[8:11], v[212:215], v[236:239], v[8:11]
	v_mfma_f32_16x16x32_bf16 v[4:7], v[172:175], v[244:247], v[4:7]
	v_mfma_f32_16x16x32_bf16 v[0:3], v[212:215], v[244:247], v[0:3]
	v_mfma_f32_16x16x32_bf16 v[44:47], v[176:179], v[224:227], v[44:47]
	v_mfma_f32_16x16x32_bf16 v[40:43], v[216:219], v[224:227], v[40:43]
	v_mfma_f32_16x16x32_bf16 v[36:39], v[176:179], v[232:235], v[36:39]
	v_mfma_f32_16x16x32_bf16 v[32:35], v[216:219], v[232:235], v[32:35]
	v_mfma_f32_16x16x32_bf16 v[16:19], v[176:179], v[240:243], v[16:19]
	v_mfma_f32_16x16x32_bf16 v[8:11], v[216:219], v[240:243], v[8:11]
	v_mfma_f32_16x16x32_bf16 v[4:7], v[176:179], v[248:251], v[4:7]
	v_mfma_f32_16x16x32_bf16 v[0:3], v[216:219], v[248:251], v[0:3]
	s_barrier
	s_add_i32 s70, s70, 2
	s_add_u32 s68, s68, 0x10000
	s_addc_u32 s69, s69, 0
	s_add_u32 s36, s36, 0x10000
	s_addc_u32 s37, s37, 0
	s_cmp_gt_u32 s70, 41
	s_cbranch_scc0 .LBB0_1481
	s_and_b64 vcc, exec, s[18:19]
	s_cbranch_vccz .LBB0_1484
	s_barrier

.LBB0_1563:
	ds_read_b128 v[168:171], v165
	ds_read_b128 v[172:175], v165 offset:1024
	ds_read_b128 v[176:179], v165 offset:2048
	ds_read_b128 v[180:183], v165 offset:3072
	ds_read_b128 v[184:187], v166
	ds_read_b128 v[188:191], v166 offset:1024
	ds_read_b128 v[192:195], v166 offset:2048
	ds_read_b128 v[196:199], v166 offset:3072
	s_add_u32 s22, s20, 0xfffc0080
	s_addc_u32 s23, s21, -1
	s_cmp_eq_u32 s49, 12
	s_cselect_b32 s25, s9, s23
	s_cselect_b32 s24, s45, s22
	s_cselect_b32 s23, s11, s48
	s_cselect_b32 s22, s46, s47
	v_lshl_add_u64 v[162:163], s[20:21], 0, v[156:157]
	s_add_i32 m0, s17, 0xc000
	ds_read_b128 v[210:213], v167
	ds_read_b128 v[214:217], v167 offset:1024
	ds_read_b128 v[218:221], v167 offset:2048
	ds_read_b128 v[222:225], v167 offset:3072
	ds_read_b128 v[226:229], v167 offset:4096
	ds_read_b128 v[230:233], v167 offset:5120
	ds_read_b128 v[234:237], v167 offset:6144
	ds_read_b128 v[238:241], v167 offset:7168
	global_load_lds_dwordx4 v[162:163], off
	v_lshl_add_u64 v[162:163], s[20:21], 0, v[154:155]
	s_add_i32 m0, s17, 0xe000
	s_nop 0
	global_load_lds_dwordx4 v[162:163], off
	s_waitcnt vmcnt(8)
	s_waitcnt lgkmcnt(0)
	s_barrier
	s_waitcnt lgkmcnt(0)
	v_mfma_f32_16x16x32_bf16 v[124:127], v[168:171], v[210:213], v[124:127]
	v_mfma_f32_16x16x32_bf16 v[116:119], v[176:179], v[210:213], v[116:119]
	v_mfma_f32_16x16x32_bf16 v[108:111], v[168:171], v[218:221], v[108:111]
	v_mfma_f32_16x16x32_bf16 v[100:103], v[176:179], v[218:221], v[100:103]
	v_mfma_f32_16x16x32_bf16 v[92:95], v[168:171], v[226:229], v[92:95]
	v_mfma_f32_16x16x32_bf16 v[84:87], v[176:179], v[226:229], v[84:87]
	v_mfma_f32_16x16x32_bf16 v[76:79], v[168:171], v[234:237], v[76:79]
	v_mfma_f32_16x16x32_bf16 v[68:71], v[176:179], v[234:237], v[68:71]
	v_mfma_f32_16x16x32_bf16 v[124:127], v[172:175], v[214:217], v[124:127]
	v_mfma_f32_16x16x32_bf16 v[116:119], v[180:183], v[214:217], v[116:119]
	v_mfma_f32_16x16x32_bf16 v[108:111], v[172:175], v[222:225], v[108:111]
	v_mfma_f32_16x16x32_bf16 v[100:103], v[180:183], v[222:225], v[100:103]
	v_mfma_f32_16x16x32_bf16 v[92:95], v[172:175], v[230:233], v[92:95]
	v_mfma_f32_16x16x32_bf16 v[84:87], v[180:183], v[230:233], v[84:87]
	v_mfma_f32_16x16x32_bf16 v[76:79], v[172:175], v[238:241], v[76:79]
	v_mfma_f32_16x16x32_bf16 v[68:71], v[180:183], v[238:241], v[68:71]
	v_mfma_f32_16x16x32_bf16 v[120:123], v[184:187], v[210:213], v[120:123]
	v_mfma_f32_16x16x32_bf16 v[112:115], v[192:195], v[210:213], v[112:115]
	v_mfma_f32_16x16x32_bf16 v[104:107], v[184:187], v[218:221], v[104:107]
	v_mfma_f32_16x16x32_bf16 v[96:99], v[192:195], v[218:221], v[96:99]
	v_mfma_f32_16x16x32_bf16 v[88:91], v[184:187], v[226:229], v[88:91]
	v_mfma_f32_16x16x32_bf16 v[80:83], v[192:195], v[226:229], v[80:83]
	v_mfma_f32_16x16x32_bf16 v[72:75], v[184:187], v[234:237], v[72:75]
	v_mfma_f32_16x16x32_bf16 v[64:67], v[192:195], v[234:237], v[64:67]
	v_mfma_f32_16x16x32_bf16 v[120:123], v[188:191], v[214:217], v[120:123]
	v_mfma_f32_16x16x32_bf16 v[112:115], v[196:199], v[214:217], v[112:115]
	v_mfma_f32_16x16x32_bf16 v[104:107], v[188:191], v[222:225], v[104:107]
	v_mfma_f32_16x16x32_bf16 v[96:99], v[196:199], v[222:225], v[96:99]
	v_mfma_f32_16x16x32_bf16 v[88:91], v[188:191], v[230:233], v[88:91]
	v_mfma_f32_16x16x32_bf16 v[80:83], v[196:199], v[230:233], v[80:83]
	v_mfma_f32_16x16x32_bf16 v[72:75], v[188:191], v[238:241], v[72:75]
	v_mfma_f32_16x16x32_bf16 v[64:67], v[196:199], v[238:241], v[64:67]
	s_barrier
	s_add_i32 s50, s43, s33
	v_lshl_add_u64 v[162:163], s[22:23], 0, v[132:133]
	s_mov_b32 m0, s50
	s_cmp_lg_u32 s54, 0
	s_cbranch_scc1 .Lts0_skip1
	ds_read_b128 v[210:213], v167 offset:16384
	ds_read_b128 v[214:217], v167 offset:17408
	ds_read_b128 v[218:221], v167 offset:18432
	ds_read_b128 v[222:225], v167 offset:19456
	ds_read_b128 v[226:229], v167 offset:20480
	ds_read_b128 v[230:233], v167 offset:21504
	ds_read_b128 v[234:237], v167 offset:22528
	ds_read_b128 v[238:241], v167 offset:23552
.Lts0_skip1:
	global_load_lds_dwordx4 v[162:163], off
	s_add_i32 m0, s50, 0x2000
	s_add_u32 s50, s22, 0x4000
	v_lshl_add_u64 v[162:163], s[22:23], 0, v[128:129]
	s_addc_u32 s51, s23, 0
	s_add_i32 s52, s44, s33
	global_load_lds_dwordx4 v[162:163], off
	v_lshl_add_u64 v[162:163], s[50:51], 0, v[132:133]
	s_mov_b32 m0, s52
	v_lshl_add_u64 v[200:201], s[24:25], 0, v[130:131]
	global_load_lds_dwordx4 v[162:163], off
	v_lshl_add_u64 v[162:163], s[50:51], 0, v[128:129]
	s_add_i32 m0, s52, 0x2000
	s_nop 0
	global_load_lds_dwordx4 v[162:163], off
	v_lshl_add_u64 v[162:163], s[24:25], 0, v[134:135]
	s_mov_b32 m0, s17
	s_nop 0
	global_load_lds_dwordx4 v[162:163], off
	s_mov_b32 m0, s19
	s_nop 0
	global_load_lds_dwordx4 v[200:201], off
	s_waitcnt vmcnt(8)
	s_waitcnt lgkmcnt(0)
	s_barrier
	s_cmp_lg_u32 s54, 0
	s_cbranch_scc1 .Lts0_skip0
	s_waitcnt lgkmcnt(0)
	v_mfma_f32_16x16x32_bf16 v[60:63], v[168:171], v[210:213], v[60:63]
	v_mfma_f32_16x16x32_bf16 v[52:55], v[176:179], v[210:213], v[52:55]
	v_mfma_f32_16x16x32_bf16 v[44:47], v[168:171], v[218:221], v[44:47]
	v_mfma_f32_16x16x32_bf16 v[36:39], v[176:179], v[218:221], v[36:39]
	v_mfma_f32_16x16x32_bf16 v[28:31], v[168:171], v[226:229], v[28:31]
	v_mfma_f32_16x16x32_bf16 v[20:23], v[176:179], v[226:229], v[20:23]
	v_mfma_f32_16x16x32_bf16 v[12:15], v[168:171], v[234:237], v[12:15]
	v_mfma_f32_16x16x32_bf16 v[4:7], v[176:179], v[234:237], v[4:7]
	v_mfma_f32_16x16x32_bf16 v[60:63], v[172:175], v[214:217], v[60:63]
	v_mfma_f32_16x16x32_bf16 v[52:55], v[180:183], v[214:217], v[52:55]
	v_mfma_f32_16x16x32_bf16 v[44:47], v[172:175], v[222:225], v[44:47]
	v_mfma_f32_16x16x32_bf16 v[36:39], v[180:183], v[222:225], v[36:39]
	v_mfma_f32_16x16x32_bf16 v[28:31], v[172:175], v[230:233], v[28:31]
	v_mfma_f32_16x16x32_bf16 v[20:23], v[180:183], v[230:233], v[20:23]
	v_mfma_f32_16x16x32_bf16 v[12:15], v[172:175], v[238:241], v[12:15]
	v_mfma_f32_16x16x32_bf16 v[4:7], v[180:183], v[238:241], v[4:7]
	v_mfma_f32_16x16x32_bf16 v[56:59], v[184:187], v[210:213], v[56:59]
	v_mfma_f32_16x16x32_bf16 v[48:51], v[192:195], v[210:213], v[48:51]
	v_mfma_f32_16x16x32_bf16 v[40:43], v[184:187], v[218:221], v[40:43]
	v_mfma_f32_16x16x32_bf16 v[32:35], v[192:195], v[218:221], v[32:35]
	v_mfma_f32_16x16x32_bf16 v[24:27], v[184:187], v[226:229], v[24:27]
	v_mfma_f32_16x16x32_bf16 v[16:19], v[192:195], v[226:229], v[16:19]
	v_mfma_f32_16x16x32_bf16 v[8:11], v[184:187], v[234:237], v[8:11]
	v_mfma_f32_16x16x32_bf16 v[0:3], v[192:195], v[234:237], v[0:3]
	v_mfma_f32_16x16x32_bf16 v[56:59], v[188:191], v[214:217], v[56:59]
	v_mfma_f32_16x16x32_bf16 v[48:51], v[196:199], v[214:217], v[48:51]
	v_mfma_f32_16x16x32_bf16 v[40:43], v[188:191], v[222:225], v[40:43]
	v_mfma_f32_16x16x32_bf16 v[32:35], v[196:199], v[222:225], v[32:35]
	v_mfma_f32_16x16x32_bf16 v[24:27], v[188:191], v[230:233], v[24:27]
	v_mfma_f32_16x16x32_bf16 v[16:19], v[196:199], v[230:233], v[16:19]
	v_mfma_f32_16x16x32_bf16 v[8:11], v[188:191], v[238:241], v[8:11]
	v_mfma_f32_16x16x32_bf16 v[0:3], v[196:199], v[238:241], v[0:3]
.Lts0_skip0:
	s_barrier
	s_add_i32 s50, 0, 0x18000
	s_add_i32 s51, 0, 0x1c000
	v_add_u32_e32 v180, s50, v164
	v_add_u32_e32 v196, s51, v164
	ds_read_b128 v[168:171], v180
	ds_read_b128 v[172:175], v180 offset:1024
	ds_read_b128 v[176:179], v180 offset:2048
	ds_read_b128 v[180:183], v180 offset:3072
	ds_read_b128 v[184:187], v196
	ds_read_b128 v[188:191], v196 offset:1024
	ds_read_b128 v[192:195], v196 offset:2048
	ds_read_b128 v[196:199], v196 offset:3072
	s_add_u32 s24, s24, 0x40000
	s_addc_u32 s25, s25, 0
	s_mov_b32 m0, s36
	v_lshl_add_u64 v[204:205], s[24:25], 0, v[134:135]
	ds_read_b128 v[210:213], v167 offset:32768
	ds_read_b128 v[214:217], v167 offset:33792
	ds_read_b128 v[218:221], v167 offset:34816
	ds_read_b128 v[222:225], v167 offset:35840
	ds_read_b128 v[226:229], v167 offset:36864
	ds_read_b128 v[230:233], v167 offset:37888
	ds_read_b128 v[234:237], v167 offset:38912
	ds_read_b128 v[238:241], v167 offset:39936
	global_load_lds_dwordx4 v[204:205], off
	v_lshl_add_u64 v[204:205], s[24:25], 0, v[130:131]
	s_mov_b32 m0, s37
	s_nop 0
	global_load_lds_dwordx4 v[204:205], off
	s_waitcnt vmcnt(8)
	s_waitcnt lgkmcnt(0)
	s_barrier
	s_waitcnt lgkmcnt(0)
	v_mfma_f32_16x16x32_bf16 v[124:127], v[168:171], v[210:213], v[124:127]
	v_mfma_f32_16x16x32_bf16 v[116:119], v[176:179], v[210:213], v[116:119]
	v_mfma_f32_16x16x32_bf16 v[108:111], v[168:171], v[218:221], v[108:111]
	v_mfma_f32_16x16x32_bf16 v[100:103], v[176:179], v[218:221], v[100:103]
	v_mfma_f32_16x16x32_bf16 v[92:95], v[168:171], v[226:229], v[92:95]
	v_mfma_f32_16x16x32_bf16 v[84:87], v[176:179], v[226:229], v[84:87]
	v_mfma_f32_16x16x32_bf16 v[76:79], v[168:171], v[234:237], v[76:79]
	v_mfma_f32_16x16x32_bf16 v[68:71], v[176:179], v[234:237], v[68:71]
	v_mfma_f32_16x16x32_bf16 v[124:127], v[172:175], v[214:217], v[124:127]
	v_mfma_f32_16x16x32_bf16 v[116:119], v[180:183], v[214:217], v[116:119]
	v_mfma_f32_16x16x32_bf16 v[108:111], v[172:175], v[222:225], v[108:111]
	v_mfma_f32_16x16x32_bf16 v[100:103], v[180:183], v[222:225], v[100:103]
	v_mfma_f32_16x16x32_bf16 v[92:95], v[172:175], v[230:233], v[92:95]
	v_mfma_f32_16x16x32_bf16 v[84:87], v[180:183], v[230:233], v[84:87]
	v_mfma_f32_16x16x32_bf16 v[76:79], v[172:175], v[238:241], v[76:79]
	v_mfma_f32_16x16x32_bf16 v[68:71], v[180:183], v[238:241], v[68:71]
	v_mfma_f32_16x16x32_bf16 v[120:123], v[184:187], v[210:213], v[120:123]
	v_mfma_f32_16x16x32_bf16 v[112:115], v[192:195], v[210:213], v[112:115]
	v_mfma_f32_16x16x32_bf16 v[104:107], v[184:187], v[218:221], v[104:107]
	v_mfma_f32_16x16x32_bf16 v[96:99], v[192:195], v[218:221], v[96:99]
	v_mfma_f32_16x16x32_bf16 v[88:91], v[184:187], v[226:229], v[88:91]
	v_mfma_f32_16x16x32_bf16 v[80:83], v[192:195], v[226:229], v[80:83]
	v_mfma_f32_16x16x32_bf16 v[72:75], v[184:187], v[234:237], v[72:75]
	v_mfma_f32_16x16x32_bf16 v[64:67], v[192:195], v[234:237], v[64:67]
	v_mfma_f32_16x16x32_bf16 v[120:123], v[188:191], v[214:217], v[120:123]
	v_mfma_f32_16x16x32_bf16 v[112:115], v[196:199], v[214:217], v[112:115]
	v_mfma_f32_16x16x32_bf16 v[104:107], v[188:191], v[222:225], v[104:107]
	v_mfma_f32_16x16x32_bf16 v[96:99], v[196:199], v[222:225], v[96:99]
	v_mfma_f32_16x16x32_bf16 v[88:91], v[188:191], v[230:233], v[88:91]
	v_mfma_f32_16x16x32_bf16 v[80:83], v[196:199], v[230:233], v[80:83]
	v_mfma_f32_16x16x32_bf16 v[72:75], v[188:191], v[238:241], v[72:75]
	v_mfma_f32_16x16x32_bf16 v[64:67], v[196:199], v[238:241], v[64:67]
	s_barrier
	s_add_u32 s24, s22, 0x8000
	s_addc_u32 s25, s23, 0
	s_add_i32 s50, s50, s33
	v_lshl_add_u64 v[204:205], s[24:25], 0, v[132:133]
	s_mov_b32 m0, s50
	s_cmp_lg_u32 s54, 0
	s_cbranch_scc1 .Lts0_skip3
	ds_read_b128 v[210:213], v167 offset:49152
	ds_read_b128 v[214:217], v167 offset:50176
	ds_read_b128 v[218:221], v167 offset:51200
	ds_read_b128 v[222:225], v167 offset:52224
	ds_read_b128 v[226:229], v167 offset:53248
	ds_read_b128 v[230:233], v167 offset:54272
	ds_read_b128 v[234:237], v167 offset:55296
	ds_read_b128 v[238:241], v167 offset:56320
.Lts0_skip3:
	global_load_lds_dwordx4 v[204:205], off
	s_add_i32 m0, s50, 0x2000
	s_add_u32 s22, s22, 0xc000
	v_lshl_add_u64 v[204:205], s[24:25], 0, v[128:129]
	s_addc_u32 s23, s23, 0
	s_add_i32 s24, s51, s33
	global_load_lds_dwordx4 v[204:205], off
	v_lshl_add_u64 v[204:205], s[22:23], 0, v[132:133]
	s_mov_b32 m0, s24
	v_lshl_add_u64 v[162:163], v[162:163], 0, s[4:5]
	global_load_lds_dwordx4 v[204:205], off
	v_lshl_add_u64 v[204:205], s[22:23], 0, v[128:129]
	s_add_i32 m0, s24, 0x2000
	s_nop 0
	global_load_lds_dwordx4 v[204:205], off
	s_mov_b32 m0, s40
	s_nop 0
	global_load_lds_dwordx4 v[162:163], off
	v_lshl_add_u64 v[162:163], v[200:201], 0, s[4:5]
	s_mov_b32 m0, s41
	s_nop 0
	global_load_lds_dwordx4 v[162:163], off
	s_waitcnt vmcnt(8)
	s_waitcnt lgkmcnt(0)
	s_barrier
	s_cmp_lg_u32 s54, 0
	s_cbranch_scc1 .Lts0_skip2
	s_waitcnt lgkmcnt(0)
	v_mfma_f32_16x16x32_bf16 v[60:63], v[168:171], v[210:213], v[60:63]
	v_mfma_f32_16x16x32_bf16 v[52:55], v[176:179], v[210:213], v[52:55]
	v_mfma_f32_16x16x32_bf16 v[44:47], v[168:171], v[218:221], v[44:47]
	v_mfma_f32_16x16x32_bf16 v[36:39], v[176:179], v[218:221], v[36:39]
	v_mfma_f32_16x16x32_bf16 v[28:31], v[168:171], v[226:229], v[28:31]
	v_mfma_f32_16x16x32_bf16 v[20:23], v[176:179], v[226:229], v[20:23]
	v_mfma_f32_16x16x32_bf16 v[12:15], v[168:171], v[234:237], v[12:15]
	v_mfma_f32_16x16x32_bf16 v[4:7], v[176:179], v[234:237], v[4:7]
	v_mfma_f32_16x16x32_bf16 v[60:63], v[172:175], v[214:217], v[60:63]
	v_mfma_f32_16x16x32_bf16 v[52:55], v[180:183], v[214:217], v[52:55]
	v_mfma_f32_16x16x32_bf16 v[44:47], v[172:175], v[222:225], v[44:47]
	v_mfma_f32_16x16x32_bf16 v[36:39], v[180:183], v[222:225], v[36:39]
	v_mfma_f32_16x16x32_bf16 v[28:31], v[172:175], v[230:233], v[28:31]
	v_mfma_f32_16x16x32_bf16 v[20:23], v[180:183], v[230:233], v[20:23]
	v_mfma_f32_16x16x32_bf16 v[12:15], v[172:175], v[238:241], v[12:15]
	v_mfma_f32_16x16x32_bf16 v[4:7], v[180:183], v[238:241], v[4:7]
	v_mfma_f32_16x16x32_bf16 v[56:59], v[184:187], v[210:213], v[56:59]
	v_mfma_f32_16x16x32_bf16 v[48:51], v[192:195], v[210:213], v[48:51]
	v_mfma_f32_16x16x32_bf16 v[40:43], v[184:187], v[218:221], v[40:43]
	v_mfma_f32_16x16x32_bf16 v[32:35], v[192:195], v[218:221], v[32:35]
	v_mfma_f32_16x16x32_bf16 v[24:27], v[184:187], v[226:229], v[24:27]
	v_mfma_f32_16x16x32_bf16 v[16:19], v[192:195], v[226:229], v[16:19]
	v_mfma_f32_16x16x32_bf16 v[8:11], v[184:187], v[234:237], v[8:11]
	v_mfma_f32_16x16x32_bf16 v[0:3], v[192:195], v[234:237], v[0:3]
	v_mfma_f32_16x16x32_bf16 v[56:59], v[188:191], v[214:217], v[56:59]
	v_mfma_f32_16x16x32_bf16 v[48:51], v[196:199], v[214:217], v[48:51]
	v_mfma_f32_16x16x32_bf16 v[40:43], v[188:191], v[222:225], v[40:43]
	v_mfma_f32_16x16x32_bf16 v[32:35], v[196:199], v[222:225], v[32:35]
	v_mfma_f32_16x16x32_bf16 v[24:27], v[188:191], v[230:233], v[24:27]
	v_mfma_f32_16x16x32_bf16 v[16:19], v[196:199], v[230:233], v[16:19]
	v_mfma_f32_16x16x32_bf16 v[8:11], v[188:191], v[238:241], v[8:11]
	v_mfma_f32_16x16x32_bf16 v[0:3], v[196:199], v[238:241], v[0:3]

.LBB0_1645:
	v_add_u32_e32 v168, s69, v182
	v_add_u32_e32 v204, s70, v182
	ds_read_b128 v[156:159], v168
	ds_read_b128 v[160:163], v168 offset:1024
	ds_read_b128 v[164:167], v168 offset:2048
	ds_read_b128 v[168:171], v168 offset:3072
	ds_read_b128 v[172:175], v204
	ds_read_b128 v[176:179], v204 offset:1024
	ds_read_b128 v[212:215], v204 offset:2048
	ds_read_b128 v[216:219], v204 offset:3072
	s_add_u32 s38, s36, 0x4000
	s_addc_u32 s39, s37, 0
	s_cmp_eq_u32 s47, 40
	s_cselect_b32 s42, s0, s38
	s_cselect_b32 s43, s1, s39
	s_cselect_b32 s40, s34, s45
	s_cselect_b32 s41, s35, s46
	s_add_u32 s38, s42, 0x8000
	s_addc_u32 s39, s43, 0
	v_lshl_add_u64 v[204:205], s[36:37], 0, v[150:151]
	s_add_i32 m0, s56, 0xc000
	ds_read_b128 v[220:223], v199
	ds_read_b128 v[224:227], v199 offset:1024
	ds_read_b128 v[228:231], v199 offset:2048
	ds_read_b128 v[232:235], v199 offset:3072
	ds_read_b128 v[236:239], v199 offset:4096
	ds_read_b128 v[240:243], v199 offset:5120
	ds_read_b128 v[244:247], v199 offset:6144
	ds_read_b128 v[248:251], v199 offset:7168
	global_load_lds_dwordx4 v[204:205], off
	v_lshl_add_u64 v[204:205], s[36:37], 0, v[148:149]
	s_add_i32 m0, s56, 0xe000
	s_nop 0
	global_load_lds_dwordx4 v[204:205], off
	s_waitcnt vmcnt(8)
	s_waitcnt lgkmcnt(0)
	s_barrier
	s_waitcnt lgkmcnt(0)
	v_mfma_f32_16x16x32_bf16 v[124:127], v[156:159], v[220:223], v[124:127]
	v_mfma_f32_16x16x32_bf16 v[120:123], v[164:167], v[220:223], v[120:123]
	v_mfma_f32_16x16x32_bf16 v[116:119], v[156:159], v[228:231], v[116:119]
	v_mfma_f32_16x16x32_bf16 v[112:115], v[164:167], v[228:231], v[112:115]
	v_mfma_f32_16x16x32_bf16 v[92:95], v[156:159], v[236:239], v[92:95]
	v_mfma_f32_16x16x32_bf16 v[88:91], v[164:167], v[236:239], v[88:91]
	v_mfma_f32_16x16x32_bf16 v[84:87], v[156:159], v[244:247], v[84:87]
	v_mfma_f32_16x16x32_bf16 v[80:83], v[164:167], v[244:247], v[80:83]
	v_mfma_f32_16x16x32_bf16 v[124:127], v[160:163], v[224:227], v[124:127]
	v_mfma_f32_16x16x32_bf16 v[120:123], v[168:171], v[224:227], v[120:123]
	v_mfma_f32_16x16x32_bf16 v[116:119], v[160:163], v[232:235], v[116:119]
	v_mfma_f32_16x16x32_bf16 v[112:115], v[168:171], v[232:235], v[112:115]
	v_mfma_f32_16x16x32_bf16 v[92:95], v[160:163], v[240:243], v[92:95]
	v_mfma_f32_16x16x32_bf16 v[88:91], v[168:171], v[240:243], v[88:91]
	v_mfma_f32_16x16x32_bf16 v[84:87], v[160:163], v[248:251], v[84:87]
	v_mfma_f32_16x16x32_bf16 v[80:83], v[168:171], v[248:251], v[80:83]
	v_mfma_f32_16x16x32_bf16 v[108:111], v[172:175], v[220:223], v[108:111]
	v_mfma_f32_16x16x32_bf16 v[104:107], v[212:215], v[220:223], v[104:107]
	v_mfma_f32_16x16x32_bf16 v[100:103], v[172:175], v[228:231], v[100:103]
	v_mfma_f32_16x16x32_bf16 v[96:99], v[212:215], v[228:231], v[96:99]
	v_mfma_f32_16x16x32_bf16 v[76:79], v[172:175], v[236:239], v[76:79]
	v_mfma_f32_16x16x32_bf16 v[72:75], v[212:215], v[236:239], v[72:75]
	v_mfma_f32_16x16x32_bf16 v[68:71], v[172:175], v[244:247], v[68:71]
	v_mfma_f32_16x16x32_bf16 v[64:67], v[212:215], v[244:247], v[64:67]
	v_mfma_f32_16x16x32_bf16 v[108:111], v[176:179], v[224:227], v[108:111]
	v_mfma_f32_16x16x32_bf16 v[104:107], v[216:219], v[224:227], v[104:107]
	v_mfma_f32_16x16x32_bf16 v[100:103], v[176:179], v[232:235], v[100:103]
	v_mfma_f32_16x16x32_bf16 v[96:99], v[216:219], v[232:235], v[96:99]
	v_mfma_f32_16x16x32_bf16 v[76:79], v[176:179], v[240:243], v[76:79]
	v_mfma_f32_16x16x32_bf16 v[72:75], v[216:219], v[240:243], v[72:75]
	v_mfma_f32_16x16x32_bf16 v[68:71], v[176:179], v[248:251], v[68:71]
	v_mfma_f32_16x16x32_bf16 v[64:67], v[216:219], v[248:251], v[64:67]
	s_barrier
	s_add_i32 s48, s69, s55
	v_lshl_add_u64 v[204:205], s[40:41], 0, v[128:129]
	s_mov_b32 m0, s48
	ds_read_b128 v[220:223], v199 offset:16384
	ds_read_b128 v[224:227], v199 offset:17408
	ds_read_b128 v[228:231], v199 offset:18432
	ds_read_b128 v[232:235], v199 offset:19456
	ds_read_b128 v[236:239], v199 offset:20480
	ds_read_b128 v[240:243], v199 offset:21504
	ds_read_b128 v[244:247], v199 offset:22528
	ds_read_b128 v[248:251], v199 offset:23552
	global_load_lds_dwordx4 v[204:205], off
	s_add_i32 m0, s48, 0x2000
	s_add_u32 s48, s40, 0x4000
	v_lshl_add_u64 v[204:205], s[40:41], 0, v[130:131]
	s_addc_u32 s49, s41, 0
	s_add_i32 s50, s70, s55
	global_load_lds_dwordx4 v[204:205], off
	v_lshl_add_u64 v[204:205], s[48:49], 0, v[128:129]
	s_mov_b32 m0, s50
	s_nop 0
	global_load_lds_dwordx4 v[204:205], off
	v_lshl_add_u64 v[204:205], s[48:49], 0, v[130:131]
	s_add_i32 m0, s50, 0x2000
	s_nop 0
	global_load_lds_dwordx4 v[204:205], off
	v_lshl_add_u64 v[204:205], s[42:43], 0, v[128:129]
	s_mov_b32 m0, s56
	s_nop 0
	global_load_lds_dwordx4 v[204:205], off
	v_lshl_add_u64 v[204:205], s[42:43], 0, v[130:131]
	s_mov_b32 m0, s57
	s_nop 0
	global_load_lds_dwordx4 v[204:205], off
	s_waitcnt vmcnt(8)
	s_waitcnt lgkmcnt(0)
	s_barrier
	s_waitcnt lgkmcnt(0)
	v_mfma_f32_16x16x32_bf16 v[60:63], v[156:159], v[220:223], v[60:63]
	v_mfma_f32_16x16x32_bf16 v[56:59], v[164:167], v[220:223], v[56:59]
	v_mfma_f32_16x16x32_bf16 v[52:55], v[156:159], v[228:231], v[52:55]
	v_mfma_f32_16x16x32_bf16 v[48:51], v[164:167], v[228:231], v[48:51]
	v_mfma_f32_16x16x32_bf16 v[28:31], v[156:159], v[236:239], v[28:31]
	v_mfma_f32_16x16x32_bf16 v[24:27], v[164:167], v[236:239], v[24:27]
	v_mfma_f32_16x16x32_bf16 v[20:23], v[156:159], v[244:247], v[20:23]
	v_mfma_f32_16x16x32_bf16 v[12:15], v[164:167], v[244:247], v[12:15]
	v_mfma_f32_16x16x32_bf16 v[60:63], v[160:163], v[224:227], v[60:63]
	v_mfma_f32_16x16x32_bf16 v[56:59], v[168:171], v[224:227], v[56:59]
	v_mfma_f32_16x16x32_bf16 v[52:55], v[160:163], v[232:235], v[52:55]
	v_mfma_f32_16x16x32_bf16 v[48:51], v[168:171], v[232:235], v[48:51]
	v_mfma_f32_16x16x32_bf16 v[28:31], v[160:163], v[240:243], v[28:31]
	v_mfma_f32_16x16x32_bf16 v[24:27], v[168:171], v[240:243], v[24:27]
	v_mfma_f32_16x16x32_bf16 v[20:23], v[160:163], v[248:251], v[20:23]
	v_mfma_f32_16x16x32_bf16 v[12:15], v[168:171], v[248:251], v[12:15]
	v_mfma_f32_16x16x32_bf16 v[44:47], v[172:175], v[220:223], v[44:47]
	v_mfma_f32_16x16x32_bf16 v[40:43], v[212:215], v[220:223], v[40:43]
	v_mfma_f32_16x16x32_bf16 v[36:39], v[172:175], v[228:231], v[36:39]
	v_mfma_f32_16x16x32_bf16 v[32:35], v[212:215], v[228:231], v[32:35]
	v_mfma_f32_16x16x32_bf16 v[16:19], v[172:175], v[236:239], v[16:19]
	v_mfma_f32_16x16x32_bf16 v[8:11], v[212:215], v[236:239], v[8:11]
	v_mfma_f32_16x16x32_bf16 v[4:7], v[172:175], v[244:247], v[4:7]
	v_mfma_f32_16x16x32_bf16 v[0:3], v[212:215], v[244:247], v[0:3]
	v_mfma_f32_16x16x32_bf16 v[44:47], v[176:179], v[224:227], v[44:47]
	v_mfma_f32_16x16x32_bf16 v[40:43], v[216:219], v[224:227], v[40:43]
	v_mfma_f32_16x16x32_bf16 v[36:39], v[176:179], v[232:235], v[36:39]
	v_mfma_f32_16x16x32_bf16 v[32:35], v[216:219], v[232:235], v[32:35]
	v_mfma_f32_16x16x32_bf16 v[16:19], v[176:179], v[240:243], v[16:19]
	v_mfma_f32_16x16x32_bf16 v[8:11], v[216:219], v[240:243], v[8:11]
	v_mfma_f32_16x16x32_bf16 v[4:7], v[176:179], v[248:251], v[4:7]
	v_mfma_f32_16x16x32_bf16 v[0:3], v[216:219], v[248:251], v[0:3]
	s_barrier
	s_add_i32 s48, 0, 0x18000
	s_add_i32 s49, 0, 0x1c000
	v_add_u32_e32 v168, s48, v182
	v_add_u32_e32 v204, s49, v182
	ds_read_b128 v[156:159], v168
	ds_read_b128 v[160:163], v168 offset:1024
	ds_read_b128 v[164:167], v168 offset:2048
	ds_read_b128 v[168:171], v168 offset:3072
	ds_read_b128 v[172:175], v204
	ds_read_b128 v[176:179], v204 offset:1024
	ds_read_b128 v[212:215], v204 offset:2048
	ds_read_b128 v[216:219], v204 offset:3072
	s_add_u32 s42, s42, 0x4000
	s_addc_u32 s43, s43, 0
	s_mov_b32 m0, s58
	v_lshl_add_u64 v[204:205], s[42:43], 0, v[128:129]
	ds_read_b128 v[220:223], v199 offset:32768
	ds_read_b128 v[224:227], v199 offset:33792
	ds_read_b128 v[228:231], v199 offset:34816
	ds_read_b128 v[232:235], v199 offset:35840
	ds_read_b128 v[236:239], v199 offset:36864
	ds_read_b128 v[240:243], v199 offset:37888
	ds_read_b128 v[244:247], v199 offset:38912
	ds_read_b128 v[248:251], v199 offset:39936
	global_load_lds_dwordx4 v[204:205], off
	v_lshl_add_u64 v[204:205], s[42:43], 0, v[130:131]
	s_mov_b32 m0, s59
	s_nop 0
	global_load_lds_dwordx4 v[204:205], off
	s_waitcnt vmcnt(8)
	s_waitcnt lgkmcnt(0)
	s_barrier
	s_waitcnt lgkmcnt(0)
	v_mfma_f32_16x16x32_bf16 v[124:127], v[156:159], v[220:223], v[124:127]
	v_mfma_f32_16x16x32_bf16 v[120:123], v[164:167], v[220:223], v[120:123]
	v_mfma_f32_16x16x32_bf16 v[116:119], v[156:159], v[228:231], v[116:119]
	v_mfma_f32_16x16x32_bf16 v[112:115], v[164:167], v[228:231], v[112:115]
	v_mfma_f32_16x16x32_bf16 v[92:95], v[156:159], v[236:239], v[92:95]
	v_mfma_f32_16x16x32_bf16 v[88:91], v[164:167], v[236:239], v[88:91]
	v_mfma_f32_16x16x32_bf16 v[84:87], v[156:159], v[244:247], v[84:87]
	v_mfma_f32_16x16x32_bf16 v[80:83], v[164:167], v[244:247], v[80:83]
	v_mfma_f32_16x16x32_bf16 v[124:127], v[160:163], v[224:227], v[124:127]
	v_mfma_f32_16x16x32_bf16 v[120:123], v[168:171], v[224:227], v[120:123]
	v_mfma_f32_16x16x32_bf16 v[116:119], v[160:163], v[232:235], v[116:119]
	v_mfma_f32_16x16x32_bf16 v[112:115], v[168:171], v[232:235], v[112:115]
	v_mfma_f32_16x16x32_bf16 v[92:95], v[160:163], v[240:243], v[92:95]
	v_mfma_f32_16x16x32_bf16 v[88:91], v[168:171], v[240:243], v[88:91]
	v_mfma_f32_16x16x32_bf16 v[84:87], v[160:163], v[248:251], v[84:87]
	v_mfma_f32_16x16x32_bf16 v[80:83], v[168:171], v[248:251], v[80:83]
	v_mfma_f32_16x16x32_bf16 v[108:111], v[172:175], v[220:223], v[108:111]
	v_mfma_f32_16x16x32_bf16 v[104:107], v[212:215], v[220:223], v[104:107]
	v_mfma_f32_16x16x32_bf16 v[100:103], v[172:175], v[228:231], v[100:103]
	v_mfma_f32_16x16x32_bf16 v[96:99], v[212:215], v[228:231], v[96:99]
	v_mfma_f32_16x16x32_bf16 v[76:79], v[172:175], v[236:239], v[76:79]
	v_mfma_f32_16x16x32_bf16 v[72:75], v[212:215], v[236:239], v[72:75]
	v_mfma_f32_16x16x32_bf16 v[68:71], v[172:175], v[244:247], v[68:71]
	v_mfma_f32_16x16x32_bf16 v[64:67], v[212:215], v[244:247], v[64:67]
	v_mfma_f32_16x16x32_bf16 v[108:111], v[176:179], v[224:227], v[108:111]
	v_mfma_f32_16x16x32_bf16 v[104:107], v[216:219], v[224:227], v[104:107]
	v_mfma_f32_16x16x32_bf16 v[100:103], v[176:179], v[232:235], v[100:103]
	v_mfma_f32_16x16x32_bf16 v[96:99], v[216:219], v[232:235], v[96:99]
	v_mfma_f32_16x16x32_bf16 v[76:79], v[176:179], v[240:243], v[76:79]
	v_mfma_f32_16x16x32_bf16 v[72:75], v[216:219], v[240:243], v[72:75]
	v_mfma_f32_16x16x32_bf16 v[68:71], v[176:179], v[248:251], v[68:71]
	v_mfma_f32_16x16x32_bf16 v[64:67], v[216:219], v[248:251], v[64:67]
	s_barrier
	s_add_u32 s42, s40, 0x8000
	s_addc_u32 s43, s41, 0
	s_add_i32 s48, s48, s55
	v_lshl_add_u64 v[204:205], s[42:43], 0, v[128:129]
	s_mov_b32 m0, s48
	ds_read_b128 v[220:223], v199 offset:49152
	ds_read_b128 v[224:227], v199 offset:50176
	ds_read_b128 v[228:231], v199 offset:51200
	ds_read_b128 v[232:235], v199 offset:52224
	ds_read_b128 v[236:239], v199 offset:53248
	ds_read_b128 v[240:243], v199 offset:54272
	ds_read_b128 v[244:247], v199 offset:55296
	ds_read_b128 v[248:251], v199 offset:56320
	global_load_lds_dwordx4 v[204:205], off
	s_add_i32 m0, s48, 0x2000
	s_add_u32 s40, s40, 0xc000
	v_lshl_add_u64 v[204:205], s[42:43], 0, v[130:131]
	s_addc_u32 s41, s41, 0
	s_add_i32 s42, s49, s55
	global_load_lds_dwordx4 v[204:205], off
	v_lshl_add_u64 v[204:205], s[40:41], 0, v[128:129]
	s_mov_b32 m0, s42
	s_nop 0
	global_load_lds_dwordx4 v[204:205], off
	v_lshl_add_u64 v[204:205], s[40:41], 0, v[130:131]
	s_add_i32 m0, s42, 0x2000
	s_nop 0
	global_load_lds_dwordx4 v[204:205], off
	v_lshl_add_u64 v[204:205], s[38:39], 0, v[128:129]
	s_mov_b32 m0, s65
	s_nop 0
	global_load_lds_dwordx4 v[204:205], off
	v_lshl_add_u64 v[204:205], s[38:39], 0, v[130:131]
	s_mov_b32 m0, s66
	s_nop 0
	global_load_lds_dwordx4 v[204:205], off
	s_waitcnt vmcnt(8)
	s_waitcnt lgkmcnt(0)
	s_barrier
	s_waitcnt lgkmcnt(0)
	v_mfma_f32_16x16x32_bf16 v[60:63], v[156:159], v[220:223], v[60:63]
	v_mfma_f32_16x16x32_bf16 v[56:59], v[164:167], v[220:223], v[56:59]
	v_mfma_f32_16x16x32_bf16 v[52:55], v[156:159], v[228:231], v[52:55]
	v_mfma_f32_16x16x32_bf16 v[48:51], v[164:167], v[228:231], v[48:51]
	v_mfma_f32_16x16x32_bf16 v[28:31], v[156:159], v[236:239], v[28:31]
	v_mfma_f32_16x16x32_bf16 v[24:27], v[164:167], v[236:239], v[24:27]
	v_mfma_f32_16x16x32_bf16 v[20:23], v[156:159], v[244:247], v[20:23]
	v_mfma_f32_16x16x32_bf16 v[12:15], v[164:167], v[244:247], v[12:15]
	v_mfma_f32_16x16x32_bf16 v[60:63], v[160:163], v[224:227], v[60:63]
	v_mfma_f32_16x16x32_bf16 v[56:59], v[168:171], v[224:227], v[56:59]
	v_mfma_f32_16x16x32_bf16 v[52:55], v[160:163], v[232:235], v[52:55]
	v_mfma_f32_16x16x32_bf16 v[48:51], v[168:171], v[232:235], v[48:51]
	v_mfma_f32_16x16x32_bf16 v[28:31], v[160:163], v[240:243], v[28:31]
	v_mfma_f32_16x16x32_bf16 v[24:27], v[168:171], v[240:243], v[24:27]
	v_mfma_f32_16x16x32_bf16 v[20:23], v[160:163], v[248:251], v[20:23]
	v_mfma_f32_16x16x32_bf16 v[12:15], v[168:171], v[248:251], v[12:15]
	v_mfma_f32_16x16x32_bf16 v[44:47], v[172:175], v[220:223], v[44:47]
	v_mfma_f32_16x16x32_bf16 v[40:43], v[212:215], v[220:223], v[40:43]
	v_mfma_f32_16x16x32_bf16 v[36:39], v[172:175], v[228:231], v[36:39]
	v_mfma_f32_16x16x32_bf16 v[32:35], v[212:215], v[228:231], v[32:35]
	v_mfma_f32_16x16x32_bf16 v[16:19], v[172:175], v[236:239], v[16:19]
	v_mfma_f32_16x16x32_bf16 v[8:11], v[212:215], v[236:239], v[8:11]
	v_mfma_f32_16x16x32_bf16 v[4:7], v[172:175], v[244:247], v[4:7]
	v_mfma_f32_16x16x32_bf16 v[0:3], v[212:215], v[244:247], v[0:3]
	v_mfma_f32_16x16x32_bf16 v[44:47], v[176:179], v[224:227], v[44:47]
	v_mfma_f32_16x16x32_bf16 v[40:43], v[216:219], v[224:227], v[40:43]
	v_mfma_f32_16x16x32_bf16 v[36:39], v[176:179], v[232:235], v[36:39]
	v_mfma_f32_16x16x32_bf16 v[32:35], v[216:219], v[232:235], v[32:35]
	v_mfma_f32_16x16x32_bf16 v[16:19], v[176:179], v[240:243], v[16:19]
	v_mfma_f32_16x16x32_bf16 v[8:11], v[216:219], v[240:243], v[8:11]
	v_mfma_f32_16x16x32_bf16 v[4:7], v[176:179], v[248:251], v[4:7]
	v_mfma_f32_16x16x32_bf16 v[0:3], v[216:219], v[248:251], v[0:3]
	s_barrier
	s_add_i32 s47, s47, 2
	s_add_u32 s45, s45, 0x10000
	s_addc_u32 s46, s46, 0
	s_add_u32 s36, s36, 0x10000
	s_addc_u32 s37, s37, 0
	s_cmp_gt_u32 s47, 41
	s_cbranch_scc0 .LBB0_1645
	s_and_b64 vcc, exec, s[2:3]
	s_cbranch_vccz .LBB0_1648
	s_barrier

.LBB0_1729:
	ds_read_b128 v[128:131], v210
	ds_read_b128 v[132:135], v210 offset:1024
	ds_read_b128 v[136:139], v210 offset:2048
	ds_read_b128 v[140:143], v210 offset:3072
	ds_read_b128 v[144:147], v211
	ds_read_b128 v[148:151], v211 offset:1024
	ds_read_b128 v[152:155], v211 offset:2048
	ds_read_b128 v[156:159], v211 offset:3072
	s_add_u32 s26, s6, 0xfffc0080
	s_addc_u32 s27, s7, -1
	s_cmp_eq_u32 s35, 12
	s_cselect_b32 s29, s1, s27
	s_cselect_b32 s28, s19, s26
	s_cselect_b32 s27, s21, s34
	s_cselect_b32 s26, s30, s31
	v_lshl_add_u64 v[198:199], s[6:7], 0, v[188:189]
	s_add_i32 m0, s42, 0xc000
	ds_read_b128 v[160:163], v212
	ds_read_b128 v[164:167], v212 offset:1024
	ds_read_b128 v[194:197], v212 offset:2048
	ds_read_b128 v[214:217], v212 offset:3072
	ds_read_b128 v[218:221], v212 offset:4096
	ds_read_b128 v[222:225], v212 offset:5120
	ds_read_b128 v[226:229], v212 offset:6144
	ds_read_b128 v[230:233], v212 offset:7168
	global_load_lds_dwordx4 v[198:199], off
	v_lshl_add_u64 v[198:199], s[6:7], 0, v[186:187]
	s_add_i32 m0, s42, 0xe000
	s_nop 0
	global_load_lds_dwordx4 v[198:199], off
	s_waitcnt vmcnt(8)
	s_waitcnt lgkmcnt(0)
	s_barrier
	s_waitcnt lgkmcnt(0)
	v_mfma_f32_16x16x32_bf16 v[124:127], v[128:131], v[160:163], v[124:127]
	v_mfma_f32_16x16x32_bf16 v[120:123], v[136:139], v[160:163], v[120:123]
	v_mfma_f32_16x16x32_bf16 v[116:119], v[128:131], v[194:197], v[116:119]
	v_mfma_f32_16x16x32_bf16 v[112:115], v[136:139], v[194:197], v[112:115]
	v_mfma_f32_16x16x32_bf16 v[108:111], v[128:131], v[218:221], v[108:111]
	v_mfma_f32_16x16x32_bf16 v[104:107], v[136:139], v[218:221], v[104:107]
	v_mfma_f32_16x16x32_bf16 v[100:103], v[128:131], v[226:229], v[100:103]
	v_mfma_f32_16x16x32_bf16 v[96:99], v[136:139], v[226:229], v[96:99]
	v_mfma_f32_16x16x32_bf16 v[124:127], v[132:135], v[164:167], v[124:127]
	v_mfma_f32_16x16x32_bf16 v[120:123], v[140:143], v[164:167], v[120:123]
	v_mfma_f32_16x16x32_bf16 v[116:119], v[132:135], v[214:217], v[116:119]
	v_mfma_f32_16x16x32_bf16 v[112:115], v[140:143], v[214:217], v[112:115]
	v_mfma_f32_16x16x32_bf16 v[108:111], v[132:135], v[222:225], v[108:111]
	v_mfma_f32_16x16x32_bf16 v[104:107], v[140:143], v[222:225], v[104:107]
	v_mfma_f32_16x16x32_bf16 v[100:103], v[132:135], v[230:233], v[100:103]
	v_mfma_f32_16x16x32_bf16 v[96:99], v[140:143], v[230:233], v[96:99]
	v_mfma_f32_16x16x32_bf16 v[60:63], v[144:147], v[160:163], v[60:63]
	v_mfma_f32_16x16x32_bf16 v[56:59], v[152:155], v[160:163], v[56:59]
	v_mfma_f32_16x16x32_bf16 v[52:55], v[144:147], v[194:197], v[52:55]
	v_mfma_f32_16x16x32_bf16 v[48:51], v[152:155], v[194:197], v[48:51]
	v_mfma_f32_16x16x32_bf16 v[44:47], v[144:147], v[218:221], v[44:47]
	v_mfma_f32_16x16x32_bf16 v[40:43], v[152:155], v[218:221], v[40:43]
	v_mfma_f32_16x16x32_bf16 v[36:39], v[144:147], v[226:229], v[36:39]
	v_mfma_f32_16x16x32_bf16 v[32:35], v[152:155], v[226:229], v[32:35]
	v_mfma_f32_16x16x32_bf16 v[60:63], v[148:151], v[164:167], v[60:63]
	v_mfma_f32_16x16x32_bf16 v[56:59], v[156:159], v[164:167], v[56:59]
	v_mfma_f32_16x16x32_bf16 v[52:55], v[148:151], v[214:217], v[52:55]
	v_mfma_f32_16x16x32_bf16 v[48:51], v[156:159], v[214:217], v[48:51]
	v_mfma_f32_16x16x32_bf16 v[44:47], v[148:151], v[222:225], v[44:47]
	v_mfma_f32_16x16x32_bf16 v[40:43], v[156:159], v[222:225], v[40:43]
	v_mfma_f32_16x16x32_bf16 v[36:39], v[148:151], v[230:233], v[36:39]
	v_mfma_f32_16x16x32_bf16 v[32:35], v[156:159], v[230:233], v[32:35]
	s_barrier
	s_add_i32 s61, s56, s41
	v_lshl_add_u64 v[198:199], s[26:27], 0, v[170:171]
	s_mov_b32 m0, s61
	ds_read_b128 v[160:163], v212 offset:16384
	ds_read_b128 v[164:167], v212 offset:17408
	ds_read_b128 v[194:197], v212 offset:18432
	ds_read_b128 v[214:217], v212 offset:19456
	ds_read_b128 v[218:221], v212 offset:20480
	ds_read_b128 v[222:225], v212 offset:21504
	ds_read_b128 v[226:229], v212 offset:22528
	ds_read_b128 v[230:233], v212 offset:23552
	global_load_lds_dwordx4 v[198:199], off
	s_add_i32 m0, s61, 0x2000
	s_add_u32 s62, s26, 0x4000
	v_lshl_add_u64 v[198:199], s[26:27], 0, v[174:175]
	s_addc_u32 s63, s27, 0
	s_add_i32 s61, s57, s41
	global_load_lds_dwordx4 v[198:199], off
	v_lshl_add_u64 v[198:199], s[62:63], 0, v[170:171]
	s_mov_b32 m0, s61
	v_lshl_add_u64 v[204:205], s[28:29], 0, v[172:173]
	global_load_lds_dwordx4 v[198:199], off
	v_lshl_add_u64 v[198:199], s[62:63], 0, v[174:175]
	s_add_i32 m0, s61, 0x2000
	s_nop 0
	global_load_lds_dwordx4 v[198:199], off
	v_lshl_add_u64 v[198:199], s[28:29], 0, v[168:169]
	s_mov_b32 m0, s42
	s_nop 0
	global_load_lds_dwordx4 v[198:199], off
	s_mov_b32 m0, s43
	s_nop 0
	global_load_lds_dwordx4 v[204:205], off
	s_waitcnt vmcnt(8)
	s_waitcnt lgkmcnt(0)
	s_barrier
	s_waitcnt lgkmcnt(0)
	v_mfma_f32_16x16x32_bf16 v[92:95], v[128:131], v[160:163], v[92:95]
	v_mfma_f32_16x16x32_bf16 v[88:91], v[136:139], v[160:163], v[88:91]
	v_mfma_f32_16x16x32_bf16 v[84:87], v[128:131], v[194:197], v[84:87]
	v_mfma_f32_16x16x32_bf16 v[80:83], v[136:139], v[194:197], v[80:83]
	v_mfma_f32_16x16x32_bf16 v[76:79], v[128:131], v[218:221], v[76:79]
	v_mfma_f32_16x16x32_bf16 v[72:75], v[136:139], v[218:221], v[72:75]
	v_mfma_f32_16x16x32_bf16 v[68:71], v[128:131], v[226:229], v[68:71]
	v_mfma_f32_16x16x32_bf16 v[64:67], v[136:139], v[226:229], v[64:67]
	v_mfma_f32_16x16x32_bf16 v[92:95], v[132:135], v[164:167], v[92:95]
	v_mfma_f32_16x16x32_bf16 v[88:91], v[140:143], v[164:167], v[88:91]
	v_mfma_f32_16x16x32_bf16 v[84:87], v[132:135], v[214:217], v[84:87]
	v_mfma_f32_16x16x32_bf16 v[80:83], v[140:143], v[214:217], v[80:83]
	v_mfma_f32_16x16x32_bf16 v[76:79], v[132:135], v[222:225], v[76:79]
	v_mfma_f32_16x16x32_bf16 v[72:75], v[140:143], v[222:225], v[72:75]
	v_mfma_f32_16x16x32_bf16 v[68:71], v[132:135], v[230:233], v[68:71]
	v_mfma_f32_16x16x32_bf16 v[64:67], v[140:143], v[230:233], v[64:67]
	v_mfma_f32_16x16x32_bf16 v[28:31], v[144:147], v[160:163], v[28:31]
	v_mfma_f32_16x16x32_bf16 v[24:27], v[152:155], v[160:163], v[24:27]
	v_mfma_f32_16x16x32_bf16 v[20:23], v[144:147], v[194:197], v[20:23]
	v_mfma_f32_16x16x32_bf16 v[16:19], v[152:155], v[194:197], v[16:19]
	v_mfma_f32_16x16x32_bf16 v[12:15], v[144:147], v[218:221], v[12:15]
	v_mfma_f32_16x16x32_bf16 v[8:11], v[152:155], v[218:221], v[8:11]
	v_mfma_f32_16x16x32_bf16 v[4:7], v[144:147], v[226:229], v[4:7]
	v_mfma_f32_16x16x32_bf16 v[0:3], v[152:155], v[226:229], v[0:3]
	v_mfma_f32_16x16x32_bf16 v[28:31], v[148:151], v[164:167], v[28:31]
	v_mfma_f32_16x16x32_bf16 v[24:27], v[156:159], v[164:167], v[24:27]
	v_mfma_f32_16x16x32_bf16 v[20:23], v[148:151], v[214:217], v[20:23]
	v_mfma_f32_16x16x32_bf16 v[16:19], v[156:159], v[214:217], v[16:19]
	v_mfma_f32_16x16x32_bf16 v[12:15], v[148:151], v[222:225], v[12:15]
	v_mfma_f32_16x16x32_bf16 v[8:11], v[156:159], v[222:225], v[8:11]
	v_mfma_f32_16x16x32_bf16 v[4:7], v[148:151], v[230:233], v[4:7]
	v_mfma_f32_16x16x32_bf16 v[0:3], v[156:159], v[230:233], v[0:3]
	s_barrier
	s_add_i32 s61, 0, 0x18000
	s_add_i32 s62, 0, 0x1c000
	v_add_u32_e32 v140, s61, v200
	v_add_u32_e32 v156, s62, v200
	ds_read_b128 v[128:131], v140
	ds_read_b128 v[132:135], v140 offset:1024
	ds_read_b128 v[136:139], v140 offset:2048
	ds_read_b128 v[140:143], v140 offset:3072
	ds_read_b128 v[144:147], v156
	ds_read_b128 v[148:151], v156 offset:1024
	ds_read_b128 v[152:155], v156 offset:2048
	ds_read_b128 v[156:159], v156 offset:3072
	s_add_u32 s28, s28, 0x40000
	s_addc_u32 s29, s29, 0
	s_mov_b32 m0, s44
	v_lshl_add_u64 v[206:207], s[28:29], 0, v[168:169]
	ds_read_b128 v[160:163], v212 offset:32768
	ds_read_b128 v[164:167], v212 offset:33792
	ds_read_b128 v[194:197], v212 offset:34816
	ds_read_b128 v[214:217], v212 offset:35840
	ds_read_b128 v[218:221], v212 offset:36864
	ds_read_b128 v[222:225], v212 offset:37888
	ds_read_b128 v[226:229], v212 offset:38912
	ds_read_b128 v[230:233], v212 offset:39936
	global_load_lds_dwordx4 v[206:207], off
	v_lshl_add_u64 v[206:207], s[28:29], 0, v[172:173]
	s_mov_b32 m0, s45
	s_nop 0
	global_load_lds_dwordx4 v[206:207], off
	s_waitcnt vmcnt(8)
	s_waitcnt lgkmcnt(0)
	s_barrier
	s_waitcnt lgkmcnt(0)
	v_mfma_f32_16x16x32_bf16 v[124:127], v[128:131], v[160:163], v[124:127]
	v_mfma_f32_16x16x32_bf16 v[120:123], v[136:139], v[160:163], v[120:123]
	v_mfma_f32_16x16x32_bf16 v[116:119], v[128:131], v[194:197], v[116:119]
	v_mfma_f32_16x16x32_bf16 v[112:115], v[136:139], v[194:197], v[112:115]
	v_mfma_f32_16x16x32_bf16 v[108:111], v[128:131], v[218:221], v[108:111]
	v_mfma_f32_16x16x32_bf16 v[104:107], v[136:139], v[218:221], v[104:107]
	v_mfma_f32_16x16x32_bf16 v[100:103], v[128:131], v[226:229], v[100:103]
	v_mfma_f32_16x16x32_bf16 v[96:99], v[136:139], v[226:229], v[96:99]
	v_mfma_f32_16x16x32_bf16 v[124:127], v[132:135], v[164:167], v[124:127]
	v_mfma_f32_16x16x32_bf16 v[120:123], v[140:143], v[164:167], v[120:123]
	v_mfma_f32_16x16x32_bf16 v[116:119], v[132:135], v[214:217], v[116:119]
	v_mfma_f32_16x16x32_bf16 v[112:115], v[140:143], v[214:217], v[112:115]
	v_mfma_f32_16x16x32_bf16 v[108:111], v[132:135], v[222:225], v[108:111]
	v_mfma_f32_16x16x32_bf16 v[104:107], v[140:143], v[222:225], v[104:107]
	v_mfma_f32_16x16x32_bf16 v[100:103], v[132:135], v[230:233], v[100:103]
	v_mfma_f32_16x16x32_bf16 v[96:99], v[140:143], v[230:233], v[96:99]
	v_mfma_f32_16x16x32_bf16 v[60:63], v[144:147], v[160:163], v[60:63]
	v_mfma_f32_16x16x32_bf16 v[56:59], v[152:155], v[160:163], v[56:59]
	v_mfma_f32_16x16x32_bf16 v[52:55], v[144:147], v[194:197], v[52:55]
	v_mfma_f32_16x16x32_bf16 v[48:51], v[152:155], v[194:197], v[48:51]
	v_mfma_f32_16x16x32_bf16 v[44:47], v[144:147], v[218:221], v[44:47]
	v_mfma_f32_16x16x32_bf16 v[40:43], v[152:155], v[218:221], v[40:43]
	v_mfma_f32_16x16x32_bf16 v[36:39], v[144:147], v[226:229], v[36:39]
	v_mfma_f32_16x16x32_bf16 v[32:35], v[152:155], v[226:229], v[32:35]
	v_mfma_f32_16x16x32_bf16 v[60:63], v[148:151], v[164:167], v[60:63]
	v_mfma_f32_16x16x32_bf16 v[56:59], v[156:159], v[164:167], v[56:59]
	v_mfma_f32_16x16x32_bf16 v[52:55], v[148:151], v[214:217], v[52:55]
	v_mfma_f32_16x16x32_bf16 v[48:51], v[156:159], v[214:217], v[48:51]
	v_mfma_f32_16x16x32_bf16 v[44:47], v[148:151], v[222:225], v[44:47]
	v_mfma_f32_16x16x32_bf16 v[40:43], v[156:159], v[222:225], v[40:43]
	v_mfma_f32_16x16x32_bf16 v[36:39], v[148:151], v[230:233], v[36:39]
	v_mfma_f32_16x16x32_bf16 v[32:35], v[156:159], v[230:233], v[32:35]
	s_barrier
	s_add_u32 s28, s26, 0x8000
	s_addc_u32 s29, s27, 0
	s_add_i32 s61, s61, s41
	v_lshl_add_u64 v[206:207], s[28:29], 0, v[170:171]
	s_mov_b32 m0, s61
	ds_read_b128 v[160:163], v212 offset:49152
	ds_read_b128 v[164:167], v212 offset:50176
	ds_read_b128 v[194:197], v212 offset:51200
	ds_read_b128 v[214:217], v212 offset:52224
	ds_read_b128 v[218:221], v212 offset:53248
	ds_read_b128 v[222:225], v212 offset:54272
	ds_read_b128 v[226:229], v212 offset:55296
	ds_read_b128 v[230:233], v212 offset:56320
	global_load_lds_dwordx4 v[206:207], off
	s_add_i32 m0, s61, 0x2000
	s_add_u32 s26, s26, 0xc000
	v_lshl_add_u64 v[206:207], s[28:29], 0, v[174:175]
	s_addc_u32 s27, s27, 0
	s_add_i32 s28, s62, s41
	global_load_lds_dwordx4 v[206:207], off
	v_lshl_add_u64 v[206:207], s[26:27], 0, v[170:171]
	s_mov_b32 m0, s28
	v_lshl_add_u64 v[198:199], v[198:199], 0, s[12:13]
	global_load_lds_dwordx4 v[206:207], off
	v_lshl_add_u64 v[206:207], s[26:27], 0, v[174:175]
	s_add_i32 m0, s28, 0x2000
	s_nop 0
	global_load_lds_dwordx4 v[206:207], off
	s_mov_b32 m0, s50
	s_nop 0
	global_load_lds_dwordx4 v[198:199], off
	v_lshl_add_u64 v[198:199], v[204:205], 0, s[12:13]
	s_mov_b32 m0, s51
	s_nop 0
	global_load_lds_dwordx4 v[198:199], off
	s_waitcnt vmcnt(8)
	s_waitcnt lgkmcnt(0)
	s_barrier
	s_waitcnt lgkmcnt(0)
	v_mfma_f32_16x16x32_bf16 v[92:95], v[128:131], v[160:163], v[92:95]
	v_mfma_f32_16x16x32_bf16 v[88:91], v[136:139], v[160:163], v[88:91]
	v_mfma_f32_16x16x32_bf16 v[84:87], v[128:131], v[194:197], v[84:87]
	v_mfma_f32_16x16x32_bf16 v[80:83], v[136:139], v[194:197], v[80:83]
	v_mfma_f32_16x16x32_bf16 v[76:79], v[128:131], v[218:221], v[76:79]
	v_mfma_f32_16x16x32_bf16 v[72:75], v[136:139], v[218:221], v[72:75]
	v_mfma_f32_16x16x32_bf16 v[68:71], v[128:131], v[226:229], v[68:71]
	v_mfma_f32_16x16x32_bf16 v[64:67], v[136:139], v[226:229], v[64:67]
	v_mfma_f32_16x16x32_bf16 v[92:95], v[132:135], v[164:167], v[92:95]
	v_mfma_f32_16x16x32_bf16 v[88:91], v[140:143], v[164:167], v[88:91]
	v_mfma_f32_16x16x32_bf16 v[84:87], v[132:135], v[214:217], v[84:87]
	v_mfma_f32_16x16x32_bf16 v[80:83], v[140:143], v[214:217], v[80:83]
	v_mfma_f32_16x16x32_bf16 v[76:79], v[132:135], v[222:225], v[76:79]
	v_mfma_f32_16x16x32_bf16 v[72:75], v[140:143], v[222:225], v[72:75]
	v_mfma_f32_16x16x32_bf16 v[68:71], v[132:135], v[230:233], v[68:71]
	v_mfma_f32_16x16x32_bf16 v[64:67], v[140:143], v[230:233], v[64:67]
	v_mfma_f32_16x16x32_bf16 v[28:31], v[144:147], v[160:163], v[28:31]
	v_mfma_f32_16x16x32_bf16 v[24:27], v[152:155], v[160:163], v[24:27]
	v_mfma_f32_16x16x32_bf16 v[20:23], v[144:147], v[194:197], v[20:23]
	v_mfma_f32_16x16x32_bf16 v[16:19], v[152:155], v[194:197], v[16:19]
	v_mfma_f32_16x16x32_bf16 v[12:15], v[144:147], v[218:221], v[12:15]
	v_mfma_f32_16x16x32_bf16 v[8:11], v[152:155], v[218:221], v[8:11]
	v_mfma_f32_16x16x32_bf16 v[4:7], v[144:147], v[226:229], v[4:7]
	v_mfma_f32_16x16x32_bf16 v[0:3], v[152:155], v[226:229], v[0:3]
	v_mfma_f32_16x16x32_bf16 v[28:31], v[148:151], v[164:167], v[28:31]
	v_mfma_f32_16x16x32_bf16 v[24:27], v[156:159], v[164:167], v[24:27]
	v_mfma_f32_16x16x32_bf16 v[20:23], v[148:151], v[214:217], v[20:23]
	v_mfma_f32_16x16x32_bf16 v[16:19], v[156:159], v[214:217], v[16:19]
	v_mfma_f32_16x16x32_bf16 v[12:15], v[148:151], v[222:225], v[12:15]
	v_mfma_f32_16x16x32_bf16 v[8:11], v[156:159], v[222:225], v[8:11]
	v_mfma_f32_16x16x32_bf16 v[4:7], v[148:151], v[230:233], v[4:7]
	v_mfma_f32_16x16x32_bf16 v[0:3], v[156:159], v[230:233], v[0:3]
	s_barrier
	s_add_i32 s35, s35, 2
	s_add_u32 s31, s31, 0x10000
	s_addc_u32 s34, s34, 0
	s_add_u32 s6, s6, 0x100
	s_addc_u32 s7, s7, 0
	s_cmp_gt_u32 s35, 13
	s_cbranch_scc0 .LBB0_1729
	s_and_b64 vcc, exec, s[14:15]
	s_cbranch_vccz .LBB0_1740
	s_barrier
	v_lshl_add_u32 v214, s0, 8, v179
	s_cmp_gt_i32 s2, 4
	s_mov_b64 s[0:1], -1
	s_cbranch_scc1 .LBB0_1741

.LBB0_2258:
	ds_read_b128 v[128:131], v170
	ds_read_b128 v[148:151], v170 offset:1024
	ds_read_b128 v[152:155], v170 offset:2048
	ds_read_b128 v[174:177], v170 offset:3072
	ds_read_b128 v[178:181], v171
	ds_read_b128 v[182:185], v171 offset:1024
	ds_read_b128 v[186:189], v171 offset:2048
	ds_read_b128 v[190:193], v171 offset:3072
	s_add_u32 s30, s28, 0xfffe0080
	s_addc_u32 s31, s29, -1
	s_cmp_eq_u32 s56, 4
	s_cselect_b32 s35, s17, s31
	s_cselect_b32 s34, s52, s30
	s_cselect_b32 s31, s19, s55
	s_cselect_b32 s30, s53, s54
	v_lshl_add_u64 v[204:205], s[28:29], 0, v[142:143]
	s_add_i32 m0, s25, 0xc000
	ds_read_b128 v[194:197], v172
	ds_read_b128 v[198:201], v172 offset:1024
	ds_read_b128 v[210:213], v172 offset:2048
	ds_read_b128 v[214:217], v172 offset:3072
	ds_read_b128 v[218:221], v172 offset:4096
	ds_read_b128 v[222:225], v172 offset:5120
	ds_read_b128 v[226:229], v172 offset:6144
	ds_read_b128 v[230:233], v172 offset:7168
	global_load_lds_dwordx4 v[204:205], off
	v_lshl_add_u64 v[204:205], s[28:29], 0, v[140:141]
	s_add_i32 m0, s25, 0xe000
	s_nop 0
	global_load_lds_dwordx4 v[204:205], off
	s_waitcnt vmcnt(8)
	s_waitcnt lgkmcnt(0)
	s_barrier
	s_waitcnt lgkmcnt(0)
	v_mfma_f32_16x16x32_bf16 v[124:127], v[128:131], v[194:197], v[124:127]
	v_mfma_f32_16x16x32_bf16 v[120:123], v[152:155], v[194:197], v[120:123]
	v_mfma_f32_16x16x32_bf16 v[116:119], v[128:131], v[210:213], v[116:119]
	v_mfma_f32_16x16x32_bf16 v[112:115], v[152:155], v[210:213], v[112:115]
	v_mfma_f32_16x16x32_bf16 v[92:95], v[128:131], v[218:221], v[92:95]
	v_mfma_f32_16x16x32_bf16 v[88:91], v[152:155], v[218:221], v[88:91]
	v_mfma_f32_16x16x32_bf16 v[84:87], v[128:131], v[226:229], v[84:87]
	v_mfma_f32_16x16x32_bf16 v[72:75], v[152:155], v[226:229], v[72:75]
	v_mfma_f32_16x16x32_bf16 v[124:127], v[148:151], v[198:201], v[124:127]
	v_mfma_f32_16x16x32_bf16 v[120:123], v[174:177], v[198:201], v[120:123]
	v_mfma_f32_16x16x32_bf16 v[116:119], v[148:151], v[214:217], v[116:119]
	v_mfma_f32_16x16x32_bf16 v[112:115], v[174:177], v[214:217], v[112:115]
	v_mfma_f32_16x16x32_bf16 v[92:95], v[148:151], v[222:225], v[92:95]
	v_mfma_f32_16x16x32_bf16 v[88:91], v[174:177], v[222:225], v[88:91]
	v_mfma_f32_16x16x32_bf16 v[84:87], v[148:151], v[230:233], v[84:87]
	v_mfma_f32_16x16x32_bf16 v[72:75], v[174:177], v[230:233], v[72:75]
	v_mfma_f32_16x16x32_bf16 v[108:111], v[178:181], v[194:197], v[108:111]
	v_mfma_f32_16x16x32_bf16 v[104:107], v[186:189], v[194:197], v[104:107]
	v_mfma_f32_16x16x32_bf16 v[100:103], v[178:181], v[210:213], v[100:103]
	v_mfma_f32_16x16x32_bf16 v[96:99], v[186:189], v[210:213], v[96:99]
	v_mfma_f32_16x16x32_bf16 v[80:83], v[178:181], v[218:221], v[80:83]
	v_mfma_f32_16x16x32_bf16 v[76:79], v[186:189], v[218:221], v[76:79]
	v_mfma_f32_16x16x32_bf16 v[68:71], v[178:181], v[226:229], v[68:71]
	v_mfma_f32_16x16x32_bf16 v[64:67], v[186:189], v[226:229], v[64:67]
	v_mfma_f32_16x16x32_bf16 v[108:111], v[182:185], v[198:201], v[108:111]
	v_mfma_f32_16x16x32_bf16 v[104:107], v[190:193], v[198:201], v[104:107]
	v_mfma_f32_16x16x32_bf16 v[100:103], v[182:185], v[214:217], v[100:103]
	v_mfma_f32_16x16x32_bf16 v[96:99], v[190:193], v[214:217], v[96:99]
	v_mfma_f32_16x16x32_bf16 v[80:83], v[182:185], v[222:225], v[80:83]
	v_mfma_f32_16x16x32_bf16 v[76:79], v[190:193], v[222:225], v[76:79]
	v_mfma_f32_16x16x32_bf16 v[68:71], v[182:185], v[230:233], v[68:71]
	v_mfma_f32_16x16x32_bf16 v[64:67], v[190:193], v[230:233], v[64:67]
	s_barrier
	s_add_i32 s57, s49, s42
	v_lshl_add_u64 v[204:205], s[30:31], 0, v[134:135]
	s_mov_b32 m0, s57
	ds_read_b128 v[194:197], v172 offset:16384
	ds_read_b128 v[198:201], v172 offset:17408
	ds_read_b128 v[210:213], v172 offset:18432
	ds_read_b128 v[214:217], v172 offset:19456
	ds_read_b128 v[218:221], v172 offset:20480
	ds_read_b128 v[222:225], v172 offset:21504
	ds_read_b128 v[226:229], v172 offset:22528
	ds_read_b128 v[230:233], v172 offset:23552
	global_load_lds_dwordx4 v[204:205], off
	s_add_i32 m0, s57, 0x2000
	s_add_u32 s58, s30, 0x4000
	v_lshl_add_u64 v[204:205], s[30:31], 0, v[138:139]
	s_addc_u32 s59, s31, 0
	s_add_i32 s57, s50, s42
	global_load_lds_dwordx4 v[204:205], off
	v_lshl_add_u64 v[204:205], s[58:59], 0, v[134:135]
	s_mov_b32 m0, s57
	v_lshl_add_u64 v[206:207], s[34:35], 0, v[136:137]
	global_load_lds_dwordx4 v[204:205], off
	v_lshl_add_u64 v[204:205], s[58:59], 0, v[138:139]
	s_add_i32 m0, s57, 0x2000
	s_nop 0
	global_load_lds_dwordx4 v[204:205], off
	v_lshl_add_u64 v[204:205], s[34:35], 0, v[132:133]
	s_mov_b32 m0, s25
	s_nop 0
	global_load_lds_dwordx4 v[204:205], off
	s_mov_b32 m0, s27
	s_nop 0
	global_load_lds_dwordx4 v[206:207], off
	s_waitcnt vmcnt(8)
	s_waitcnt lgkmcnt(0)
	s_barrier
	s_waitcnt lgkmcnt(0)
	v_mfma_f32_16x16x32_bf16 v[60:63], v[128:131], v[194:197], v[60:63]
	v_mfma_f32_16x16x32_bf16 v[56:59], v[152:155], v[194:197], v[56:59]
	v_mfma_f32_16x16x32_bf16 v[48:51], v[128:131], v[210:213], v[48:51]
	v_mfma_f32_16x16x32_bf16 v[40:43], v[152:155], v[210:213], v[40:43]
	v_mfma_f32_16x16x32_bf16 v[32:35], v[128:131], v[218:221], v[32:35]
	v_mfma_f32_16x16x32_bf16 v[24:27], v[152:155], v[218:221], v[24:27]
	v_mfma_f32_16x16x32_bf16 v[16:19], v[128:131], v[226:229], v[16:19]
	v_mfma_f32_16x16x32_bf16 v[8:11], v[152:155], v[226:229], v[8:11]
	v_mfma_f32_16x16x32_bf16 v[60:63], v[148:151], v[198:201], v[60:63]
	v_mfma_f32_16x16x32_bf16 v[56:59], v[174:177], v[198:201], v[56:59]
	v_mfma_f32_16x16x32_bf16 v[48:51], v[148:151], v[214:217], v[48:51]
	v_mfma_f32_16x16x32_bf16 v[40:43], v[174:177], v[214:217], v[40:43]
	v_mfma_f32_16x16x32_bf16 v[32:35], v[148:151], v[222:225], v[32:35]
	v_mfma_f32_16x16x32_bf16 v[24:27], v[174:177], v[222:225], v[24:27]
	v_mfma_f32_16x16x32_bf16 v[16:19], v[148:151], v[230:233], v[16:19]
	v_mfma_f32_16x16x32_bf16 v[8:11], v[174:177], v[230:233], v[8:11]
	v_mfma_f32_16x16x32_bf16 v[52:55], v[178:181], v[194:197], v[52:55]
	v_mfma_f32_16x16x32_bf16 v[44:47], v[186:189], v[194:197], v[44:47]
	v_mfma_f32_16x16x32_bf16 v[36:39], v[178:181], v[210:213], v[36:39]
	v_mfma_f32_16x16x32_bf16 v[28:31], v[186:189], v[210:213], v[28:31]
	v_mfma_f32_16x16x32_bf16 v[20:23], v[178:181], v[218:221], v[20:23]
	v_mfma_f32_16x16x32_bf16 v[12:15], v[186:189], v[218:221], v[12:15]
	v_mfma_f32_16x16x32_bf16 v[4:7], v[178:181], v[226:229], v[4:7]
	v_mfma_f32_16x16x32_bf16 v[0:3], v[186:189], v[226:229], v[0:3]
	v_mfma_f32_16x16x32_bf16 v[52:55], v[182:185], v[198:201], v[52:55]
	v_mfma_f32_16x16x32_bf16 v[44:47], v[190:193], v[198:201], v[44:47]
	v_mfma_f32_16x16x32_bf16 v[36:39], v[182:185], v[214:217], v[36:39]
	v_mfma_f32_16x16x32_bf16 v[28:31], v[190:193], v[214:217], v[28:31]
	v_mfma_f32_16x16x32_bf16 v[20:23], v[182:185], v[222:225], v[20:23]
	v_mfma_f32_16x16x32_bf16 v[12:15], v[190:193], v[222:225], v[12:15]
	v_mfma_f32_16x16x32_bf16 v[4:7], v[182:185], v[230:233], v[4:7]
	v_mfma_f32_16x16x32_bf16 v[0:3], v[190:193], v[230:233], v[0:3]
	s_barrier
	s_add_i32 s57, 0, 0x18000
	v_add_u32_e32 v173, s57, v168
	s_add_i32 s58, 0, 0x1c000
	ds_read_b128 v[128:131], v173
	ds_read_b128 v[148:151], v173 offset:1024
	ds_read_b128 v[152:155], v173 offset:2048
	ds_read_b128 v[174:177], v173 offset:3072
	v_add_u32_e32 v173, s58, v168
	ds_read_b128 v[178:181], v173
	ds_read_b128 v[182:185], v173 offset:1024
	ds_read_b128 v[186:189], v173 offset:2048
	ds_read_b128 v[190:193], v173 offset:3072
	s_add_u32 s34, s34, 0x20000
	s_addc_u32 s35, s35, 0
	s_mov_b32 m0, s43
	v_lshl_add_u64 v[234:235], s[34:35], 0, v[132:133]
	ds_read_b128 v[194:197], v172 offset:32768
	ds_read_b128 v[198:201], v172 offset:33792
	ds_read_b128 v[210:213], v172 offset:34816
	ds_read_b128 v[214:217], v172 offset:35840
	ds_read_b128 v[218:221], v172 offset:36864
	ds_read_b128 v[222:225], v172 offset:37888
	ds_read_b128 v[226:229], v172 offset:38912
	ds_read_b128 v[230:233], v172 offset:39936
	global_load_lds_dwordx4 v[234:235], off
	v_lshl_add_u64 v[234:235], s[34:35], 0, v[136:137]
	s_mov_b32 m0, s44
	s_nop 0
	global_load_lds_dwordx4 v[234:235], off
	s_waitcnt vmcnt(8)
	s_waitcnt lgkmcnt(0)
	s_barrier
	s_waitcnt lgkmcnt(0)
	v_mfma_f32_16x16x32_bf16 v[124:127], v[128:131], v[194:197], v[124:127]
	v_mfma_f32_16x16x32_bf16 v[120:123], v[152:155], v[194:197], v[120:123]
	v_mfma_f32_16x16x32_bf16 v[116:119], v[128:131], v[210:213], v[116:119]
	v_mfma_f32_16x16x32_bf16 v[112:115], v[152:155], v[210:213], v[112:115]
	v_mfma_f32_16x16x32_bf16 v[92:95], v[128:131], v[218:221], v[92:95]
	v_mfma_f32_16x16x32_bf16 v[88:91], v[152:155], v[218:221], v[88:91]
	v_mfma_f32_16x16x32_bf16 v[84:87], v[128:131], v[226:229], v[84:87]
	v_mfma_f32_16x16x32_bf16 v[72:75], v[152:155], v[226:229], v[72:75]
	v_mfma_f32_16x16x32_bf16 v[124:127], v[148:151], v[198:201], v[124:127]
	v_mfma_f32_16x16x32_bf16 v[120:123], v[174:177], v[198:201], v[120:123]
	v_mfma_f32_16x16x32_bf16 v[116:119], v[148:151], v[214:217], v[116:119]
	v_mfma_f32_16x16x32_bf16 v[112:115], v[174:177], v[214:217], v[112:115]
	v_mfma_f32_16x16x32_bf16 v[92:95], v[148:151], v[222:225], v[92:95]
	v_mfma_f32_16x16x32_bf16 v[88:91], v[174:177], v[222:225], v[88:91]
	v_mfma_f32_16x16x32_bf16 v[84:87], v[148:151], v[230:233], v[84:87]
	v_mfma_f32_16x16x32_bf16 v[72:75], v[174:177], v[230:233], v[72:75]
	v_mfma_f32_16x16x32_bf16 v[108:111], v[178:181], v[194:197], v[108:111]
	v_mfma_f32_16x16x32_bf16 v[104:107], v[186:189], v[194:197], v[104:107]
	v_mfma_f32_16x16x32_bf16 v[100:103], v[178:181], v[210:213], v[100:103]
	v_mfma_f32_16x16x32_bf16 v[96:99], v[186:189], v[210:213], v[96:99]
	v_mfma_f32_16x16x32_bf16 v[80:83], v[178:181], v[218:221], v[80:83]
	v_mfma_f32_16x16x32_bf16 v[76:79], v[186:189], v[218:221], v[76:79]
	v_mfma_f32_16x16x32_bf16 v[68:71], v[178:181], v[226:229], v[68:71]
	v_mfma_f32_16x16x32_bf16 v[64:67], v[186:189], v[226:229], v[64:67]
	v_mfma_f32_16x16x32_bf16 v[108:111], v[182:185], v[198:201], v[108:111]
	v_mfma_f32_16x16x32_bf16 v[104:107], v[190:193], v[198:201], v[104:107]
	v_mfma_f32_16x16x32_bf16 v[100:103], v[182:185], v[214:217], v[100:103]
	v_mfma_f32_16x16x32_bf16 v[96:99], v[190:193], v[214:217], v[96:99]
	v_mfma_f32_16x16x32_bf16 v[80:83], v[182:185], v[222:225], v[80:83]
	v_mfma_f32_16x16x32_bf16 v[76:79], v[190:193], v[222:225], v[76:79]
	v_mfma_f32_16x16x32_bf16 v[68:71], v[182:185], v[230:233], v[68:71]
	v_mfma_f32_16x16x32_bf16 v[64:67], v[190:193], v[230:233], v[64:67]
	s_barrier
	s_add_u32 s34, s30, 0x8000
	s_addc_u32 s35, s31, 0
	s_add_i32 s57, s57, s42
	v_lshl_add_u64 v[234:235], s[34:35], 0, v[134:135]
	s_mov_b32 m0, s57
	ds_read_b128 v[194:197], v172 offset:49152
	ds_read_b128 v[198:201], v172 offset:50176
	ds_read_b128 v[210:213], v172 offset:51200
	ds_read_b128 v[214:217], v172 offset:52224
	ds_read_b128 v[218:221], v172 offset:53248
	ds_read_b128 v[222:225], v172 offset:54272
	ds_read_b128 v[226:229], v172 offset:55296
	ds_read_b128 v[230:233], v172 offset:56320
	global_load_lds_dwordx4 v[234:235], off
	s_add_i32 m0, s57, 0x2000
	s_add_u32 s30, s30, 0xc000
	v_lshl_add_u64 v[234:235], s[34:35], 0, v[138:139]
	s_addc_u32 s31, s31, 0
	s_add_i32 s34, s58, s42
	global_load_lds_dwordx4 v[234:235], off
	v_lshl_add_u64 v[234:235], s[30:31], 0, v[134:135]
	s_mov_b32 m0, s34
	v_lshl_add_u64 v[204:205], v[204:205], 0, s[12:13]
	global_load_lds_dwordx4 v[234:235], off
	v_lshl_add_u64 v[234:235], s[30:31], 0, v[138:139]
	s_add_i32 m0, s34, 0x2000
	s_nop 0
	global_load_lds_dwordx4 v[234:235], off
	s_mov_b32 m0, s46
	s_nop 0
	global_load_lds_dwordx4 v[204:205], off
	v_lshl_add_u64 v[204:205], v[206:207], 0, s[12:13]
	s_mov_b32 m0, s47
	s_nop 0
	global_load_lds_dwordx4 v[204:205], off
	s_waitcnt vmcnt(8)
	s_waitcnt lgkmcnt(0)
	s_barrier
	s_waitcnt lgkmcnt(0)
	v_mfma_f32_16x16x32_bf16 v[60:63], v[128:131], v[194:197], v[60:63]
	v_mfma_f32_16x16x32_bf16 v[56:59], v[152:155], v[194:197], v[56:59]
	v_mfma_f32_16x16x32_bf16 v[48:51], v[128:131], v[210:213], v[48:51]
	v_mfma_f32_16x16x32_bf16 v[40:43], v[152:155], v[210:213], v[40:43]
	v_mfma_f32_16x16x32_bf16 v[32:35], v[128:131], v[218:221], v[32:35]
	v_mfma_f32_16x16x32_bf16 v[24:27], v[152:155], v[218:221], v[24:27]
	v_mfma_f32_16x16x32_bf16 v[16:19], v[128:131], v[226:229], v[16:19]
	v_mfma_f32_16x16x32_bf16 v[8:11], v[152:155], v[226:229], v[8:11]
	v_mfma_f32_16x16x32_bf16 v[60:63], v[148:151], v[198:201], v[60:63]
	v_mfma_f32_16x16x32_bf16 v[56:59], v[174:177], v[198:201], v[56:59]
	v_mfma_f32_16x16x32_bf16 v[48:51], v[148:151], v[214:217], v[48:51]
	v_mfma_f32_16x16x32_bf16 v[40:43], v[174:177], v[214:217], v[40:43]
	v_mfma_f32_16x16x32_bf16 v[32:35], v[148:151], v[222:225], v[32:35]
	v_mfma_f32_16x16x32_bf16 v[24:27], v[174:177], v[222:225], v[24:27]
	v_mfma_f32_16x16x32_bf16 v[16:19], v[148:151], v[230:233], v[16:19]
	v_mfma_f32_16x16x32_bf16 v[8:11], v[174:177], v[230:233], v[8:11]
	v_mfma_f32_16x16x32_bf16 v[52:55], v[178:181], v[194:197], v[52:55]
	v_mfma_f32_16x16x32_bf16 v[44:47], v[186:189], v[194:197], v[44:47]
	v_mfma_f32_16x16x32_bf16 v[36:39], v[178:181], v[210:213], v[36:39]
	v_mfma_f32_16x16x32_bf16 v[28:31], v[186:189], v[210:213], v[28:31]
	v_mfma_f32_16x16x32_bf16 v[20:23], v[178:181], v[218:221], v[20:23]
	v_mfma_f32_16x16x32_bf16 v[12:15], v[186:189], v[218:221], v[12:15]
	v_mfma_f32_16x16x32_bf16 v[4:7], v[178:181], v[226:229], v[4:7]
	v_mfma_f32_16x16x32_bf16 v[0:3], v[186:189], v[226:229], v[0:3]
	v_mfma_f32_16x16x32_bf16 v[52:55], v[182:185], v[198:201], v[52:55]
	v_mfma_f32_16x16x32_bf16 v[44:47], v[190:193], v[198:201], v[44:47]
	v_mfma_f32_16x16x32_bf16 v[36:39], v[182:185], v[214:217], v[36:39]
	v_mfma_f32_16x16x32_bf16 v[28:31], v[190:193], v[214:217], v[28:31]
	v_mfma_f32_16x16x32_bf16 v[20:23], v[182:185], v[222:225], v[20:23]
	v_mfma_f32_16x16x32_bf16 v[12:15], v[190:193], v[222:225], v[12:15]
	v_mfma_f32_16x16x32_bf16 v[4:7], v[182:185], v[230:233], v[4:7]
	v_mfma_f32_16x16x32_bf16 v[0:3], v[190:193], v[230:233], v[0:3]
	s_barrier
	s_add_i32 s56, s56, 2
	s_add_u32 s54, s54, 0x10000
	s_addc_u32 s55, s55, 0
	s_add_u32 s28, s28, 0x100
	s_addc_u32 s29, s29, 0
	s_cmp_gt_u32 s56, 5
	s_cbranch_scc0 .LBB0_2258
	s_and_b64 vcc, exec, s[14:15]
	s_cbranch_vccz .LBB0_2261
	s_barrier

.LBB0_2282:
	ds_read_b128 v[144:147], v155
	ds_read_b128 v[148:151], v155 offset:1024
	ds_read_b128 v[158:161], v155 offset:2048
	ds_read_b128 v[162:165], v155 offset:3072
	ds_read_b128 v[166:169], v156
	ds_read_b128 v[170:173], v156 offset:1024
	ds_read_b128 v[174:177], v156 offset:2048
	ds_read_b128 v[178:181], v156 offset:3072
	s_add_u32 s28, s26, 0xfffe0080
	s_addc_u32 s29, s27, -1
	s_cmp_eq_u32 s54, 4
	s_cselect_b32 s31, s15, s29
	s_cselect_b32 s30, s50, s28
	s_cselect_b32 s29, s17, s53
	s_cselect_b32 s28, s51, s52
	v_lshl_add_u64 v[204:205], s[26:27], 0, v[130:131]
	s_add_i32 m0, s23, 0xc000
	ds_read_b128 v[182:185], v157
	ds_read_b128 v[186:189], v157 offset:1024
	ds_read_b128 v[190:193], v157 offset:2048
	ds_read_b128 v[194:197], v157 offset:3072
	ds_read_b128 v[198:201], v157 offset:4096
	ds_read_b128 v[210:213], v157 offset:5120
	ds_read_b128 v[214:217], v157 offset:6144
	ds_read_b128 v[218:221], v157 offset:7168
	global_load_lds_dwordx4 v[204:205], off
	v_lshl_add_u64 v[204:205], s[26:27], 0, v[128:129]
	s_add_i32 m0, s23, 0xe000
	s_nop 0
	global_load_lds_dwordx4 v[204:205], off
	s_waitcnt vmcnt(8)
	s_waitcnt lgkmcnt(0)
	s_barrier
	s_waitcnt lgkmcnt(0)
	v_mfma_f32_16x16x32_bf16 v[124:127], v[144:147], v[182:185], v[124:127]
	v_mfma_f32_16x16x32_bf16 v[120:123], v[158:161], v[182:185], v[120:123]
	v_mfma_f32_16x16x32_bf16 v[112:115], v[144:147], v[190:193], v[112:115]
	v_mfma_f32_16x16x32_bf16 v[104:107], v[158:161], v[190:193], v[104:107]
	v_mfma_f32_16x16x32_bf16 v[92:95], v[144:147], v[198:201], v[92:95]
	v_mfma_f32_16x16x32_bf16 v[88:91], v[158:161], v[198:201], v[88:91]
	v_mfma_f32_16x16x32_bf16 v[80:83], v[144:147], v[214:217], v[80:83]
	v_mfma_f32_16x16x32_bf16 v[72:75], v[158:161], v[214:217], v[72:75]
	v_mfma_f32_16x16x32_bf16 v[124:127], v[148:151], v[186:189], v[124:127]
	v_mfma_f32_16x16x32_bf16 v[120:123], v[162:165], v[186:189], v[120:123]
	v_mfma_f32_16x16x32_bf16 v[112:115], v[148:151], v[194:197], v[112:115]
	v_mfma_f32_16x16x32_bf16 v[104:107], v[162:165], v[194:197], v[104:107]
	v_mfma_f32_16x16x32_bf16 v[92:95], v[148:151], v[210:213], v[92:95]
	v_mfma_f32_16x16x32_bf16 v[88:91], v[162:165], v[210:213], v[88:91]
	v_mfma_f32_16x16x32_bf16 v[80:83], v[148:151], v[218:221], v[80:83]
	v_mfma_f32_16x16x32_bf16 v[72:75], v[162:165], v[218:221], v[72:75]
	v_mfma_f32_16x16x32_bf16 v[116:119], v[166:169], v[182:185], v[116:119]
	v_mfma_f32_16x16x32_bf16 v[108:111], v[174:177], v[182:185], v[108:111]
	v_mfma_f32_16x16x32_bf16 v[100:103], v[166:169], v[190:193], v[100:103]
	v_mfma_f32_16x16x32_bf16 v[96:99], v[174:177], v[190:193], v[96:99]
	v_mfma_f32_16x16x32_bf16 v[84:87], v[166:169], v[198:201], v[84:87]
	v_mfma_f32_16x16x32_bf16 v[76:79], v[174:177], v[198:201], v[76:79]
	v_mfma_f32_16x16x32_bf16 v[68:71], v[166:169], v[214:217], v[68:71]
	v_mfma_f32_16x16x32_bf16 v[64:67], v[174:177], v[214:217], v[64:67]
	v_mfma_f32_16x16x32_bf16 v[116:119], v[170:173], v[186:189], v[116:119]
	v_mfma_f32_16x16x32_bf16 v[108:111], v[178:181], v[186:189], v[108:111]
	v_mfma_f32_16x16x32_bf16 v[100:103], v[170:173], v[194:197], v[100:103]
	v_mfma_f32_16x16x32_bf16 v[96:99], v[178:181], v[194:197], v[96:99]
	v_mfma_f32_16x16x32_bf16 v[84:87], v[170:173], v[210:213], v[84:87]
	v_mfma_f32_16x16x32_bf16 v[76:79], v[178:181], v[210:213], v[76:79]
	v_mfma_f32_16x16x32_bf16 v[68:71], v[170:173], v[218:221], v[68:71]
	v_mfma_f32_16x16x32_bf16 v[64:67], v[178:181], v[218:221], v[64:67]
	s_barrier
	s_add_i32 s55, s47, s40
	v_lshl_add_u64 v[204:205], s[28:29], 0, v[134:135]
	s_mov_b32 m0, s55
	ds_read_b128 v[182:185], v157 offset:16384
	ds_read_b128 v[186:189], v157 offset:17408
	ds_read_b128 v[190:193], v157 offset:18432
	ds_read_b128 v[194:197], v157 offset:19456
	ds_read_b128 v[198:201], v157 offset:20480
	ds_read_b128 v[210:213], v157 offset:21504
	ds_read_b128 v[214:217], v157 offset:22528
	ds_read_b128 v[218:221], v157 offset:23552
	global_load_lds_dwordx4 v[204:205], off
	s_add_i32 m0, s55, 0x2000
	s_add_u32 s56, s28, 0x4000
	v_lshl_add_u64 v[204:205], s[28:29], 0, v[138:139]
	s_addc_u32 s57, s29, 0
	s_add_i32 s55, s48, s40
	global_load_lds_dwordx4 v[204:205], off
	v_lshl_add_u64 v[204:205], s[56:57], 0, v[134:135]
	s_mov_b32 m0, s55
	v_lshl_add_u64 v[206:207], s[30:31], 0, v[136:137]
	global_load_lds_dwordx4 v[204:205], off
	v_lshl_add_u64 v[204:205], s[56:57], 0, v[138:139]
	s_add_i32 m0, s55, 0x2000
	s_nop 0
	global_load_lds_dwordx4 v[204:205], off
	v_lshl_add_u64 v[204:205], s[30:31], 0, v[132:133]
	s_mov_b32 m0, s23
	s_nop 0
	global_load_lds_dwordx4 v[204:205], off
	s_mov_b32 m0, s25
	s_nop 0
	global_load_lds_dwordx4 v[206:207], off
	s_waitcnt vmcnt(8)
	s_waitcnt lgkmcnt(0)
	s_barrier
	s_waitcnt lgkmcnt(0)
	v_mfma_f32_16x16x32_bf16 v[60:63], v[144:147], v[182:185], v[60:63]
	v_mfma_f32_16x16x32_bf16 v[56:59], v[158:161], v[182:185], v[56:59]
	v_mfma_f32_16x16x32_bf16 v[48:51], v[144:147], v[190:193], v[48:51]
	v_mfma_f32_16x16x32_bf16 v[40:43], v[158:161], v[190:193], v[40:43]
	v_mfma_f32_16x16x32_bf16 v[28:31], v[144:147], v[198:201], v[28:31]
	v_mfma_f32_16x16x32_bf16 v[24:27], v[158:161], v[198:201], v[24:27]
	v_mfma_f32_16x16x32_bf16 v[16:19], v[144:147], v[214:217], v[16:19]
	v_mfma_f32_16x16x32_bf16 v[8:11], v[158:161], v[214:217], v[8:11]
	v_mfma_f32_16x16x32_bf16 v[60:63], v[148:151], v[186:189], v[60:63]
	v_mfma_f32_16x16x32_bf16 v[56:59], v[162:165], v[186:189], v[56:59]
	v_mfma_f32_16x16x32_bf16 v[48:51], v[148:151], v[194:197], v[48:51]
	v_mfma_f32_16x16x32_bf16 v[40:43], v[162:165], v[194:197], v[40:43]
	v_mfma_f32_16x16x32_bf16 v[28:31], v[148:151], v[210:213], v[28:31]
	v_mfma_f32_16x16x32_bf16 v[24:27], v[162:165], v[210:213], v[24:27]
	v_mfma_f32_16x16x32_bf16 v[16:19], v[148:151], v[218:221], v[16:19]
	v_mfma_f32_16x16x32_bf16 v[8:11], v[162:165], v[218:221], v[8:11]
	v_mfma_f32_16x16x32_bf16 v[52:55], v[166:169], v[182:185], v[52:55]
	v_mfma_f32_16x16x32_bf16 v[44:47], v[174:177], v[182:185], v[44:47]
	v_mfma_f32_16x16x32_bf16 v[36:39], v[166:169], v[190:193], v[36:39]
	v_mfma_f32_16x16x32_bf16 v[32:35], v[174:177], v[190:193], v[32:35]
	v_mfma_f32_16x16x32_bf16 v[20:23], v[166:169], v[198:201], v[20:23]
	v_mfma_f32_16x16x32_bf16 v[12:15], v[174:177], v[198:201], v[12:15]
	v_mfma_f32_16x16x32_bf16 v[4:7], v[166:169], v[214:217], v[4:7]
	v_mfma_f32_16x16x32_bf16 v[0:3], v[174:177], v[214:217], v[0:3]
	v_mfma_f32_16x16x32_bf16 v[52:55], v[170:173], v[186:189], v[52:55]
	v_mfma_f32_16x16x32_bf16 v[44:47], v[178:181], v[186:189], v[44:47]
	v_mfma_f32_16x16x32_bf16 v[36:39], v[170:173], v[194:197], v[36:39]
	v_mfma_f32_16x16x32_bf16 v[32:35], v[178:181], v[194:197], v[32:35]
	v_mfma_f32_16x16x32_bf16 v[20:23], v[170:173], v[210:213], v[20:23]
	v_mfma_f32_16x16x32_bf16 v[12:15], v[178:181], v[210:213], v[12:15]
	v_mfma_f32_16x16x32_bf16 v[4:7], v[170:173], v[218:221], v[4:7]
	v_mfma_f32_16x16x32_bf16 v[0:3], v[178:181], v[218:221], v[0:3]
	s_barrier
	s_add_i32 s55, 0, 0x18000
	s_add_i32 s56, 0, 0x1c000
	v_add_u32_e32 v162, s55, v153
	v_add_u32_e32 v178, s56, v153
	ds_read_b128 v[144:147], v162
	ds_read_b128 v[148:151], v162 offset:1024
	ds_read_b128 v[158:161], v162 offset:2048
	ds_read_b128 v[162:165], v162 offset:3072
	ds_read_b128 v[166:169], v178
	ds_read_b128 v[170:173], v178 offset:1024
	ds_read_b128 v[174:177], v178 offset:2048
	ds_read_b128 v[178:181], v178 offset:3072
	s_add_u32 s30, s30, 0x20000
	s_addc_u32 s31, s31, 0
	s_mov_b32 m0, s41
	v_lshl_add_u64 v[222:223], s[30:31], 0, v[132:133]
	ds_read_b128 v[182:185], v157 offset:32768
	ds_read_b128 v[186:189], v157 offset:33792
	ds_read_b128 v[190:193], v157 offset:34816
	ds_read_b128 v[194:197], v157 offset:35840
	ds_read_b128 v[198:201], v157 offset:36864
	ds_read_b128 v[210:213], v157 offset:37888
	ds_read_b128 v[214:217], v157 offset:38912
	ds_read_b128 v[218:221], v157 offset:39936
	global_load_lds_dwordx4 v[222:223], off
	v_lshl_add_u64 v[222:223], s[30:31], 0, v[136:137]
	s_mov_b32 m0, s42
	s_nop 0
	global_load_lds_dwordx4 v[222:223], off
	s_waitcnt vmcnt(8)
	s_waitcnt lgkmcnt(0)
	s_barrier
	s_waitcnt lgkmcnt(0)
	v_mfma_f32_16x16x32_bf16 v[124:127], v[144:147], v[182:185], v[124:127]
	v_mfma_f32_16x16x32_bf16 v[120:123], v[158:161], v[182:185], v[120:123]
	v_mfma_f32_16x16x32_bf16 v[112:115], v[144:147], v[190:193], v[112:115]
	v_mfma_f32_16x16x32_bf16 v[104:107], v[158:161], v[190:193], v[104:107]
	v_mfma_f32_16x16x32_bf16 v[92:95], v[144:147], v[198:201], v[92:95]
	v_mfma_f32_16x16x32_bf16 v[88:91], v[158:161], v[198:201], v[88:91]
	v_mfma_f32_16x16x32_bf16 v[80:83], v[144:147], v[214:217], v[80:83]
	v_mfma_f32_16x16x32_bf16 v[72:75], v[158:161], v[214:217], v[72:75]
	v_mfma_f32_16x16x32_bf16 v[124:127], v[148:151], v[186:189], v[124:127]
	v_mfma_f32_16x16x32_bf16 v[120:123], v[162:165], v[186:189], v[120:123]
	v_mfma_f32_16x16x32_bf16 v[112:115], v[148:151], v[194:197], v[112:115]
	v_mfma_f32_16x16x32_bf16 v[104:107], v[162:165], v[194:197], v[104:107]
	v_mfma_f32_16x16x32_bf16 v[92:95], v[148:151], v[210:213], v[92:95]
	v_mfma_f32_16x16x32_bf16 v[88:91], v[162:165], v[210:213], v[88:91]
	v_mfma_f32_16x16x32_bf16 v[80:83], v[148:151], v[218:221], v[80:83]
	v_mfma_f32_16x16x32_bf16 v[72:75], v[162:165], v[218:221], v[72:75]
	v_mfma_f32_16x16x32_bf16 v[116:119], v[166:169], v[182:185], v[116:119]
	v_mfma_f32_16x16x32_bf16 v[108:111], v[174:177], v[182:185], v[108:111]
	v_mfma_f32_16x16x32_bf16 v[100:103], v[166:169], v[190:193], v[100:103]
	v_mfma_f32_16x16x32_bf16 v[96:99], v[174:177], v[190:193], v[96:99]
	v_mfma_f32_16x16x32_bf16 v[84:87], v[166:169], v[198:201], v[84:87]
	v_mfma_f32_16x16x32_bf16 v[76:79], v[174:177], v[198:201], v[76:79]
	v_mfma_f32_16x16x32_bf16 v[68:71], v[166:169], v[214:217], v[68:71]
	v_mfma_f32_16x16x32_bf16 v[64:67], v[174:177], v[214:217], v[64:67]
	v_mfma_f32_16x16x32_bf16 v[116:119], v[170:173], v[186:189], v[116:119]
	v_mfma_f32_16x16x32_bf16 v[108:111], v[178:181], v[186:189], v[108:111]
	v_mfma_f32_16x16x32_bf16 v[100:103], v[170:173], v[194:197], v[100:103]
	v_mfma_f32_16x16x32_bf16 v[96:99], v[178:181], v[194:197], v[96:99]
	v_mfma_f32_16x16x32_bf16 v[84:87], v[170:173], v[210:213], v[84:87]
	v_mfma_f32_16x16x32_bf16 v[76:79], v[178:181], v[210:213], v[76:79]
	v_mfma_f32_16x16x32_bf16 v[68:71], v[170:173], v[218:221], v[68:71]
	v_mfma_f32_16x16x32_bf16 v[64:67], v[178:181], v[218:221], v[64:67]
	s_barrier
	s_add_u32 s30, s28, 0x8000
	s_addc_u32 s31, s29, 0
	s_add_i32 s55, s55, s40
	v_lshl_add_u64 v[222:223], s[30:31], 0, v[134:135]
	s_mov_b32 m0, s55
	ds_read_b128 v[182:185], v157 offset:49152
	ds_read_b128 v[186:189], v157 offset:50176
	ds_read_b128 v[190:193], v157 offset:51200
	ds_read_b128 v[194:197], v157 offset:52224
	ds_read_b128 v[198:201], v157 offset:53248
	ds_read_b128 v[210:213], v157 offset:54272
	ds_read_b128 v[214:217], v157 offset:55296
	ds_read_b128 v[218:221], v157 offset:56320
	global_load_lds_dwordx4 v[222:223], off
	s_add_i32 m0, s55, 0x2000
	s_add_u32 s28, s28, 0xc000
	v_lshl_add_u64 v[222:223], s[30:31], 0, v[138:139]
	s_addc_u32 s29, s29, 0
	s_add_i32 s30, s56, s40
	global_load_lds_dwordx4 v[222:223], off
	v_lshl_add_u64 v[222:223], s[28:29], 0, v[134:135]
	s_mov_b32 m0, s30
	v_lshl_add_u64 v[204:205], v[204:205], 0, s[8:9]
	global_load_lds_dwordx4 v[222:223], off
	v_lshl_add_u64 v[222:223], s[28:29], 0, v[138:139]
	s_add_i32 m0, s30, 0x2000
	s_nop 0
	global_load_lds_dwordx4 v[222:223], off
	s_mov_b32 m0, s44
	s_nop 0
	global_load_lds_dwordx4 v[204:205], off
	v_lshl_add_u64 v[204:205], v[206:207], 0, s[8:9]
	s_mov_b32 m0, s45
	s_nop 0
	global_load_lds_dwordx4 v[204:205], off
	s_waitcnt vmcnt(8)
	s_waitcnt lgkmcnt(0)
	s_barrier
	s_waitcnt lgkmcnt(0)
	v_mfma_f32_16x16x32_bf16 v[60:63], v[144:147], v[182:185], v[60:63]
	v_mfma_f32_16x16x32_bf16 v[56:59], v[158:161], v[182:185], v[56:59]
	v_mfma_f32_16x16x32_bf16 v[48:51], v[144:147], v[190:193], v[48:51]
	v_mfma_f32_16x16x32_bf16 v[40:43], v[158:161], v[190:193], v[40:43]
	v_mfma_f32_16x16x32_bf16 v[28:31], v[144:147], v[198:201], v[28:31]
	v_mfma_f32_16x16x32_bf16 v[24:27], v[158:161], v[198:201], v[24:27]
	v_mfma_f32_16x16x32_bf16 v[16:19], v[144:147], v[214:217], v[16:19]
	v_mfma_f32_16x16x32_bf16 v[8:11], v[158:161], v[214:217], v[8:11]
	v_mfma_f32_16x16x32_bf16 v[60:63], v[148:151], v[186:189], v[60:63]
	v_mfma_f32_16x16x32_bf16 v[56:59], v[162:165], v[186:189], v[56:59]
	v_mfma_f32_16x16x32_bf16 v[48:51], v[148:151], v[194:197], v[48:51]
	v_mfma_f32_16x16x32_bf16 v[40:43], v[162:165], v[194:197], v[40:43]
	v_mfma_f32_16x16x32_bf16 v[28:31], v[148:151], v[210:213], v[28:31]
	v_mfma_f32_16x16x32_bf16 v[24:27], v[162:165], v[210:213], v[24:27]
	v_mfma_f32_16x16x32_bf16 v[16:19], v[148:151], v[218:221], v[16:19]
	v_mfma_f32_16x16x32_bf16 v[8:11], v[162:165], v[218:221], v[8:11]
	v_mfma_f32_16x16x32_bf16 v[52:55], v[166:169], v[182:185], v[52:55]
	v_mfma_f32_16x16x32_bf16 v[44:47], v[174:177], v[182:185], v[44:47]
	v_mfma_f32_16x16x32_bf16 v[36:39], v[166:169], v[190:193], v[36:39]
	v_mfma_f32_16x16x32_bf16 v[32:35], v[174:177], v[190:193], v[32:35]
	v_mfma_f32_16x16x32_bf16 v[20:23], v[166:169], v[198:201], v[20:23]
	v_mfma_f32_16x16x32_bf16 v[12:15], v[174:177], v[198:201], v[12:15]
	v_mfma_f32_16x16x32_bf16 v[4:7], v[166:169], v[214:217], v[4:7]
	v_mfma_f32_16x16x32_bf16 v[0:3], v[174:177], v[214:217], v[0:3]
	v_mfma_f32_16x16x32_bf16 v[52:55], v[170:173], v[186:189], v[52:55]
	v_mfma_f32_16x16x32_bf16 v[44:47], v[178:181], v[186:189], v[44:47]
	v_mfma_f32_16x16x32_bf16 v[36:39], v[170:173], v[194:197], v[36:39]
	v_mfma_f32_16x16x32_bf16 v[32:35], v[178:181], v[194:197], v[32:35]
	v_mfma_f32_16x16x32_bf16 v[20:23], v[170:173], v[210:213], v[20:23]
	v_mfma_f32_16x16x32_bf16 v[12:15], v[178:181], v[210:213], v[12:15]
	v_mfma_f32_16x16x32_bf16 v[4:7], v[170:173], v[218:221], v[4:7]
	v_mfma_f32_16x16x32_bf16 v[0:3], v[178:181], v[218:221], v[0:3]
	s_barrier
	s_add_i32 s54, s54, 2
	s_add_u32 s52, s52, 0x10000
	s_addc_u32 s53, s53, 0
	s_add_u32 s26, s26, 0x100
	s_addc_u32 s27, s27, 0
	s_cmp_gt_u32 s54, 5
	s_cbranch_scc0 .LBB0_2282
	s_and_b64 vcc, exec, s[10:11]
	s_cbranch_vccz .LBB0_2285
	s_barrier

.LBB0_2358:
	v_add_u32_e32 v168, s77, v182
	v_add_u32_e32 v204, s78, v182
	ds_read_b128 v[156:159], v168
	ds_read_b128 v[160:163], v168 offset:1024
	ds_read_b128 v[164:167], v168 offset:2048
	ds_read_b128 v[168:171], v168 offset:3072
	ds_read_b128 v[172:175], v204
	ds_read_b128 v[176:179], v204 offset:1024
	ds_read_b128 v[212:215], v204 offset:2048
	ds_read_b128 v[216:219], v204 offset:3072
	s_add_u32 s48, s46, 0xfffc0080
	s_addc_u32 s49, s47, -1
	s_cmp_eq_u32 s54, 12
	s_cselect_b32 s51, s35, s49
	s_cselect_b32 s50, s43, s48
	s_cselect_b32 s49, s37, s53
	s_cselect_b32 s48, s45, s52
	v_lshl_add_u64 v[204:205], s[46:47], 0, v[154:155]
	s_add_i32 m0, s65, 0xc000
	ds_read_b128 v[220:223], v199
	ds_read_b128 v[224:227], v199 offset:1024
	ds_read_b128 v[228:231], v199 offset:2048
	ds_read_b128 v[232:235], v199 offset:3072
	ds_read_b128 v[236:239], v199 offset:4096
	ds_read_b128 v[240:243], v199 offset:5120
	ds_read_b128 v[244:247], v199 offset:6144
	ds_read_b128 v[248:251], v199 offset:7168
	global_load_lds_dwordx4 v[204:205], off
	v_lshl_add_u64 v[204:205], s[46:47], 0, v[152:153]
	s_add_i32 m0, s65, 0xe000
	s_nop 0
	global_load_lds_dwordx4 v[204:205], off
	s_waitcnt vmcnt(8)
	s_waitcnt lgkmcnt(0)
	s_barrier
	s_waitcnt lgkmcnt(0)
	v_mfma_f32_16x16x32_bf16 v[124:127], v[156:159], v[220:223], v[124:127]
	v_mfma_f32_16x16x32_bf16 v[120:123], v[164:167], v[220:223], v[120:123]
	v_mfma_f32_16x16x32_bf16 v[116:119], v[156:159], v[228:231], v[116:119]
	v_mfma_f32_16x16x32_bf16 v[112:115], v[164:167], v[228:231], v[112:115]
	v_mfma_f32_16x16x32_bf16 v[92:95], v[156:159], v[236:239], v[92:95]
	v_mfma_f32_16x16x32_bf16 v[88:91], v[164:167], v[236:239], v[88:91]
	v_mfma_f32_16x16x32_bf16 v[84:87], v[156:159], v[244:247], v[84:87]
	v_mfma_f32_16x16x32_bf16 v[80:83], v[164:167], v[244:247], v[80:83]
	v_mfma_f32_16x16x32_bf16 v[124:127], v[160:163], v[224:227], v[124:127]
	v_mfma_f32_16x16x32_bf16 v[120:123], v[168:171], v[224:227], v[120:123]
	v_mfma_f32_16x16x32_bf16 v[116:119], v[160:163], v[232:235], v[116:119]
	v_mfma_f32_16x16x32_bf16 v[112:115], v[168:171], v[232:235], v[112:115]
	v_mfma_f32_16x16x32_bf16 v[92:95], v[160:163], v[240:243], v[92:95]
	v_mfma_f32_16x16x32_bf16 v[88:91], v[168:171], v[240:243], v[88:91]
	v_mfma_f32_16x16x32_bf16 v[84:87], v[160:163], v[248:251], v[84:87]
	v_mfma_f32_16x16x32_bf16 v[80:83], v[168:171], v[248:251], v[80:83]
	v_mfma_f32_16x16x32_bf16 v[108:111], v[172:175], v[220:223], v[108:111]
	v_mfma_f32_16x16x32_bf16 v[104:107], v[212:215], v[220:223], v[104:107]
	v_mfma_f32_16x16x32_bf16 v[100:103], v[172:175], v[228:231], v[100:103]
	v_mfma_f32_16x16x32_bf16 v[96:99], v[212:215], v[228:231], v[96:99]
	v_mfma_f32_16x16x32_bf16 v[76:79], v[172:175], v[236:239], v[76:79]
	v_mfma_f32_16x16x32_bf16 v[72:75], v[212:215], v[236:239], v[72:75]
	v_mfma_f32_16x16x32_bf16 v[68:71], v[172:175], v[244:247], v[68:71]
	v_mfma_f32_16x16x32_bf16 v[64:67], v[212:215], v[244:247], v[64:67]
	v_mfma_f32_16x16x32_bf16 v[108:111], v[176:179], v[224:227], v[108:111]
	v_mfma_f32_16x16x32_bf16 v[104:107], v[216:219], v[224:227], v[104:107]
	v_mfma_f32_16x16x32_bf16 v[100:103], v[176:179], v[232:235], v[100:103]
	v_mfma_f32_16x16x32_bf16 v[96:99], v[216:219], v[232:235], v[96:99]
	v_mfma_f32_16x16x32_bf16 v[76:79], v[176:179], v[240:243], v[76:79]
	v_mfma_f32_16x16x32_bf16 v[72:75], v[216:219], v[240:243], v[72:75]
	v_mfma_f32_16x16x32_bf16 v[68:71], v[176:179], v[248:251], v[68:71]
	v_mfma_f32_16x16x32_bf16 v[64:67], v[216:219], v[248:251], v[64:67]
	s_barrier
	s_add_i32 s55, s77, s64
	v_lshl_add_u64 v[204:205], s[48:49], 0, v[130:131]
	s_mov_b32 m0, s55
	ds_read_b128 v[220:223], v199 offset:16384
	ds_read_b128 v[224:227], v199 offset:17408
	ds_read_b128 v[228:231], v199 offset:18432
	ds_read_b128 v[232:235], v199 offset:19456
	ds_read_b128 v[236:239], v199 offset:20480
	ds_read_b128 v[240:243], v199 offset:21504
	ds_read_b128 v[244:247], v199 offset:22528
	ds_read_b128 v[248:251], v199 offset:23552
	global_load_lds_dwordx4 v[204:205], off
	s_add_i32 m0, s55, 0x2000
	s_add_u32 s56, s48, 0x4000
	v_lshl_add_u64 v[204:205], s[48:49], 0, v[134:135]
	s_addc_u32 s57, s49, 0
	s_add_i32 s55, s78, s64
	global_load_lds_dwordx4 v[204:205], off
	v_lshl_add_u64 v[204:205], s[56:57], 0, v[130:131]
	s_mov_b32 m0, s55
	v_lshl_add_u64 v[206:207], s[50:51], 0, v[132:133]
	global_load_lds_dwordx4 v[204:205], off
	v_lshl_add_u64 v[204:205], s[56:57], 0, v[134:135]
	s_add_i32 m0, s55, 0x2000
	s_nop 0
	global_load_lds_dwordx4 v[204:205], off
	v_lshl_add_u64 v[204:205], s[50:51], 0, v[128:129]
	s_mov_b32 m0, s65
	s_nop 0
	global_load_lds_dwordx4 v[204:205], off
	s_mov_b32 m0, s66
	s_nop 0
	global_load_lds_dwordx4 v[206:207], off
	s_waitcnt vmcnt(8)
	s_waitcnt lgkmcnt(0)
	s_barrier
	s_waitcnt lgkmcnt(0)
	v_mfma_f32_16x16x32_bf16 v[60:63], v[156:159], v[220:223], v[60:63]
	v_mfma_f32_16x16x32_bf16 v[56:59], v[164:167], v[220:223], v[56:59]
	v_mfma_f32_16x16x32_bf16 v[52:55], v[156:159], v[228:231], v[52:55]
	v_mfma_f32_16x16x32_bf16 v[48:51], v[164:167], v[228:231], v[48:51]
	v_mfma_f32_16x16x32_bf16 v[28:31], v[156:159], v[236:239], v[28:31]
	v_mfma_f32_16x16x32_bf16 v[24:27], v[164:167], v[236:239], v[24:27]
	v_mfma_f32_16x16x32_bf16 v[20:23], v[156:159], v[244:247], v[20:23]
	v_mfma_f32_16x16x32_bf16 v[12:15], v[164:167], v[244:247], v[12:15]
	v_mfma_f32_16x16x32_bf16 v[60:63], v[160:163], v[224:227], v[60:63]
	v_mfma_f32_16x16x32_bf16 v[56:59], v[168:171], v[224:227], v[56:59]
	v_mfma_f32_16x16x32_bf16 v[52:55], v[160:163], v[232:235], v[52:55]
	v_mfma_f32_16x16x32_bf16 v[48:51], v[168:171], v[232:235], v[48:51]
	v_mfma_f32_16x16x32_bf16 v[28:31], v[160:163], v[240:243], v[28:31]
	v_mfma_f32_16x16x32_bf16 v[24:27], v[168:171], v[240:243], v[24:27]
	v_mfma_f32_16x16x32_bf16 v[20:23], v[160:163], v[248:251], v[20:23]
	v_mfma_f32_16x16x32_bf16 v[12:15], v[168:171], v[248:251], v[12:15]
	v_mfma_f32_16x16x32_bf16 v[44:47], v[172:175], v[220:223], v[44:47]
	v_mfma_f32_16x16x32_bf16 v[40:43], v[212:215], v[220:223], v[40:43]
	v_mfma_f32_16x16x32_bf16 v[36:39], v[172:175], v[228:231], v[36:39]
	v_mfma_f32_16x16x32_bf16 v[32:35], v[212:215], v[228:231], v[32:35]
	v_mfma_f32_16x16x32_bf16 v[16:19], v[172:175], v[236:239], v[16:19]
	v_mfma_f32_16x16x32_bf16 v[8:11], v[212:215], v[236:239], v[8:11]
	v_mfma_f32_16x16x32_bf16 v[4:7], v[172:175], v[244:247], v[4:7]
	v_mfma_f32_16x16x32_bf16 v[0:3], v[212:215], v[244:247], v[0:3]
	v_mfma_f32_16x16x32_bf16 v[44:47], v[176:179], v[224:227], v[44:47]
	v_mfma_f32_16x16x32_bf16 v[40:43], v[216:219], v[224:227], v[40:43]
	v_mfma_f32_16x16x32_bf16 v[36:39], v[176:179], v[232:235], v[36:39]
	v_mfma_f32_16x16x32_bf16 v[32:35], v[216:219], v[232:235], v[32:35]
	v_mfma_f32_16x16x32_bf16 v[16:19], v[176:179], v[240:243], v[16:19]
	v_mfma_f32_16x16x32_bf16 v[8:11], v[216:219], v[240:243], v[8:11]
	v_mfma_f32_16x16x32_bf16 v[4:7], v[176:179], v[248:251], v[4:7]
	v_mfma_f32_16x16x32_bf16 v[0:3], v[216:219], v[248:251], v[0:3]
	s_barrier
	s_add_i32 s55, 0, 0x18000
	s_add_i32 s56, 0, 0x1c000
	v_add_u32_e32 v168, s55, v182
	v_add_u32_e32 v216, s56, v182
	ds_read_b128 v[156:159], v168
	ds_read_b128 v[160:163], v168 offset:1024
	ds_read_b128 v[164:167], v168 offset:2048
	ds_read_b128 v[168:171], v168 offset:3072
	ds_read_b128 v[172:175], v216
	ds_read_b128 v[176:179], v216 offset:1024
	ds_read_b128 v[212:215], v216 offset:2048
	ds_read_b128 v[216:219], v216 offset:3072
	s_add_u32 s50, s50, 0x40000
	s_addc_u32 s51, s51, 0
	s_mov_b32 m0, s67
	v_lshl_add_u64 v[252:253], s[50:51], 0, v[128:129]
	ds_read_b128 v[220:223], v199 offset:32768
	ds_read_b128 v[224:227], v199 offset:33792
	ds_read_b128 v[228:231], v199 offset:34816
	ds_read_b128 v[232:235], v199 offset:35840
	ds_read_b128 v[236:239], v199 offset:36864
	ds_read_b128 v[240:243], v199 offset:37888
	ds_read_b128 v[244:247], v199 offset:38912
	ds_read_b128 v[248:251], v199 offset:39936
	global_load_lds_dwordx4 v[252:253], off
	v_lshl_add_u64 v[252:253], s[50:51], 0, v[132:133]
	s_mov_b32 m0, s68
	s_nop 0
	global_load_lds_dwordx4 v[252:253], off
	s_waitcnt vmcnt(8)
	s_waitcnt lgkmcnt(0)
	s_barrier
	s_waitcnt lgkmcnt(0)
	v_mfma_f32_16x16x32_bf16 v[124:127], v[156:159], v[220:223], v[124:127]
	v_mfma_f32_16x16x32_bf16 v[120:123], v[164:167], v[220:223], v[120:123]
	v_mfma_f32_16x16x32_bf16 v[116:119], v[156:159], v[228:231], v[116:119]
	v_mfma_f32_16x16x32_bf16 v[112:115], v[164:167], v[228:231], v[112:115]
	v_mfma_f32_16x16x32_bf16 v[92:95], v[156:159], v[236:239], v[92:95]
	v_mfma_f32_16x16x32_bf16 v[88:91], v[164:167], v[236:239], v[88:91]
	v_mfma_f32_16x16x32_bf16 v[84:87], v[156:159], v[244:247], v[84:87]
	v_mfma_f32_16x16x32_bf16 v[80:83], v[164:167], v[244:247], v[80:83]
	v_mfma_f32_16x16x32_bf16 v[124:127], v[160:163], v[224:227], v[124:127]
	v_mfma_f32_16x16x32_bf16 v[120:123], v[168:171], v[224:227], v[120:123]
	v_mfma_f32_16x16x32_bf16 v[116:119], v[160:163], v[232:235], v[116:119]
	v_mfma_f32_16x16x32_bf16 v[112:115], v[168:171], v[232:235], v[112:115]
	v_mfma_f32_16x16x32_bf16 v[92:95], v[160:163], v[240:243], v[92:95]
	v_mfma_f32_16x16x32_bf16 v[88:91], v[168:171], v[240:243], v[88:91]
	v_mfma_f32_16x16x32_bf16 v[84:87], v[160:163], v[248:251], v[84:87]
	v_mfma_f32_16x16x32_bf16 v[80:83], v[168:171], v[248:251], v[80:83]
	v_mfma_f32_16x16x32_bf16 v[108:111], v[172:175], v[220:223], v[108:111]
	v_mfma_f32_16x16x32_bf16 v[104:107], v[212:215], v[220:223], v[104:107]
	v_mfma_f32_16x16x32_bf16 v[100:103], v[172:175], v[228:231], v[100:103]
	v_mfma_f32_16x16x32_bf16 v[96:99], v[212:215], v[228:231], v[96:99]
	v_mfma_f32_16x16x32_bf16 v[76:79], v[172:175], v[236:239], v[76:79]
	v_mfma_f32_16x16x32_bf16 v[72:75], v[212:215], v[236:239], v[72:75]
	v_mfma_f32_16x16x32_bf16 v[68:71], v[172:175], v[244:247], v[68:71]
	v_mfma_f32_16x16x32_bf16 v[64:67], v[212:215], v[244:247], v[64:67]
	v_mfma_f32_16x16x32_bf16 v[108:111], v[176:179], v[224:227], v[108:111]
	v_mfma_f32_16x16x32_bf16 v[104:107], v[216:219], v[224:227], v[104:107]
	v_mfma_f32_16x16x32_bf16 v[100:103], v[176:179], v[232:235], v[100:103]
	v_mfma_f32_16x16x32_bf16 v[96:99], v[216:219], v[232:235], v[96:99]
	v_mfma_f32_16x16x32_bf16 v[76:79], v[176:179], v[240:243], v[76:79]
	v_mfma_f32_16x16x32_bf16 v[72:75], v[216:219], v[240:243], v[72:75]
	v_mfma_f32_16x16x32_bf16 v[68:71], v[176:179], v[248:251], v[68:71]
	v_mfma_f32_16x16x32_bf16 v[64:67], v[216:219], v[248:251], v[64:67]
	s_barrier
	s_add_u32 s50, s48, 0x8000
	s_addc_u32 s51, s49, 0
	s_add_i32 s55, s55, s64
	v_lshl_add_u64 v[252:253], s[50:51], 0, v[130:131]
	s_mov_b32 m0, s55
	ds_read_b128 v[220:223], v199 offset:49152
	ds_read_b128 v[224:227], v199 offset:50176
	ds_read_b128 v[228:231], v199 offset:51200
	ds_read_b128 v[232:235], v199 offset:52224
	ds_read_b128 v[236:239], v199 offset:53248
	ds_read_b128 v[240:243], v199 offset:54272
	ds_read_b128 v[244:247], v199 offset:55296
	ds_read_b128 v[248:251], v199 offset:56320
	global_load_lds_dwordx4 v[252:253], off
	s_add_i32 m0, s55, 0x2000
	s_add_u32 s48, s48, 0xc000
	v_lshl_add_u64 v[252:253], s[50:51], 0, v[134:135]
	s_addc_u32 s49, s49, 0
	s_add_i32 s50, s56, s64
	global_load_lds_dwordx4 v[252:253], off
	v_lshl_add_u64 v[252:253], s[48:49], 0, v[130:131]
	s_mov_b32 m0, s50
	v_lshl_add_u64 v[204:205], v[204:205], 0, s[14:15]
	global_load_lds_dwordx4 v[252:253], off
	v_lshl_add_u64 v[252:253], s[48:49], 0, v[134:135]
	s_add_i32 m0, s50, 0x2000
	s_nop 0
	global_load_lds_dwordx4 v[252:253], off
	s_mov_b32 m0, s74
	s_nop 0
	global_load_lds_dwordx4 v[204:205], off
	v_lshl_add_u64 v[204:205], v[206:207], 0, s[14:15]
	s_mov_b32 m0, s75
	s_nop 0
	global_load_lds_dwordx4 v[204:205], off
	s_waitcnt vmcnt(8)
	s_waitcnt lgkmcnt(0)
	s_barrier
	s_waitcnt lgkmcnt(0)
	v_mfma_f32_16x16x32_bf16 v[60:63], v[156:159], v[220:223], v[60:63]
	v_mfma_f32_16x16x32_bf16 v[56:59], v[164:167], v[220:223], v[56:59]
	v_mfma_f32_16x16x32_bf16 v[52:55], v[156:159], v[228:231], v[52:55]
	v_mfma_f32_16x16x32_bf16 v[48:51], v[164:167], v[228:231], v[48:51]
	v_mfma_f32_16x16x32_bf16 v[28:31], v[156:159], v[236:239], v[28:31]
	v_mfma_f32_16x16x32_bf16 v[24:27], v[164:167], v[236:239], v[24:27]
	v_mfma_f32_16x16x32_bf16 v[20:23], v[156:159], v[244:247], v[20:23]
	v_mfma_f32_16x16x32_bf16 v[12:15], v[164:167], v[244:247], v[12:15]
	v_mfma_f32_16x16x32_bf16 v[60:63], v[160:163], v[224:227], v[60:63]
	v_mfma_f32_16x16x32_bf16 v[56:59], v[168:171], v[224:227], v[56:59]
	v_mfma_f32_16x16x32_bf16 v[52:55], v[160:163], v[232:235], v[52:55]
	v_mfma_f32_16x16x32_bf16 v[48:51], v[168:171], v[232:235], v[48:51]
	v_mfma_f32_16x16x32_bf16 v[28:31], v[160:163], v[240:243], v[28:31]
	v_mfma_f32_16x16x32_bf16 v[24:27], v[168:171], v[240:243], v[24:27]
	v_mfma_f32_16x16x32_bf16 v[20:23], v[160:163], v[248:251], v[20:23]
	v_mfma_f32_16x16x32_bf16 v[12:15], v[168:171], v[248:251], v[12:15]
	v_mfma_f32_16x16x32_bf16 v[44:47], v[172:175], v[220:223], v[44:47]
	v_mfma_f32_16x16x32_bf16 v[40:43], v[212:215], v[220:223], v[40:43]
	v_mfma_f32_16x16x32_bf16 v[36:39], v[172:175], v[228:231], v[36:39]
	v_mfma_f32_16x16x32_bf16 v[32:35], v[212:215], v[228:231], v[32:35]
	v_mfma_f32_16x16x32_bf16 v[16:19], v[172:175], v[236:239], v[16:19]
	v_mfma_f32_16x16x32_bf16 v[8:11], v[212:215], v[236:239], v[8:11]
	v_mfma_f32_16x16x32_bf16 v[4:7], v[172:175], v[244:247], v[4:7]
	v_mfma_f32_16x16x32_bf16 v[0:3], v[212:215], v[244:247], v[0:3]
	v_mfma_f32_16x16x32_bf16 v[44:47], v[176:179], v[224:227], v[44:47]
	v_mfma_f32_16x16x32_bf16 v[40:43], v[216:219], v[224:227], v[40:43]
	v_mfma_f32_16x16x32_bf16 v[36:39], v[176:179], v[232:235], v[36:39]
	v_mfma_f32_16x16x32_bf16 v[32:35], v[216:219], v[232:235], v[32:35]
	v_mfma_f32_16x16x32_bf16 v[16:19], v[176:179], v[240:243], v[16:19]
	v_mfma_f32_16x16x32_bf16 v[8:11], v[216:219], v[240:243], v[8:11]
	v_mfma_f32_16x16x32_bf16 v[4:7], v[176:179], v[248:251], v[4:7]
	v_mfma_f32_16x16x32_bf16 v[0:3], v[216:219], v[248:251], v[0:3]
	s_barrier
	s_add_i32 s54, s54, 2
	s_add_u32 s52, s52, 0x10000
	s_addc_u32 s53, s53, 0
	s_add_u32 s46, s46, 0x100
	s_addc_u32 s47, s47, 0
	s_cmp_gt_u32 s54, 13
	s_cbranch_scc0 .LBB0_2358
	s_and_b64 vcc, exec, s[16:17]
	s_cbranch_vccz .LBB0_2361
	s_barrier

.LBB0_2519:
	ds_read_b128 v[144:147], v178
	ds_read_b128 v[148:151], v178 offset:1024
	ds_read_b128 v[152:155], v178 offset:2048
	ds_read_b128 v[156:159], v178 offset:3072
	ds_read_b128 v[160:163], v179
	ds_read_b128 v[164:167], v179 offset:1024
	ds_read_b128 v[182:185], v179 offset:2048
	ds_read_b128 v[186:189], v179 offset:3072
	s_add_u32 s34, s30, 0x4000
	s_addc_u32 s35, s31, 0
	s_cmp_eq_u32 s64, 40
	s_cselect_b32 s38, s4, s34
	s_cselect_b32 s39, s5, s35
	s_cselect_b32 s36, s28, s62
	s_cselect_b32 s37, s29, s63
	s_add_u32 s34, s38, 0x8000
	s_addc_u32 s35, s39, 0
	v_lshl_add_u64 v[222:223], s[30:31], 0, v[138:139]
	s_add_i32 m0, s42, 0xc000
	ds_read_b128 v[190:193], v180
	ds_read_b128 v[194:197], v180 offset:1024
	ds_read_b128 v[198:201], v180 offset:2048
	ds_read_b128 v[202:205], v180 offset:3072
	ds_read_b128 v[206:209], v180 offset:4096
	ds_read_b128 v[210:213], v180 offset:5120
	ds_read_b128 v[214:217], v180 offset:6144
	ds_read_b128 v[218:221], v180 offset:7168
	global_load_lds_dwordx4 v[222:223], off
	v_lshl_add_u64 v[222:223], s[30:31], 0, v[136:137]
	s_add_i32 m0, s42, 0xe000
	s_nop 0
	global_load_lds_dwordx4 v[222:223], off
	s_waitcnt vmcnt(8)
	s_waitcnt lgkmcnt(0)
	s_barrier
	s_waitcnt lgkmcnt(0)
	v_mfma_f32_16x16x32_bf16 v[124:127], v[144:147], v[190:193], v[124:127]
	v_mfma_f32_16x16x32_bf16 v[120:123], v[152:155], v[190:193], v[120:123]
	v_mfma_f32_16x16x32_bf16 v[116:119], v[144:147], v[198:201], v[116:119]
	v_mfma_f32_16x16x32_bf16 v[112:115], v[152:155], v[198:201], v[112:115]
	v_mfma_f32_16x16x32_bf16 v[92:95], v[144:147], v[206:209], v[92:95]
	v_mfma_f32_16x16x32_bf16 v[88:91], v[152:155], v[206:209], v[88:91]
	v_mfma_f32_16x16x32_bf16 v[84:87], v[144:147], v[214:217], v[84:87]
	v_mfma_f32_16x16x32_bf16 v[80:83], v[152:155], v[214:217], v[80:83]
	v_mfma_f32_16x16x32_bf16 v[124:127], v[148:151], v[194:197], v[124:127]
	v_mfma_f32_16x16x32_bf16 v[120:123], v[156:159], v[194:197], v[120:123]
	v_mfma_f32_16x16x32_bf16 v[116:119], v[148:151], v[202:205], v[116:119]
	v_mfma_f32_16x16x32_bf16 v[112:115], v[156:159], v[202:205], v[112:115]
	v_mfma_f32_16x16x32_bf16 v[92:95], v[148:151], v[210:213], v[92:95]
	v_mfma_f32_16x16x32_bf16 v[88:91], v[156:159], v[210:213], v[88:91]
	v_mfma_f32_16x16x32_bf16 v[84:87], v[148:151], v[218:221], v[84:87]
	v_mfma_f32_16x16x32_bf16 v[80:83], v[156:159], v[218:221], v[80:83]
	v_mfma_f32_16x16x32_bf16 v[108:111], v[160:163], v[190:193], v[108:111]
	v_mfma_f32_16x16x32_bf16 v[104:107], v[182:185], v[190:193], v[104:107]
	v_mfma_f32_16x16x32_bf16 v[100:103], v[160:163], v[198:201], v[100:103]
	v_mfma_f32_16x16x32_bf16 v[96:99], v[182:185], v[198:201], v[96:99]
	v_mfma_f32_16x16x32_bf16 v[76:79], v[160:163], v[206:209], v[76:79]
	v_mfma_f32_16x16x32_bf16 v[72:75], v[182:185], v[206:209], v[72:75]
	v_mfma_f32_16x16x32_bf16 v[68:71], v[160:163], v[214:217], v[68:71]
	v_mfma_f32_16x16x32_bf16 v[64:67], v[182:185], v[214:217], v[64:67]
	v_mfma_f32_16x16x32_bf16 v[108:111], v[164:167], v[194:197], v[108:111]
	v_mfma_f32_16x16x32_bf16 v[104:107], v[186:189], v[194:197], v[104:107]
	v_mfma_f32_16x16x32_bf16 v[100:103], v[164:167], v[202:205], v[100:103]
	v_mfma_f32_16x16x32_bf16 v[96:99], v[186:189], v[202:205], v[96:99]
	v_mfma_f32_16x16x32_bf16 v[76:79], v[164:167], v[210:213], v[76:79]
	v_mfma_f32_16x16x32_bf16 v[72:75], v[186:189], v[210:213], v[72:75]
	v_mfma_f32_16x16x32_bf16 v[68:71], v[164:167], v[218:221], v[68:71]
	v_mfma_f32_16x16x32_bf16 v[64:67], v[186:189], v[218:221], v[64:67]
	s_barrier
	s_add_i32 s65, s55, s41
	v_lshl_add_u64 v[222:223], s[36:37], 0, v[128:129]
	s_mov_b32 m0, s65
	ds_read_b128 v[190:193], v180 offset:16384
	ds_read_b128 v[194:197], v180 offset:17408
	ds_read_b128 v[198:201], v180 offset:18432
	ds_read_b128 v[202:205], v180 offset:19456
	ds_read_b128 v[206:209], v180 offset:20480
	ds_read_b128 v[210:213], v180 offset:21504
	ds_read_b128 v[214:217], v180 offset:22528
	ds_read_b128 v[218:221], v180 offset:23552
	global_load_lds_dwordx4 v[222:223], off
	s_add_i32 m0, s65, 0x2000
	s_add_u32 s66, s36, 0x4000
	v_lshl_add_u64 v[222:223], s[36:37], 0, v[130:131]
	s_addc_u32 s67, s37, 0
	s_add_i32 s65, s56, s41
	global_load_lds_dwordx4 v[222:223], off
	v_lshl_add_u64 v[222:223], s[66:67], 0, v[128:129]
	s_mov_b32 m0, s65
	s_nop 0
	global_load_lds_dwordx4 v[222:223], off
	v_lshl_add_u64 v[222:223], s[66:67], 0, v[130:131]
	s_add_i32 m0, s65, 0x2000
	s_nop 0
	global_load_lds_dwordx4 v[222:223], off
	v_lshl_add_u64 v[222:223], s[38:39], 0, v[128:129]
	s_mov_b32 m0, s42
	s_nop 0
	global_load_lds_dwordx4 v[222:223], off
	v_lshl_add_u64 v[222:223], s[38:39], 0, v[130:131]
	s_mov_b32 m0, s43
	s_nop 0
	global_load_lds_dwordx4 v[222:223], off
	s_waitcnt vmcnt(8)
	s_waitcnt lgkmcnt(0)
	s_barrier
	s_waitcnt lgkmcnt(0)
	v_mfma_f32_16x16x32_bf16 v[60:63], v[144:147], v[190:193], v[60:63]
	v_mfma_f32_16x16x32_bf16 v[56:59], v[152:155], v[190:193], v[56:59]
	v_mfma_f32_16x16x32_bf16 v[52:55], v[144:147], v[198:201], v[52:55]
	v_mfma_f32_16x16x32_bf16 v[48:51], v[152:155], v[198:201], v[48:51]
	v_mfma_f32_16x16x32_bf16 v[28:31], v[144:147], v[206:209], v[28:31]
	v_mfma_f32_16x16x32_bf16 v[24:27], v[152:155], v[206:209], v[24:27]
	v_mfma_f32_16x16x32_bf16 v[20:23], v[144:147], v[214:217], v[20:23]
	v_mfma_f32_16x16x32_bf16 v[12:15], v[152:155], v[214:217], v[12:15]
	v_mfma_f32_16x16x32_bf16 v[60:63], v[148:151], v[194:197], v[60:63]
	v_mfma_f32_16x16x32_bf16 v[56:59], v[156:159], v[194:197], v[56:59]
	v_mfma_f32_16x16x32_bf16 v[52:55], v[148:151], v[202:205], v[52:55]
	v_mfma_f32_16x16x32_bf16 v[48:51], v[156:159], v[202:205], v[48:51]
	v_mfma_f32_16x16x32_bf16 v[28:31], v[148:151], v[210:213], v[28:31]
	v_mfma_f32_16x16x32_bf16 v[24:27], v[156:159], v[210:213], v[24:27]
	v_mfma_f32_16x16x32_bf16 v[20:23], v[148:151], v[218:221], v[20:23]
	v_mfma_f32_16x16x32_bf16 v[12:15], v[156:159], v[218:221], v[12:15]
	v_mfma_f32_16x16x32_bf16 v[44:47], v[160:163], v[190:193], v[44:47]
	v_mfma_f32_16x16x32_bf16 v[40:43], v[182:185], v[190:193], v[40:43]
	v_mfma_f32_16x16x32_bf16 v[36:39], v[160:163], v[198:201], v[36:39]
	v_mfma_f32_16x16x32_bf16 v[32:35], v[182:185], v[198:201], v[32:35]
	v_mfma_f32_16x16x32_bf16 v[16:19], v[160:163], v[206:209], v[16:19]
	v_mfma_f32_16x16x32_bf16 v[8:11], v[182:185], v[206:209], v[8:11]
	v_mfma_f32_16x16x32_bf16 v[4:7], v[160:163], v[214:217], v[4:7]
	v_mfma_f32_16x16x32_bf16 v[0:3], v[182:185], v[214:217], v[0:3]
	v_mfma_f32_16x16x32_bf16 v[44:47], v[164:167], v[194:197], v[44:47]
	v_mfma_f32_16x16x32_bf16 v[40:43], v[186:189], v[194:197], v[40:43]
	v_mfma_f32_16x16x32_bf16 v[36:39], v[164:167], v[202:205], v[36:39]
	v_mfma_f32_16x16x32_bf16 v[32:35], v[186:189], v[202:205], v[32:35]
	v_mfma_f32_16x16x32_bf16 v[16:19], v[164:167], v[210:213], v[16:19]
	v_mfma_f32_16x16x32_bf16 v[8:11], v[186:189], v[210:213], v[8:11]
	v_mfma_f32_16x16x32_bf16 v[4:7], v[164:167], v[218:221], v[4:7]
	v_mfma_f32_16x16x32_bf16 v[0:3], v[186:189], v[218:221], v[0:3]
	s_barrier
	s_add_i32 s65, 0, 0x18000
	s_add_i32 s66, 0, 0x1c000
	v_add_u32_e32 v156, s65, v170
	v_add_u32_e32 v186, s66, v170
	ds_read_b128 v[144:147], v156
	ds_read_b128 v[148:151], v156 offset:1024
	ds_read_b128 v[152:155], v156 offset:2048
	ds_read_b128 v[156:159], v156 offset:3072
	ds_read_b128 v[160:163], v186
	ds_read_b128 v[164:167], v186 offset:1024
	ds_read_b128 v[182:185], v186 offset:2048
	ds_read_b128 v[186:189], v186 offset:3072
	s_add_u32 s38, s38, 0x4000
	s_addc_u32 s39, s39, 0
	s_mov_b32 m0, s44
	v_lshl_add_u64 v[222:223], s[38:39], 0, v[128:129]
	ds_read_b128 v[190:193], v180 offset:32768
	ds_read_b128 v[194:197], v180 offset:33792
	ds_read_b128 v[198:201], v180 offset:34816
	ds_read_b128 v[202:205], v180 offset:35840
	ds_read_b128 v[206:209], v180 offset:36864
	ds_read_b128 v[210:213], v180 offset:37888
	ds_read_b128 v[214:217], v180 offset:38912
	ds_read_b128 v[218:221], v180 offset:39936
	global_load_lds_dwordx4 v[222:223], off
	v_lshl_add_u64 v[222:223], s[38:39], 0, v[130:131]
	s_mov_b32 m0, s45
	s_nop 0
	global_load_lds_dwordx4 v[222:223], off
	s_waitcnt vmcnt(8)
	s_waitcnt lgkmcnt(0)
	s_barrier
	s_waitcnt lgkmcnt(0)
	v_mfma_f32_16x16x32_bf16 v[124:127], v[144:147], v[190:193], v[124:127]
	v_mfma_f32_16x16x32_bf16 v[120:123], v[152:155], v[190:193], v[120:123]
	v_mfma_f32_16x16x32_bf16 v[116:119], v[144:147], v[198:201], v[116:119]
	v_mfma_f32_16x16x32_bf16 v[112:115], v[152:155], v[198:201], v[112:115]
	v_mfma_f32_16x16x32_bf16 v[92:95], v[144:147], v[206:209], v[92:95]
	v_mfma_f32_16x16x32_bf16 v[88:91], v[152:155], v[206:209], v[88:91]
	v_mfma_f32_16x16x32_bf16 v[84:87], v[144:147], v[214:217], v[84:87]
	v_mfma_f32_16x16x32_bf16 v[80:83], v[152:155], v[214:217], v[80:83]
	v_mfma_f32_16x16x32_bf16 v[124:127], v[148:151], v[194:197], v[124:127]
	v_mfma_f32_16x16x32_bf16 v[120:123], v[156:159], v[194:197], v[120:123]
	v_mfma_f32_16x16x32_bf16 v[116:119], v[148:151], v[202:205], v[116:119]
	v_mfma_f32_16x16x32_bf16 v[112:115], v[156:159], v[202:205], v[112:115]
	v_mfma_f32_16x16x32_bf16 v[92:95], v[148:151], v[210:213], v[92:95]
	v_mfma_f32_16x16x32_bf16 v[88:91], v[156:159], v[210:213], v[88:91]
	v_mfma_f32_16x16x32_bf16 v[84:87], v[148:151], v[218:221], v[84:87]
	v_mfma_f32_16x16x32_bf16 v[80:83], v[156:159], v[218:221], v[80:83]
	v_mfma_f32_16x16x32_bf16 v[108:111], v[160:163], v[190:193], v[108:111]
	v_mfma_f32_16x16x32_bf16 v[104:107], v[182:185], v[190:193], v[104:107]
	v_mfma_f32_16x16x32_bf16 v[100:103], v[160:163], v[198:201], v[100:103]
	v_mfma_f32_16x16x32_bf16 v[96:99], v[182:185], v[198:201], v[96:99]
	v_mfma_f32_16x16x32_bf16 v[76:79], v[160:163], v[206:209], v[76:79]
	v_mfma_f32_16x16x32_bf16 v[72:75], v[182:185], v[206:209], v[72:75]
	v_mfma_f32_16x16x32_bf16 v[68:71], v[160:163], v[214:217], v[68:71]
	v_mfma_f32_16x16x32_bf16 v[64:67], v[182:185], v[214:217], v[64:67]
	v_mfma_f32_16x16x32_bf16 v[108:111], v[164:167], v[194:197], v[108:111]
	v_mfma_f32_16x16x32_bf16 v[104:107], v[186:189], v[194:197], v[104:107]
	v_mfma_f32_16x16x32_bf16 v[100:103], v[164:167], v[202:205], v[100:103]
	v_mfma_f32_16x16x32_bf16 v[96:99], v[186:189], v[202:205], v[96:99]
	v_mfma_f32_16x16x32_bf16 v[76:79], v[164:167], v[210:213], v[76:79]
	v_mfma_f32_16x16x32_bf16 v[72:75], v[186:189], v[210:213], v[72:75]
	v_mfma_f32_16x16x32_bf16 v[68:71], v[164:167], v[218:221], v[68:71]
	v_mfma_f32_16x16x32_bf16 v[64:67], v[186:189], v[218:221], v[64:67]
	s_barrier
	s_add_u32 s38, s36, 0x8000
	s_addc_u32 s39, s37, 0
	s_add_i32 s65, s65, s41
	v_lshl_add_u64 v[222:223], s[38:39], 0, v[128:129]
	s_mov_b32 m0, s65
	ds_read_b128 v[190:193], v180 offset:49152
	ds_read_b128 v[194:197], v180 offset:50176
	ds_read_b128 v[198:201], v180 offset:51200
	ds_read_b128 v[202:205], v180 offset:52224
	ds_read_b128 v[206:209], v180 offset:53248
	ds_read_b128 v[210:213], v180 offset:54272
	ds_read_b128 v[214:217], v180 offset:55296
	ds_read_b128 v[218:221], v180 offset:56320
	global_load_lds_dwordx4 v[222:223], off
	s_add_i32 m0, s65, 0x2000
	s_add_u32 s36, s36, 0xc000
	v_lshl_add_u64 v[222:223], s[38:39], 0, v[130:131]
	s_addc_u32 s37, s37, 0
	s_add_i32 s38, s66, s41
	global_load_lds_dwordx4 v[222:223], off
	v_lshl_add_u64 v[222:223], s[36:37], 0, v[128:129]
	s_mov_b32 m0, s38
	s_nop 0
	global_load_lds_dwordx4 v[222:223], off
	v_lshl_add_u64 v[222:223], s[36:37], 0, v[130:131]
	s_add_i32 m0, s38, 0x2000
	s_nop 0
	global_load_lds_dwordx4 v[222:223], off
	v_lshl_add_u64 v[222:223], s[34:35], 0, v[128:129]
	s_mov_b32 m0, s51
	s_nop 0
	global_load_lds_dwordx4 v[222:223], off
	v_lshl_add_u64 v[222:223], s[34:35], 0, v[130:131]
	s_mov_b32 m0, s52
	s_nop 0
	global_load_lds_dwordx4 v[222:223], off
	s_waitcnt vmcnt(8)
	s_waitcnt lgkmcnt(0)
	s_barrier
	s_waitcnt lgkmcnt(0)
	v_mfma_f32_16x16x32_bf16 v[60:63], v[144:147], v[190:193], v[60:63]
	v_mfma_f32_16x16x32_bf16 v[56:59], v[152:155], v[190:193], v[56:59]
	v_mfma_f32_16x16x32_bf16 v[52:55], v[144:147], v[198:201], v[52:55]
	v_mfma_f32_16x16x32_bf16 v[48:51], v[152:155], v[198:201], v[48:51]
	v_mfma_f32_16x16x32_bf16 v[28:31], v[144:147], v[206:209], v[28:31]
	v_mfma_f32_16x16x32_bf16 v[24:27], v[152:155], v[206:209], v[24:27]
	v_mfma_f32_16x16x32_bf16 v[20:23], v[144:147], v[214:217], v[20:23]
	v_mfma_f32_16x16x32_bf16 v[12:15], v[152:155], v[214:217], v[12:15]
	v_mfma_f32_16x16x32_bf16 v[60:63], v[148:151], v[194:197], v[60:63]
	v_mfma_f32_16x16x32_bf16 v[56:59], v[156:159], v[194:197], v[56:59]
	v_mfma_f32_16x16x32_bf16 v[52:55], v[148:151], v[202:205], v[52:55]
	v_mfma_f32_16x16x32_bf16 v[48:51], v[156:159], v[202:205], v[48:51]
	v_mfma_f32_16x16x32_bf16 v[28:31], v[148:151], v[210:213], v[28:31]
	v_mfma_f32_16x16x32_bf16 v[24:27], v[156:159], v[210:213], v[24:27]
	v_mfma_f32_16x16x32_bf16 v[20:23], v[148:151], v[218:221], v[20:23]
	v_mfma_f32_16x16x32_bf16 v[12:15], v[156:159], v[218:221], v[12:15]
	v_mfma_f32_16x16x32_bf16 v[44:47], v[160:163], v[190:193], v[44:47]
	v_mfma_f32_16x16x32_bf16 v[40:43], v[182:185], v[190:193], v[40:43]
	v_mfma_f32_16x16x32_bf16 v[36:39], v[160:163], v[198:201], v[36:39]
	v_mfma_f32_16x16x32_bf16 v[32:35], v[182:185], v[198:201], v[32:35]
	v_mfma_f32_16x16x32_bf16 v[16:19], v[160:163], v[206:209], v[16:19]
	v_mfma_f32_16x16x32_bf16 v[8:11], v[182:185], v[206:209], v[8:11]
	v_mfma_f32_16x16x32_bf16 v[4:7], v[160:163], v[214:217], v[4:7]
	v_mfma_f32_16x16x32_bf16 v[0:3], v[182:185], v[214:217], v[0:3]
	v_mfma_f32_16x16x32_bf16 v[44:47], v[164:167], v[194:197], v[44:47]
	v_mfma_f32_16x16x32_bf16 v[40:43], v[186:189], v[194:197], v[40:43]
	v_mfma_f32_16x16x32_bf16 v[36:39], v[164:167], v[202:205], v[36:39]
	v_mfma_f32_16x16x32_bf16 v[32:35], v[186:189], v[202:205], v[32:35]
	v_mfma_f32_16x16x32_bf16 v[16:19], v[164:167], v[210:213], v[16:19]
	v_mfma_f32_16x16x32_bf16 v[8:11], v[186:189], v[210:213], v[8:11]
	v_mfma_f32_16x16x32_bf16 v[4:7], v[164:167], v[218:221], v[4:7]
	v_mfma_f32_16x16x32_bf16 v[0:3], v[186:189], v[218:221], v[0:3]
	s_barrier
	s_add_i32 s64, s64, 2
	s_add_u32 s62, s62, 0x10000
	s_addc_u32 s63, s63, 0
	s_add_u32 s30, s30, 0x10000
	s_addc_u32 s31, s31, 0
	s_cmp_gt_u32 s64, 41
	s_cbranch_scc0 .LBB0_2519
	s_and_b64 vcc, exec, s[14:15]
	s_cbranch_vccz .LBB0_2522
	s_barrier
